# K-loop DMA schedule: 4 pieces issued right after the stage barrier (was 2), 2 per MFMA group after
# speedup vs baseline: 1.0462x; 1.0462x over previous
; template <int EPI, int MI>
; DI void gemm_tile(const GemmDesc& g, int tm, int tn, char* smem) {
;     ...
;   const int tid = get_tid(), lane = tid & 63, wave = tid >> 6, r = lane & 31, hh = lane >> 5;
;   const int wm = wave >> 1, wn = wave & 1;
;   const int m0 = tm * BM, n0 = tn * 128;
;   const int nk = g.K >> 6;
;   f32x16 acc[MI][2];
; #pragma unroll
;   for (int a = 0; a < MI; ++a)
; #pragma unroll
;     for (int b = 0; b < 2; ++b)
; #pragma unroll
;       for (int i = 0; i < 16; ++i) acc[a][b][i] = 0.f;
;   const int srow = tid >> 3;
;   const int schunk = (tid & 7) ^ ((srow & 7) ^ ((srow >> 3) & 3));
;     ...
;   const int rowA = wm * (32 * MI) + r, rowB = wn * 64 + r;
;   const int hk = hh ^ ((r & 7) ^ ((r >> 3) & 3));
;     ...
;   G_GLDS(0, 0);
;   asm volatile("s_waitcnt vmcnt(0)" ::: "memory");
;   __syncthreads();
; template <int EPI, int MI>
; DI void gemm_phase(const GemmDesc& g, char* smem, int vb, int nvb) {
;     ...
;   for (int q = start; q < local; q += step) {
;     const int mg = q / per;
;     const int rem = q - mg * per;
;     const int tn = rem / PM;
;     const int tm = mbase + mg * PM + (rem - tn * PM);
.LBB0_202:
	s_abs_i32 s1, s5
	v_readlane_b32 s15, v219, 45
	s_mul_hi_u32 s15, s1, s15
	v_readlane_b32 s18, v219, 44
	s_mul_i32 s16, s15, s18
	s_sub_i32 s1, s1, s16
	s_ashr_i32 s0, s5, 31
	s_add_i32 s16, s15, 1
	s_sub_i32 s17, s1, s18
	s_cmp_ge_u32 s1, s18
	s_cselect_b32 s15, s16, s15
	s_cselect_b32 s1, s17, s1
	s_add_i32 s16, s15, 1
	s_cmp_ge_u32 s1, s18
	s_cselect_b32 s1, s16, s15
	s_xor_b32 s1, s1, s0
	s_sub_i32 s15, s1, s0
	s_mul_i32 s16, s15, s18
	s_sub_i32 s16, s5, s16
	s_abs_i32 s18, s16
	v_readlane_b32 s19, v219, 46
	s_mul_hi_u32 s19, s18, s19
	v_readlane_b32 s42, v218, 32
	s_mul_i32 s38, s19, s42
	s_sub_i32 s18, s18, s38
	s_ashr_i32 s17, s16, 31
	s_add_i32 s38, s19, 1
	s_sub_i32 s39, s18, s42
	s_cmp_ge_u32 s18, s42
	s_cselect_b32 s19, s38, s19
	s_cselect_b32 s18, s39, s18
	s_add_i32 s38, s19, 1
	s_cmp_ge_u32 s18, s42
	s_cselect_b32 s18, s38, s19
	s_xor_b32 s18, s18, s17
	s_sub_i32 s39, s18, s17
	s_sub_i32 s15, s15, s39
	v_mov_b32_e32 v4, v132
	s_mul_i32 s15, s15, s42
	s_add_i32 s16, s16, s54
	s_add_i32 s38, s16, s15
	v_ashrrev_i32_e32 v97, 3, v4
	v_ashrrev_i32_e32 v120, 7, v4
	v_bfe_u32 v0, v4, 6, 2
	v_xor_b32_e32 v1, v97, v4
	s_mulk_i32 s38, 0xc0
	v_and_b32_e32 v121, 31, v4
	v_bitop3_b32 v2, v1, v0, 7 bitop3:0x6c
	v_mul_lo_u32 v0, v120, s6
	v_and_b32_e32 v115, 7, v4
	v_or_b32_e32 v5, v0, v121
	v_lshrrev_b32_e32 v0, 3, v4
	s_waitcnt vmcnt(10)
	v_add_u32_e32 v98, s38, v97
	v_bfe_u32 v122, v4, 5, 1
	v_bitop3_b32 v0, v0, v115, 3 bitop3:0x6c
	v_ashrrev_i32_e32 v99, 31, v98
	v_xor_b32_e32 v6, v0, v122
	v_lshlrev_b64 v[0:1], 11, v[98:99]
	v_readlane_b32 s42, v223, 59
	v_lshlrev_b32_e32 v99, 4, v4
	v_readlane_b32 s43, v223, 60
	v_lshlrev_b32_e32 v100, 4, v2
	v_lshl_add_u32 v2, s39, 7, v97
	v_add_u32_e32 v124, 0, v99
	v_lshl_add_u64 v[0:1], s[42:43], 0, v[0:1]
	v_mov_b32_e32 v101, v96
	v_ashrrev_i32_e32 v3, 31, v2
	v_readfirstlane_b32 s15, v124
	v_add_u32_e32 v125, 0x1000, v124
	v_lshl_add_u64 v[0:1], v[0:1], 0, v[100:101]
	v_lshlrev_b64 v[2:3], 11, v[2:3]
	s_mov_b32 m0, s15
	s_mov_b64 s[42:43], 0x10000
	v_readfirstlane_b32 s15, v125
	v_add_u32_e32 v126, 0x2000, v124
	s_waitcnt vmcnt(9)
	v_lshl_add_u64 v[102:103], s[70:71], 0, v[2:3]
	global_load_lds_dwordx4 v[0:1], off
	v_lshl_add_u64 v[2:3], v[0:1], 0, s[42:43]
	s_mov_b32 m0, s15
	s_mov_b64 s[44:45], 0x20000
	v_readfirstlane_b32 s15, v126
	v_add_u32_e32 v127, 0x3000, v124
	global_load_lds_dwordx4 v[2:3], off
	v_lshl_add_u64 v[2:3], v[0:1], 0, s[44:45]
	s_mov_b32 m0, s15
	s_mov_b64 s[46:47], 0x30000
	v_readfirstlane_b32 s15, v127
	v_add_u32_e32 v128, 0x4000, v124
	global_load_lds_dwordx4 v[2:3], off
	v_lshl_add_u64 v[2:3], v[0:1], 0, s[46:47]
	s_mov_b32 m0, s15
	s_mov_b64 s[52:53], 0x40000
	v_readfirstlane_b32 s15, v128
	v_add_u32_e32 v129, 0x5000, v124
	global_load_lds_dwordx4 v[2:3], off
	v_lshl_add_u64 v[2:3], v[0:1], 0, s[52:53]
	s_mov_b32 m0, s15
	s_mov_b64 s[52:53], 0x50000
	v_readfirstlane_b32 s15, v129
	v_add_u32_e32 v130, 0xc000, v124
	global_load_lds_dwordx4 v[2:3], off
	v_lshl_add_u64 v[0:1], v[0:1], 0, s[52:53]
	s_mov_b32 m0, s15
	v_readfirstlane_b32 s15, v130
	v_add_u32_e32 v131, 0xd000, v124
	global_load_lds_dwordx4 v[0:1], off
	v_lshl_add_u64 v[0:1], v[102:103], 0, v[100:101]
	s_mov_b32 m0, s15
	v_readfirstlane_b32 s15, v131
	v_add_u32_e32 v153, 0xe000, v124
	global_load_lds_dwordx4 v[0:1], off
	v_lshl_add_u64 v[2:3], v[0:1], 0, s[42:43]
	s_mov_b32 m0, s15
	v_readfirstlane_b32 s15, v153
	v_add_u32_e32 v154, 0xf000, v124
	global_load_lds_dwordx4 v[2:3], off
	v_lshl_add_u64 v[2:3], v[0:1], 0, s[44:45]
	s_mov_b32 m0, s15
	v_readfirstlane_b32 s15, v154
	global_load_lds_dwordx4 v[2:3], off
	v_lshl_add_u64 v[0:1], v[0:1], 0, s[46:47]
	s_mov_b32 m0, s15
	s_mul_i32 s0, s0, 43
	global_load_lds_dwordx4 v[0:1], off
	s_add_i32 s17, s17, s0
	s_sub_i32 s0, s17, s18
	s_mul_i32 s1, s1, 43
	s_sub_i32 s0, s0, s1
	v_readlane_b32 s1, v218, 33
	v_bfe_u32 v123, v4, 6, 1
	v_lshlrev_b32_e32 v0, 7, v121
	s_mul_i32 s0, s1, s0
	v_lshl_or_b32 v0, v123, 13, v0
	s_add_i32 s0, s0, s4
	v_add_u32_e32 v156, 0, v0
	v_add_u32_e32 v158, s10, v0
	v_add_u32_e32 v0, s0, v97
	v_ashrrev_i32_e32 v1, 31, v0
	s_waitcnt vmcnt(0)
	v_lshlrev_b64 v[0:1], 11, v[0:1]
	v_lshlrev_b32_e32 v157, 4, v6
	v_lshl_add_u64 v[104:105], s[70:71], 0, v[0:1]
	v_mov_b32_e32 v0, 0
	v_lshl_add_u32 v155, v5, 7, 0
	s_mov_b32 s15, 0
	v_mov_b32_e32 v1, v0
	v_mov_b32_e32 v2, v0
	v_mov_b32_e32 v3, v0
	v_mov_b32_e32 v4, v0
	v_mov_b32_e32 v5, v0
	v_mov_b32_e32 v6, v0
	v_mov_b32_e32 v7, v0
	v_mov_b32_e32 v8, v0
	v_mov_b32_e32 v9, v0
	v_mov_b32_e32 v10, v0
	v_mov_b32_e32 v11, v0
	v_mov_b32_e32 v12, v0
	v_mov_b32_e32 v13, v0
	v_mov_b32_e32 v14, v0
	v_mov_b32_e32 v15, v0
	v_mov_b32_e32 v16, v0
	v_mov_b32_e32 v17, v0
	v_mov_b32_e32 v18, v0
	v_mov_b32_e32 v19, v0
	v_mov_b32_e32 v20, v0
	v_mov_b32_e32 v21, v0
	v_mov_b32_e32 v22, v0
	v_mov_b32_e32 v23, v0
	v_mov_b32_e32 v24, v0
	v_mov_b32_e32 v25, v0
	v_mov_b32_e32 v26, v0
	v_mov_b32_e32 v27, v0
	v_mov_b32_e32 v28, v0
	v_mov_b32_e32 v29, v0
	v_mov_b32_e32 v30, v0
	v_mov_b32_e32 v31, v0
	v_mov_b32_e32 v32, v0
	v_mov_b32_e32 v33, v0
	v_mov_b32_e32 v34, v0
	v_mov_b32_e32 v35, v0
	v_mov_b32_e32 v36, v0
	v_mov_b32_e32 v37, v0
	v_mov_b32_e32 v38, v0
	v_mov_b32_e32 v39, v0
	v_mov_b32_e32 v40, v0
	v_mov_b32_e32 v41, v0
	v_mov_b32_e32 v42, v0
	v_mov_b32_e32 v43, v0
	v_mov_b32_e32 v44, v0
	v_mov_b32_e32 v45, v0
	v_mov_b32_e32 v46, v0
	v_mov_b32_e32 v47, v0
	v_mov_b32_e32 v48, v0
	s_waitcnt vmcnt(0)
; template <int EPI, int MI>
; DI void gemm_tile(const GemmDesc& g, int tm, int tn, char* smem) {
;     ...
;   f32x16 acc[MI][2];
; #pragma unroll
;   for (int a = 0; a < MI; ++a)
; #pragma unroll
;     for (int b = 0; b < 2; ++b)
; #pragma unroll
;       for (int i = 0; i < 16; ++i) acc[a][b][i] = 0.f;
;   const int srow = tid >> 3;
;   const int schunk = (tid & 7) ^ ((srow & 7) ^ ((srow >> 3) & 3));
;     ...
;   const int rowA = wm * (32 * MI) + r, rowB = wn * 64 + r;
;   const int hk = hh ^ ((r & 7) ^ ((r >> 3) & 3));
;     ...
;   G_GLDS(0, 0);
;   asm volatile("s_waitcnt vmcnt(0)" ::: "memory");
;   __syncthreads();
;   for (int kt = 0; kt < nk; kt += 2) {
;     if (kt + 1 < nk) G_GLDS(kt + 1, 1);
;     G_COMPUTE(0);
;     asm volatile("s_waitcnt vmcnt(0)" ::: "memory");
;     __syncthreads();
;     if (kt + 1 < nk) {
;       if (kt + 2 < nk) G_GLDS(kt + 2, 0);
;       G_COMPUTE(1);
;       asm volatile("s_waitcnt vmcnt(0)" ::: "memory");
;       __syncthreads();
;     }
;   }
	v_mov_b32_e32 v49, v0
	v_mov_b32_e32 v50, v0
	v_mov_b32_e32 v51, v0
	v_mov_b32_e32 v52, v0
	v_mov_b32_e32 v53, v0
	v_mov_b32_e32 v54, v0
	v_mov_b32_e32 v55, v0
	v_mov_b32_e32 v56, v0
	v_mov_b32_e32 v57, v0
	v_mov_b32_e32 v58, v0
	v_mov_b32_e32 v59, v0
	v_mov_b32_e32 v60, v0
	v_mov_b32_e32 v61, v0
	v_mov_b32_e32 v62, v0
	v_mov_b32_e32 v63, v0
	v_mov_b32_e32 v64, v0
	v_mov_b32_e32 v65, v0
	v_mov_b32_e32 v66, v0
	v_mov_b32_e32 v67, v0
	v_mov_b32_e32 v68, v0
	v_mov_b32_e32 v69, v0
	v_mov_b32_e32 v70, v0
	v_mov_b32_e32 v71, v0
	v_mov_b32_e32 v72, v0
	v_mov_b32_e32 v73, v0
	v_mov_b32_e32 v74, v0
	v_mov_b32_e32 v75, v0
	v_mov_b32_e32 v76, v0
	v_mov_b32_e32 v77, v0
	v_mov_b32_e32 v78, v0
	v_mov_b32_e32 v79, v0
	v_mov_b32_e32 v80, v0
	v_mov_b32_e32 v81, v0
	v_mov_b32_e32 v82, v0
	v_mov_b32_e32 v83, v0
	v_mov_b32_e32 v84, v0
	v_mov_b32_e32 v85, v0
	v_mov_b32_e32 v86, v0
	v_mov_b32_e32 v87, v0
	v_mov_b32_e32 v88, v0
	v_mov_b32_e32 v89, v0
	v_mov_b32_e32 v90, v0
	v_mov_b32_e32 v91, v0
	v_mov_b32_e32 v92, v0
	v_mov_b32_e32 v93, v0
	v_mov_b32_e32 v94, v0
	v_mov_b32_e32 v95, v0
	v_xor_b32_e32 v159, 32, v157
	v_xor_b32_e32 v160, 64, v157
	v_xor_b32_e32 v161, 0x60, v157
	s_mov_b64 s[18:19], 0x80
	s_mov_b64 s[42:43], 0x10080
	v_add_u32_e32 v162, v155, v157
	v_add_u32_e32 v163, v155, v159
	v_add_u32_e32 v164, v155, v160
	v_add_u32_e32 v165, v155, v161
	v_add_u32_e32 v166, v156, v157
	v_add_u32_e32 v167, v156, v159
	v_add_u32_e32 v168, v156, v160
	v_add_u32_e32 v169, v156, v161
	v_add_u32_e32 v170, v158, v157
	v_add_u32_e32 v171, v158, v159
	v_add_u32_e32 v172, v158, v160
	v_add_u32_e32 v173, v158, v161
	v_lshl_add_u64 v[174:175], v[104:105], 0, v[100:101]
	v_lshl_add_u64 v[176:177], v[102:103], 0, v[100:101]
	v_readfirstlane_b32 s100, v124
	s_waitcnt vmcnt(0) lgkmcnt(0)
	s_barrier
	s_add_u32 m0, s100, 0x6000
	v_lshl_add_u64 v[106:107], v[174:175], 0, s[96:97]
	global_load_lds_dwordx4 v[106:107], off
	s_add_u32 m0, s100, 0x7000
	v_lshl_add_u64 v[106:107], v[174:175], 0, s[50:51]
	global_load_lds_dwordx4 v[106:107], off
	s_add_u32 m0, s100, 0x8000
	v_lshl_add_u64 v[106:107], v[174:175], 0, s[24:25]
	global_load_lds_dwordx4 v[106:107], off
	s_add_u32 m0, s100, 0x9000
	v_lshl_add_u64 v[106:107], v[174:175], 0, s[26:27]
	global_load_lds_dwordx4 v[106:107], off
	ds_read_b128 v[236:239], v166 offset:49152
	ds_read_b128 v[240:243], v166 offset:53248
	ds_read_b128 v[224:227], v162
	ds_read_b128 v[228:231], v162 offset:4096
	s_mov_b32 s15, 0
.Lga_loop:
	ds_read_b128 v[232:235], v162 offset:8192
	s_waitcnt lgkmcnt(2)
	v_mfma_f32_32x32x16_bf16 v[80:95], v[224:227], v[236:239], v[80:95]
	v_mfma_f32_32x32x16_bf16 v[64:79], v[224:227], v[240:243], v[64:79]
	s_add_u32 m0, s100, 0xa000
	v_lshl_add_u64 v[106:107], v[174:175], 0, s[28:29]
	global_load_lds_dwordx4 v[106:107], off
	s_add_u32 m0, s100, 0xb000
	v_lshl_add_u64 v[106:107], v[174:175], 0, s[30:31]
	global_load_lds_dwordx4 v[106:107], off
	v_lshl_add_u64 v[174:175], v[174:175], 0, s[18:19]
	ds_read_b128 v[244:247], v167 offset:49152
	ds_read_b128 v[248:251], v167 offset:53248
	ds_read_b128 v[224:227], v163
	s_waitcnt lgkmcnt(4)
	v_mfma_f32_32x32x16_bf16 v[48:63], v[228:231], v[236:239], v[48:63]
	v_mfma_f32_32x32x16_bf16 v[32:47], v[228:231], v[240:243], v[32:47]
	s_add_u32 m0, s100, 0x10000
	v_lshl_add_u64 v[106:107], v[176:177], 0, s[18:19]
	global_load_lds_dwordx4 v[106:107], off
	s_add_u32 m0, s100, 0x11000
	v_lshl_add_u64 v[106:107], v[176:177], 0, s[42:43]
	global_load_lds_dwordx4 v[106:107], off
	ds_read_b128 v[228:231], v163 offset:4096
	s_waitcnt lgkmcnt(4)
	v_mfma_f32_32x32x16_bf16 v[16:31], v[232:235], v[236:239], v[16:31]
	v_mfma_f32_32x32x16_bf16 v[0:15], v[232:235], v[240:243], v[0:15]
	s_mov_b64 s[16:17], 0x20080
	s_add_u32 m0, s100, 0x12000
	v_lshl_add_u64 v[106:107], v[176:177], 0, s[16:17]
	global_load_lds_dwordx4 v[106:107], off
	s_mov_b64 s[16:17], 0x30080
	s_add_u32 m0, s100, 0x13000
	v_lshl_add_u64 v[106:107], v[176:177], 0, s[16:17]
	global_load_lds_dwordx4 v[106:107], off
	v_lshl_add_u64 v[176:177], v[176:177], 0, s[18:19]
	ds_read_b128 v[232:235], v163 offset:8192
	s_waitcnt lgkmcnt(2)
	v_mfma_f32_32x32x16_bf16 v[80:95], v[224:227], v[244:247], v[80:95]
	v_mfma_f32_32x32x16_bf16 v[64:79], v[224:227], v[248:251], v[64:79]
	ds_read_b128 v[236:239], v168 offset:49152
	ds_read_b128 v[240:243], v168 offset:53248
	ds_read_b128 v[224:227], v164
	s_waitcnt lgkmcnt(4)
	v_mfma_f32_32x32x16_bf16 v[48:63], v[228:231], v[244:247], v[48:63]
	v_mfma_f32_32x32x16_bf16 v[32:47], v[228:231], v[248:251], v[32:47]
	ds_read_b128 v[228:231], v164 offset:4096
	s_waitcnt lgkmcnt(4)
	v_mfma_f32_32x32x16_bf16 v[16:31], v[232:235], v[244:247], v[16:31]
	v_mfma_f32_32x32x16_bf16 v[0:15], v[232:235], v[248:251], v[0:15]
	ds_read_b128 v[232:235], v164 offset:8192
	s_waitcnt lgkmcnt(2)
	v_mfma_f32_32x32x16_bf16 v[80:95], v[224:227], v[236:239], v[80:95]
	v_mfma_f32_32x32x16_bf16 v[64:79], v[224:227], v[240:243], v[64:79]
	ds_read_b128 v[244:247], v169 offset:49152
	ds_read_b128 v[248:251], v169 offset:53248
	ds_read_b128 v[224:227], v165
	s_waitcnt lgkmcnt(4)
	v_mfma_f32_32x32x16_bf16 v[48:63], v[228:231], v[236:239], v[48:63]
	v_mfma_f32_32x32x16_bf16 v[32:47], v[228:231], v[240:243], v[32:47]
	ds_read_b128 v[228:231], v165 offset:4096
	s_waitcnt lgkmcnt(4)
	v_mfma_f32_32x32x16_bf16 v[16:31], v[232:235], v[236:239], v[16:31]
	v_mfma_f32_32x32x16_bf16 v[0:15], v[232:235], v[240:243], v[0:15]
	ds_read_b128 v[232:235], v165 offset:8192
	s_waitcnt lgkmcnt(2)
	v_mfma_f32_32x32x16_bf16 v[80:95], v[224:227], v[244:247], v[80:95]
	v_mfma_f32_32x32x16_bf16 v[64:79], v[224:227], v[248:251], v[64:79]
	s_waitcnt lgkmcnt(0)
	s_waitcnt vmcnt(0)
	s_barrier
	s_cmp_eq_u32 s15, 14
	s_cbranch_scc1 .Lga_noearly
	s_mov_b32 m0, s100
	v_lshl_add_u64 v[106:107], v[174:175], 0, s[96:97]
	global_load_lds_dwordx4 v[106:107], off
	s_add_u32 m0, s100, 0x1000
	v_lshl_add_u64 v[106:107], v[174:175], 0, s[50:51]
	global_load_lds_dwordx4 v[106:107], off
	s_add_u32 m0, s100, 0x2000
	v_lshl_add_u64 v[106:107], v[174:175], 0, s[24:25]
	global_load_lds_dwordx4 v[106:107], off
	s_add_u32 m0, s100, 0x3000
	v_lshl_add_u64 v[106:107], v[174:175], 0, s[26:27]
	global_load_lds_dwordx4 v[106:107], off
; template <int EPI, int MI>
; DI void gemm_tile(const GemmDesc& g, int tm, int tn, char* smem) {
;     ...
;   const int rowA = wm * (32 * MI) + r, rowB = wn * 64 + r;
;   const int hk = hh ^ ((r & 7) ^ ((r >> 3) & 3));
;     ...
;   G_GLDS(0, 0);
;   asm volatile("s_waitcnt vmcnt(0)" ::: "memory");
;   __syncthreads();
;   for (int kt = 0; kt < nk; kt += 2) {
;     if (kt + 1 < nk) G_GLDS(kt + 1, 1);
;     G_COMPUTE(0);
;     asm volatile("s_waitcnt vmcnt(0)" ::: "memory");
;     __syncthreads();
;     if (kt + 1 < nk) {
;       if (kt + 2 < nk) G_GLDS(kt + 2, 0);
;       G_COMPUTE(1);
;       asm volatile("s_waitcnt vmcnt(0)" ::: "memory");
;       __syncthreads();
;     }
;   }
.Lga_noearly:
	ds_read_b128 v[236:239], v170
	ds_read_b128 v[240:243], v170 offset:4096
	ds_read_b128 v[224:227], v162 offset:24576
	v_mfma_f32_32x32x16_bf16 v[48:63], v[228:231], v[244:247], v[48:63]
	v_mfma_f32_32x32x16_bf16 v[32:47], v[228:231], v[248:251], v[32:47]
	ds_read_b128 v[228:231], v162 offset:28672
	v_mfma_f32_32x32x16_bf16 v[16:31], v[232:235], v[244:247], v[16:31]
	v_mfma_f32_32x32x16_bf16 v[0:15], v[232:235], v[248:251], v[0:15]
	s_cmp_eq_u32 s15, 14
	s_cbranch_scc1 .Lga_last
	ds_read_b128 v[232:235], v162 offset:32768
	s_waitcnt lgkmcnt(2)
	v_mfma_f32_32x32x16_bf16 v[80:95], v[224:227], v[236:239], v[80:95]
	v_mfma_f32_32x32x16_bf16 v[64:79], v[224:227], v[240:243], v[64:79]
	s_add_u32 m0, s100, 0x4000
	v_lshl_add_u64 v[106:107], v[174:175], 0, s[28:29]
	global_load_lds_dwordx4 v[106:107], off
	s_add_u32 m0, s100, 0x5000
	v_lshl_add_u64 v[106:107], v[174:175], 0, s[30:31]
	global_load_lds_dwordx4 v[106:107], off
	v_lshl_add_u64 v[174:175], v[174:175], 0, s[18:19]
	ds_read_b128 v[244:247], v171
	ds_read_b128 v[248:251], v171 offset:4096
	ds_read_b128 v[224:227], v163 offset:24576
	s_waitcnt lgkmcnt(4)
	v_mfma_f32_32x32x16_bf16 v[48:63], v[228:231], v[236:239], v[48:63]
	v_mfma_f32_32x32x16_bf16 v[32:47], v[228:231], v[240:243], v[32:47]
	s_add_u32 m0, s100, 0xc000
	v_lshl_add_u64 v[106:107], v[176:177], 0, s[18:19]
	global_load_lds_dwordx4 v[106:107], off
	s_add_u32 m0, s100, 0xd000
	v_lshl_add_u64 v[106:107], v[176:177], 0, s[42:43]
	global_load_lds_dwordx4 v[106:107], off
	ds_read_b128 v[228:231], v163 offset:28672
	s_waitcnt lgkmcnt(4)
	v_mfma_f32_32x32x16_bf16 v[16:31], v[232:235], v[236:239], v[16:31]
	v_mfma_f32_32x32x16_bf16 v[0:15], v[232:235], v[240:243], v[0:15]
	s_mov_b64 s[16:17], 0x20080
	s_add_u32 m0, s100, 0xe000
	v_lshl_add_u64 v[106:107], v[176:177], 0, s[16:17]
	global_load_lds_dwordx4 v[106:107], off
	s_mov_b64 s[16:17], 0x30080
	s_add_u32 m0, s100, 0xf000
	v_lshl_add_u64 v[106:107], v[176:177], 0, s[16:17]
	global_load_lds_dwordx4 v[106:107], off
	v_lshl_add_u64 v[176:177], v[176:177], 0, s[18:19]
	ds_read_b128 v[232:235], v163 offset:32768
	s_waitcnt lgkmcnt(2)
	v_mfma_f32_32x32x16_bf16 v[80:95], v[224:227], v[244:247], v[80:95]
	v_mfma_f32_32x32x16_bf16 v[64:79], v[224:227], v[248:251], v[64:79]
	ds_read_b128 v[236:239], v172
	ds_read_b128 v[240:243], v172 offset:4096
	ds_read_b128 v[224:227], v164 offset:24576
	s_waitcnt lgkmcnt(4)
	v_mfma_f32_32x32x16_bf16 v[48:63], v[228:231], v[244:247], v[48:63]
	v_mfma_f32_32x32x16_bf16 v[32:47], v[228:231], v[248:251], v[32:47]
	ds_read_b128 v[228:231], v164 offset:28672
	s_waitcnt lgkmcnt(4)
	v_mfma_f32_32x32x16_bf16 v[16:31], v[232:235], v[244:247], v[16:31]
	v_mfma_f32_32x32x16_bf16 v[0:15], v[232:235], v[248:251], v[0:15]
	ds_read_b128 v[232:235], v164 offset:32768
	s_waitcnt lgkmcnt(2)
	v_mfma_f32_32x32x16_bf16 v[80:95], v[224:227], v[236:239], v[80:95]
	v_mfma_f32_32x32x16_bf16 v[64:79], v[224:227], v[240:243], v[64:79]
	ds_read_b128 v[244:247], v173
	ds_read_b128 v[248:251], v173 offset:4096
	ds_read_b128 v[224:227], v165 offset:24576
	s_waitcnt lgkmcnt(4)
	v_mfma_f32_32x32x16_bf16 v[48:63], v[228:231], v[236:239], v[48:63]
	v_mfma_f32_32x32x16_bf16 v[32:47], v[228:231], v[240:243], v[32:47]
	ds_read_b128 v[228:231], v165 offset:28672
	s_waitcnt lgkmcnt(4)
	v_mfma_f32_32x32x16_bf16 v[16:31], v[232:235], v[236:239], v[16:31]
	v_mfma_f32_32x32x16_bf16 v[0:15], v[232:235], v[240:243], v[0:15]
	ds_read_b128 v[232:235], v165 offset:32768
	s_waitcnt lgkmcnt(2)
	v_mfma_f32_32x32x16_bf16 v[80:95], v[224:227], v[244:247], v[80:95]
	v_mfma_f32_32x32x16_bf16 v[64:79], v[224:227], v[248:251], v[64:79]
	s_waitcnt lgkmcnt(0)
	s_waitcnt vmcnt(0)
	s_barrier
	s_add_u32 m0, s100, 0x6000
	v_lshl_add_u64 v[106:107], v[174:175], 0, s[96:97]
	global_load_lds_dwordx4 v[106:107], off
	s_add_u32 m0, s100, 0x7000
	v_lshl_add_u64 v[106:107], v[174:175], 0, s[50:51]
	global_load_lds_dwordx4 v[106:107], off
	s_add_u32 m0, s100, 0x8000
	v_lshl_add_u64 v[106:107], v[174:175], 0, s[24:25]
	global_load_lds_dwordx4 v[106:107], off
	s_add_u32 m0, s100, 0x9000
	v_lshl_add_u64 v[106:107], v[174:175], 0, s[26:27]
	global_load_lds_dwordx4 v[106:107], off
	ds_read_b128 v[236:239], v166 offset:49152
	ds_read_b128 v[240:243], v166 offset:53248
	ds_read_b128 v[224:227], v162
	v_mfma_f32_32x32x16_bf16 v[48:63], v[228:231], v[244:247], v[48:63]
	v_mfma_f32_32x32x16_bf16 v[32:47], v[228:231], v[248:251], v[32:47]
	ds_read_b128 v[228:231], v162 offset:4096
	v_mfma_f32_32x32x16_bf16 v[16:31], v[232:235], v[244:247], v[16:31]
	v_mfma_f32_32x32x16_bf16 v[0:15], v[232:235], v[248:251], v[0:15]
	s_add_u32 s15, s15, 2
	s_branch .Lga_loop

; template <int EPI, int MI>
; DI void gemm_tile(const GemmDesc& g, int tm, int tn, char* smem) {
;     ...
;   const int tid = get_tid(), lane = tid & 63, wave = tid >> 6, r = lane & 31, hh = lane >> 5;
;   const int wm = wave >> 1, wn = wave & 1;
;   const int m0 = tm * BM, n0 = tn * 128;
;   const int nk = g.K >> 6;
;   f32x16 acc[MI][2];
; #pragma unroll
;   for (int a = 0; a < MI; ++a)
; #pragma unroll
;     for (int b = 0; b < 2; ++b)
; #pragma unroll
;       for (int i = 0; i < 16; ++i) acc[a][b][i] = 0.f;
;   const int srow = tid >> 3;
;   const int schunk = (tid & 7) ^ ((srow & 7) ^ ((srow >> 3) & 3));
;     ...
;   const int rowA = wm * (32 * MI) + r, rowB = wn * 64 + r;
;   const int hk = hh ^ ((r & 7) ^ ((r >> 3) & 3));
;     ...
;   G_GLDS(0, 0);
;   asm volatile("s_waitcnt vmcnt(0)" ::: "memory");
;   __syncthreads();
; template <int EPI, int MI>
; DI void gemm_phase(const GemmDesc& g, char* smem, int vb, int nvb) {
;     ...
;   for (int q = start; q < local; q += step) {
;     const int mg = q / per;
;     const int rem = q - mg * per;
;     const int tn = rem / PM;
;     const int tm = mbase + mg * PM + (rem - tn * PM);
;     gemm_tile<EPI, MI>(g, tm, tn, smem);
.LBB0_254:
	s_abs_i32 s0, s42
	v_readlane_b32 s1, v219, 48
	s_mul_hi_u32 s1, s0, s1
	v_readlane_b32 s17, v219, 47
	s_mul_i32 s4, s1, s17
	s_sub_i32 s0, s0, s4
	s_ashr_i32 s15, s42, 31
	s_add_i32 s4, s1, 1
	s_sub_i32 s5, s0, s17
	s_cmp_ge_u32 s0, s17
	s_cselect_b32 s1, s4, s1
	s_cselect_b32 s0, s5, s0
	s_add_i32 s4, s1, 1
	s_cmp_ge_u32 s0, s17
	s_cselect_b32 s0, s4, s1
	s_xor_b32 s16, s0, s15
	s_sub_i32 s0, s16, s15
	s_mul_i32 s1, s0, s17
	s_sub_i32 s1, s42, s1
	s_abs_i32 s4, s1
	v_readlane_b32 s5, v219, 46
	s_mul_hi_u32 s5, s4, s5
	v_readlane_b32 s43, v218, 32
	s_mul_i32 s18, s5, s43
	s_sub_i32 s4, s4, s18
	s_ashr_i32 s17, s1, 31
	s_add_i32 s18, s5, 1
	s_sub_i32 s19, s4, s43
	s_cmp_ge_u32 s4, s43
	s_cselect_b32 s5, s18, s5
	s_cselect_b32 s4, s19, s4
	s_add_i32 s18, s5, 1
	s_cmp_ge_u32 s4, s43
	s_cselect_b32 s4, s18, s5
	s_xor_b32 s18, s4, s17
	v_mov_b32_e32 v97, v132
	s_sub_i32 s4, s18, s17
	s_mul_i32 s0, s0, s43
	v_ashrrev_i32_e32 v6, 3, v97
	s_mul_i32 s5, s4, s43
	s_waitcnt vmcnt(8)
	v_ashrrev_i32_e32 v109, 7, v97
	v_bfe_u32 v1, v97, 6, 2
	v_xor_b32_e32 v2, v6, v97
	s_add_i32 s0, s0, s54
	s_sub_i32 s1, s1, s5
	v_and_b32_e32 v108, 31, v97
	v_bitop3_b32 v2, v2, v1, 7 bitop3:0x6c
	v_mul_lo_u32 v1, v109, s6
	s_add_i32 s1, s0, s1
	s_lshl_b32 s0, s4, 7
	v_and_b32_e32 v0, 7, v97
	v_or_b32_e32 v7, v1, v108
	v_lshrrev_b32_e32 v1, 3, v97
	v_readlane_b32 s4, v221, 5
	s_mul_i32 s43, s1, 0xc0
	v_bfe_u32 v115, v97, 5, 1
	v_bitop3_b32 v0, v1, v0, 3 bitop3:0x6c
	v_readlane_b32 s5, v221, 6
	v_xor_b32_e32 v8, v0, v115
	v_add_u32_e32 v3, s43, v6
	v_mov_b64_e32 v[0:1], s[4:5]
	s_movk_i32 s19, 0x1600
	v_mad_i64_i32 v[0:1], s[4:5], v3, s19, v[0:1]
	v_readlane_b32 s4, v221, 10
	v_readlane_b32 s5, v221, 11
	v_lshlrev_b32_e32 v98, 4, v2
	v_add_u32_e32 v9, s0, v6
	v_mov_b64_e32 v[2:3], s[4:5]
	v_lshlrev_b32_e32 v120, 4, v97
	v_mad_i64_i32 v[2:3], s[4:5], v9, s19, v[2:3]
	v_add_u32_e32 v121, 0, v120
	v_mov_b32_e32 v99, v96
	v_readfirstlane_b32 s4, v121
	v_add_u32_e32 v122, 0x1000, v121
	v_lshl_add_u64 v[0:1], v[0:1], 0, v[98:99]
	s_mov_b32 m0, s4
	s_mov_b64 s[44:45], 0x2c000
	v_readfirstlane_b32 s4, v122
	v_add_u32_e32 v123, 0x2000, v121
	global_load_lds_dwordx4 v[0:1], off
	v_lshl_add_u64 v[4:5], v[0:1], 0, s[44:45]
	s_mov_b32 m0, s4
	s_mov_b64 s[46:47], 0x58000
	v_readfirstlane_b32 s4, v123
	v_add_u32_e32 v124, 0x3000, v121
	global_load_lds_dwordx4 v[4:5], off
	v_lshl_add_u64 v[4:5], v[0:1], 0, s[46:47]
	s_mov_b32 m0, s4
	s_mov_b64 s[52:53], 0x84000
	v_readfirstlane_b32 s4, v124
	global_load_lds_dwordx4 v[4:5], off
	v_lshl_add_u64 v[4:5], v[0:1], 0, s[52:53]
	s_mov_b32 m0, s4
	s_mov_b64 s[4:5], 0xb0000
	v_add_u32_e32 v125, 0x4000, v121
	global_load_lds_dwordx4 v[4:5], off
	v_lshl_add_u64 v[4:5], v[0:1], 0, s[4:5]
	v_readfirstlane_b32 s4, v125
	s_mov_b32 m0, s4
	s_mov_b64 s[4:5], 0xdc000
	v_add_u32_e32 v126, 0x5000, v121
	v_lshl_add_u64 v[0:1], v[0:1], 0, s[4:5]
	v_readfirstlane_b32 s4, v126
	v_add_u32_e32 v127, 0xc000, v121
	global_load_lds_dwordx4 v[4:5], off
	s_mov_b32 m0, s4
	v_readfirstlane_b32 s4, v127
	v_add_u32_e32 v128, 0xd000, v121
	global_load_lds_dwordx4 v[0:1], off
	v_lshl_add_u64 v[0:1], v[2:3], 0, v[98:99]
	s_mov_b32 m0, s4
	v_readfirstlane_b32 s4, v128
	v_add_u32_e32 v129, 0xe000, v121
	global_load_lds_dwordx4 v[0:1], off
	v_lshl_add_u64 v[2:3], v[0:1], 0, s[44:45]
	s_mov_b32 m0, s4
	v_readfirstlane_b32 s4, v129
	v_add_u32_e32 v130, 0xf000, v121
	global_load_lds_dwordx4 v[2:3], off
	v_lshl_add_u64 v[2:3], v[0:1], 0, s[46:47]
	s_mov_b32 m0, s4
	v_readfirstlane_b32 s4, v130
	global_load_lds_dwordx4 v[2:3], off
	v_lshl_add_u64 v[0:1], v[0:1], 0, s[52:53]
	s_mov_b32 m0, s4
	s_mul_i32 s15, s15, 7
	global_load_lds_dwordx4 v[0:1], off
	s_add_i32 s17, s17, s15
	s_sub_i32 s4, s17, s18
	s_mul_i32 s16, s16, 7
	s_sub_i32 s4, s4, s16
	v_readlane_b32 s5, v218, 33
	v_lshlrev_b32_e32 v0, 7, v97
	s_mul_i32 s4, s5, s4
	v_and_b32_e32 v0, 0x2f80, v0
	s_add_i32 s4, s4, s39
	s_waitcnt vmcnt(0)
	v_add_u32_e32 v153, 0, v0
	v_add_u32_e32 v155, s10, v0
	v_add_u32_e32 v2, s4, v6
	v_mov_b64_e32 v[0:1], s[70:71]
	v_lshlrev_b32_e32 v154, 4, v8
	v_mad_i64_i32 v[100:101], s[4:5], v2, s19, v[0:1]
	v_mad_i64_i32 v[102:103], s[4:5], v9, s19, v[0:1]
	v_mov_b32_e32 v0, 0
	v_lshl_add_u32 v131, v7, 7, 0
	v_xor_b32_e32 v156, 32, v154
	v_xor_b32_e32 v157, 64, v154
	v_xor_b32_e32 v158, 0x60, v154
	s_mov_b32 s15, 0
	v_mov_b32_e32 v1, v0
	v_mov_b32_e32 v2, v0
	v_mov_b32_e32 v3, v0
	v_mov_b32_e32 v4, v0
	v_mov_b32_e32 v5, v0
	v_mov_b32_e32 v6, v0
	v_mov_b32_e32 v7, v0
	v_mov_b32_e32 v8, v0
	v_mov_b32_e32 v9, v0
	v_mov_b32_e32 v10, v0
	v_mov_b32_e32 v11, v0
	v_mov_b32_e32 v12, v0
	v_mov_b32_e32 v13, v0
	v_mov_b32_e32 v14, v0
	v_mov_b32_e32 v15, v0
	v_mov_b32_e32 v16, v0
	v_mov_b32_e32 v17, v0
	v_mov_b32_e32 v18, v0
	v_mov_b32_e32 v19, v0
	v_mov_b32_e32 v20, v0
	v_mov_b32_e32 v21, v0
	v_mov_b32_e32 v22, v0
	v_mov_b32_e32 v23, v0
	v_mov_b32_e32 v24, v0
	v_mov_b32_e32 v25, v0
	v_mov_b32_e32 v26, v0
	v_mov_b32_e32 v27, v0
	v_mov_b32_e32 v28, v0
	v_mov_b32_e32 v29, v0
	v_mov_b32_e32 v30, v0
	v_mov_b32_e32 v31, v0
	v_mov_b32_e32 v32, v0
	v_mov_b32_e32 v33, v0
	v_mov_b32_e32 v34, v0
	v_mov_b32_e32 v35, v0
	v_mov_b32_e32 v36, v0
	v_mov_b32_e32 v37, v0
	v_mov_b32_e32 v38, v0
	v_mov_b32_e32 v39, v0
	v_mov_b32_e32 v40, v0
	v_mov_b32_e32 v41, v0
	v_mov_b32_e32 v42, v0
	v_mov_b32_e32 v43, v0
	v_mov_b32_e32 v44, v0
	v_mov_b32_e32 v45, v0
	v_mov_b32_e32 v46, v0
	v_mov_b32_e32 v47, v0
	v_mov_b32_e32 v48, v0
	s_waitcnt vmcnt(0)
; template <int EPI, int MI>
; DI void gemm_tile(const GemmDesc& g, int tm, int tn, char* smem) {
;     ...
;   f32x16 acc[MI][2];
; #pragma unroll
;   for (int a = 0; a < MI; ++a)
; #pragma unroll
;     for (int b = 0; b < 2; ++b)
; #pragma unroll
;       for (int i = 0; i < 16; ++i) acc[a][b][i] = 0.f;
;   const int srow = tid >> 3;
;   const int schunk = (tid & 7) ^ ((srow & 7) ^ ((srow >> 3) & 3));
;     ...
;   const int rowA = wm * (32 * MI) + r, rowB = wn * 64 + r;
;   const int hk = hh ^ ((r & 7) ^ ((r >> 3) & 3));
;     ...
;   G_GLDS(0, 0);
;   asm volatile("s_waitcnt vmcnt(0)" ::: "memory");
;   __syncthreads();
;   for (int kt = 0; kt < nk; kt += 2) {
;     if (kt + 1 < nk) G_GLDS(kt + 1, 1);
;     G_COMPUTE(0);
;     asm volatile("s_waitcnt vmcnt(0)" ::: "memory");
;     __syncthreads();
;     if (kt + 1 < nk) {
;       if (kt + 2 < nk) G_GLDS(kt + 2, 0);
;       G_COMPUTE(1);
;       asm volatile("s_waitcnt vmcnt(0)" ::: "memory");
;       __syncthreads();
;     }
;   }
	v_mov_b32_e32 v49, v0
	v_mov_b32_e32 v50, v0
	v_mov_b32_e32 v51, v0
	v_mov_b32_e32 v52, v0
	v_mov_b32_e32 v53, v0
	v_mov_b32_e32 v54, v0
	v_mov_b32_e32 v55, v0
	v_mov_b32_e32 v56, v0
	v_mov_b32_e32 v57, v0
	v_mov_b32_e32 v58, v0
	v_mov_b32_e32 v59, v0
	v_mov_b32_e32 v60, v0
	v_mov_b32_e32 v61, v0
	v_mov_b32_e32 v62, v0
	v_mov_b32_e32 v63, v0
	v_mov_b32_e32 v64, v0
	v_mov_b32_e32 v65, v0
	v_mov_b32_e32 v66, v0
	v_mov_b32_e32 v67, v0
	v_mov_b32_e32 v68, v0
	v_mov_b32_e32 v69, v0
	v_mov_b32_e32 v70, v0
	v_mov_b32_e32 v71, v0
	v_mov_b32_e32 v72, v0
	v_mov_b32_e32 v73, v0
	v_mov_b32_e32 v74, v0
	v_mov_b32_e32 v75, v0
	v_mov_b32_e32 v76, v0
	v_mov_b32_e32 v77, v0
	v_mov_b32_e32 v78, v0
	v_mov_b32_e32 v79, v0
	v_mov_b32_e32 v80, v0
	v_mov_b32_e32 v81, v0
	v_mov_b32_e32 v82, v0
	v_mov_b32_e32 v83, v0
	v_mov_b32_e32 v84, v0
	v_mov_b32_e32 v85, v0
	v_mov_b32_e32 v86, v0
	v_mov_b32_e32 v87, v0
	v_mov_b32_e32 v88, v0
	v_mov_b32_e32 v89, v0
	v_mov_b32_e32 v90, v0
	v_mov_b32_e32 v91, v0
	v_mov_b32_e32 v92, v0
	v_mov_b32_e32 v93, v0
	v_mov_b32_e32 v94, v0
	v_mov_b32_e32 v95, v0
	v_add_u32_e32 v162, v131, v154
	v_add_u32_e32 v163, v131, v156
	v_add_u32_e32 v164, v131, v157
	v_add_u32_e32 v165, v131, v158
	v_add_u32_e32 v166, v153, v154
	v_add_u32_e32 v167, v153, v156
	v_add_u32_e32 v168, v153, v157
	v_add_u32_e32 v169, v153, v158
	v_add_u32_e32 v170, v155, v154
	v_add_u32_e32 v171, v155, v156
	v_add_u32_e32 v172, v155, v157
	v_add_u32_e32 v173, v155, v158
	v_lshl_add_u64 v[252:253], v[100:101], 0, v[98:99]
	v_lshl_add_u64 v[254:255], v[102:103], 0, v[98:99]
	v_readfirstlane_b32 s100, v121
	s_mov_b64 s[4:5], 0x80
	s_waitcnt vmcnt(0) lgkmcnt(0)
	s_barrier
	s_mov_b64 s[16:17], 0x5872080
	s_add_u32 m0, s100, 0x6000
	v_lshl_add_u64 v[106:107], v[252:253], 0, s[16:17]
	global_load_lds_dwordx4 v[106:107], off
	s_mov_b64 s[16:17], 0x589e080
	s_add_u32 m0, s100, 0x7000
	v_lshl_add_u64 v[106:107], v[252:253], 0, s[16:17]
	global_load_lds_dwordx4 v[106:107], off
	s_mov_b64 s[16:17], 0x58ca080
	s_add_u32 m0, s100, 0x8000
	v_lshl_add_u64 v[106:107], v[252:253], 0, s[16:17]
	global_load_lds_dwordx4 v[106:107], off
	s_mov_b64 s[16:17], 0x58f6080
	s_add_u32 m0, s100, 0x9000
	v_lshl_add_u64 v[106:107], v[252:253], 0, s[16:17]
	global_load_lds_dwordx4 v[106:107], off
	ds_read_b128 v[236:239], v166 offset:49152
	ds_read_b128 v[240:243], v166 offset:53248
	ds_read_b128 v[224:227], v162
	ds_read_b128 v[228:231], v162 offset:4096
	s_mov_b32 s15, 0
.Lgd_loop:
	ds_read_b128 v[232:235], v162 offset:8192
	s_waitcnt lgkmcnt(2)
	v_mfma_f32_32x32x16_bf16 v[80:95], v[224:227], v[236:239], v[80:95]
	v_mfma_f32_32x32x16_bf16 v[64:79], v[224:227], v[240:243], v[64:79]
	s_mov_b64 s[16:17], 0x5922080
	s_add_u32 m0, s100, 0xa000
	v_lshl_add_u64 v[106:107], v[252:253], 0, s[16:17]
	global_load_lds_dwordx4 v[106:107], off
	s_mov_b64 s[16:17], 0x594e080
	s_add_u32 m0, s100, 0xb000
	v_lshl_add_u64 v[106:107], v[252:253], 0, s[16:17]
	global_load_lds_dwordx4 v[106:107], off
	v_lshl_add_u64 v[252:253], v[252:253], 0, s[4:5]
	ds_read_b128 v[244:247], v167 offset:49152
	ds_read_b128 v[248:251], v167 offset:53248
	ds_read_b128 v[224:227], v163
	s_waitcnt lgkmcnt(4)
	v_mfma_f32_32x32x16_bf16 v[48:63], v[228:231], v[236:239], v[48:63]
	v_mfma_f32_32x32x16_bf16 v[32:47], v[228:231], v[240:243], v[32:47]
	s_mov_b64 s[16:17], 0x1600080
	s_add_u32 m0, s100, 0x10000
	v_lshl_add_u64 v[106:107], v[254:255], 0, s[16:17]
	global_load_lds_dwordx4 v[106:107], off
	s_mov_b64 s[16:17], 0x162c080
	s_add_u32 m0, s100, 0x11000
	v_lshl_add_u64 v[106:107], v[254:255], 0, s[16:17]
	global_load_lds_dwordx4 v[106:107], off
	ds_read_b128 v[228:231], v163 offset:4096
	s_waitcnt lgkmcnt(4)
	v_mfma_f32_32x32x16_bf16 v[16:31], v[232:235], v[236:239], v[16:31]
	v_mfma_f32_32x32x16_bf16 v[0:15], v[232:235], v[240:243], v[0:15]
	s_mov_b64 s[16:17], 0x1658080
	s_add_u32 m0, s100, 0x12000
	v_lshl_add_u64 v[106:107], v[254:255], 0, s[16:17]
	global_load_lds_dwordx4 v[106:107], off
	s_mov_b64 s[16:17], 0x1684080
	s_add_u32 m0, s100, 0x13000
	v_lshl_add_u64 v[106:107], v[254:255], 0, s[16:17]
	global_load_lds_dwordx4 v[106:107], off
	v_lshl_add_u64 v[254:255], v[254:255], 0, s[4:5]
	ds_read_b128 v[232:235], v163 offset:8192
	s_waitcnt lgkmcnt(2)
	v_mfma_f32_32x32x16_bf16 v[80:95], v[224:227], v[244:247], v[80:95]
	v_mfma_f32_32x32x16_bf16 v[64:79], v[224:227], v[248:251], v[64:79]
	ds_read_b128 v[236:239], v168 offset:49152
	ds_read_b128 v[240:243], v168 offset:53248
	ds_read_b128 v[224:227], v164
	s_waitcnt lgkmcnt(4)
	v_mfma_f32_32x32x16_bf16 v[48:63], v[228:231], v[244:247], v[48:63]
	v_mfma_f32_32x32x16_bf16 v[32:47], v[228:231], v[248:251], v[32:47]
	ds_read_b128 v[228:231], v164 offset:4096
	s_waitcnt lgkmcnt(4)
	v_mfma_f32_32x32x16_bf16 v[16:31], v[232:235], v[244:247], v[16:31]
	v_mfma_f32_32x32x16_bf16 v[0:15], v[232:235], v[248:251], v[0:15]
	ds_read_b128 v[232:235], v164 offset:8192
	s_waitcnt lgkmcnt(2)
	v_mfma_f32_32x32x16_bf16 v[80:95], v[224:227], v[236:239], v[80:95]
	v_mfma_f32_32x32x16_bf16 v[64:79], v[224:227], v[240:243], v[64:79]
	ds_read_b128 v[244:247], v169 offset:49152
	ds_read_b128 v[248:251], v169 offset:53248
	ds_read_b128 v[224:227], v165
	s_waitcnt lgkmcnt(4)
	v_mfma_f32_32x32x16_bf16 v[48:63], v[228:231], v[236:239], v[48:63]
	v_mfma_f32_32x32x16_bf16 v[32:47], v[228:231], v[240:243], v[32:47]
	ds_read_b128 v[228:231], v165 offset:4096
	s_waitcnt lgkmcnt(4)
	v_mfma_f32_32x32x16_bf16 v[16:31], v[232:235], v[236:239], v[16:31]
	v_mfma_f32_32x32x16_bf16 v[0:15], v[232:235], v[240:243], v[0:15]
	ds_read_b128 v[232:235], v165 offset:8192
	s_waitcnt lgkmcnt(2)
	v_mfma_f32_32x32x16_bf16 v[80:95], v[224:227], v[244:247], v[80:95]
	v_mfma_f32_32x32x16_bf16 v[64:79], v[224:227], v[248:251], v[64:79]
	s_waitcnt lgkmcnt(0)
	s_waitcnt vmcnt(0)
	s_barrier
	s_cmp_eq_u32 s15, 42
	s_cbranch_scc1 .Lgd_noearly
	s_mov_b64 s[16:17], 0x5872080
	s_mov_b32 m0, s100
	v_lshl_add_u64 v[106:107], v[252:253], 0, s[16:17]
	global_load_lds_dwordx4 v[106:107], off
	s_mov_b64 s[16:17], 0x589e080
	s_add_u32 m0, s100, 0x1000
	v_lshl_add_u64 v[106:107], v[252:253], 0, s[16:17]
	global_load_lds_dwordx4 v[106:107], off
	s_mov_b64 s[16:17], 0x58ca080
	s_add_u32 m0, s100, 0x2000
	v_lshl_add_u64 v[106:107], v[252:253], 0, s[16:17]
	global_load_lds_dwordx4 v[106:107], off
	s_mov_b64 s[16:17], 0x58f6080
	s_add_u32 m0, s100, 0x3000
	v_lshl_add_u64 v[106:107], v[252:253], 0, s[16:17]
	global_load_lds_dwordx4 v[106:107], off
; template <int EPI, int MI>
; DI void gemm_tile(const GemmDesc& g, int tm, int tn, char* smem) {
;     ...
;   const int rowA = wm * (32 * MI) + r, rowB = wn * 64 + r;
;   const int hk = hh ^ ((r & 7) ^ ((r >> 3) & 3));
;     ...
;   G_GLDS(0, 0);
;   asm volatile("s_waitcnt vmcnt(0)" ::: "memory");
;   __syncthreads();
;   for (int kt = 0; kt < nk; kt += 2) {
;     if (kt + 1 < nk) G_GLDS(kt + 1, 1);
;     G_COMPUTE(0);
;     asm volatile("s_waitcnt vmcnt(0)" ::: "memory");
;     __syncthreads();
;     if (kt + 1 < nk) {
;       if (kt + 2 < nk) G_GLDS(kt + 2, 0);
;       G_COMPUTE(1);
;       asm volatile("s_waitcnt vmcnt(0)" ::: "memory");
;       __syncthreads();
;     }
;   }
.Lgd_noearly:
	ds_read_b128 v[236:239], v170
	ds_read_b128 v[240:243], v170 offset:4096
	ds_read_b128 v[224:227], v162 offset:24576
	v_mfma_f32_32x32x16_bf16 v[48:63], v[228:231], v[244:247], v[48:63]
	v_mfma_f32_32x32x16_bf16 v[32:47], v[228:231], v[248:251], v[32:47]
	ds_read_b128 v[228:231], v162 offset:28672
	v_mfma_f32_32x32x16_bf16 v[16:31], v[232:235], v[244:247], v[16:31]
	v_mfma_f32_32x32x16_bf16 v[0:15], v[232:235], v[248:251], v[0:15]
	s_cmp_eq_u32 s15, 42
	s_cbranch_scc1 .Lgd_last
	ds_read_b128 v[232:235], v162 offset:32768
	s_waitcnt lgkmcnt(2)
	v_mfma_f32_32x32x16_bf16 v[80:95], v[224:227], v[236:239], v[80:95]
	v_mfma_f32_32x32x16_bf16 v[64:79], v[224:227], v[240:243], v[64:79]
	s_mov_b64 s[16:17], 0x5922080
	s_add_u32 m0, s100, 0x4000
	v_lshl_add_u64 v[106:107], v[252:253], 0, s[16:17]
	global_load_lds_dwordx4 v[106:107], off
	s_mov_b64 s[16:17], 0x594e080
	s_add_u32 m0, s100, 0x5000
	v_lshl_add_u64 v[106:107], v[252:253], 0, s[16:17]
	global_load_lds_dwordx4 v[106:107], off
	v_lshl_add_u64 v[252:253], v[252:253], 0, s[4:5]
	ds_read_b128 v[244:247], v171
	ds_read_b128 v[248:251], v171 offset:4096
	ds_read_b128 v[224:227], v163 offset:24576
	s_waitcnt lgkmcnt(4)
	v_mfma_f32_32x32x16_bf16 v[48:63], v[228:231], v[236:239], v[48:63]
	v_mfma_f32_32x32x16_bf16 v[32:47], v[228:231], v[240:243], v[32:47]
	s_mov_b64 s[16:17], 0x1600080
	s_add_u32 m0, s100, 0xc000
	v_lshl_add_u64 v[106:107], v[254:255], 0, s[16:17]
	global_load_lds_dwordx4 v[106:107], off
	s_mov_b64 s[16:17], 0x162c080
	s_add_u32 m0, s100, 0xd000
	v_lshl_add_u64 v[106:107], v[254:255], 0, s[16:17]
	global_load_lds_dwordx4 v[106:107], off
	ds_read_b128 v[228:231], v163 offset:28672
	s_waitcnt lgkmcnt(4)
	v_mfma_f32_32x32x16_bf16 v[16:31], v[232:235], v[236:239], v[16:31]
	v_mfma_f32_32x32x16_bf16 v[0:15], v[232:235], v[240:243], v[0:15]
	s_mov_b64 s[16:17], 0x1658080
	s_add_u32 m0, s100, 0xe000
	v_lshl_add_u64 v[106:107], v[254:255], 0, s[16:17]
	global_load_lds_dwordx4 v[106:107], off
	s_mov_b64 s[16:17], 0x1684080
	s_add_u32 m0, s100, 0xf000
	v_lshl_add_u64 v[106:107], v[254:255], 0, s[16:17]
	global_load_lds_dwordx4 v[106:107], off
	v_lshl_add_u64 v[254:255], v[254:255], 0, s[4:5]
	ds_read_b128 v[232:235], v163 offset:32768
	s_waitcnt lgkmcnt(2)
	v_mfma_f32_32x32x16_bf16 v[80:95], v[224:227], v[244:247], v[80:95]
	v_mfma_f32_32x32x16_bf16 v[64:79], v[224:227], v[248:251], v[64:79]
	ds_read_b128 v[236:239], v172
	ds_read_b128 v[240:243], v172 offset:4096
	ds_read_b128 v[224:227], v164 offset:24576
	s_waitcnt lgkmcnt(4)
	v_mfma_f32_32x32x16_bf16 v[48:63], v[228:231], v[244:247], v[48:63]
	v_mfma_f32_32x32x16_bf16 v[32:47], v[228:231], v[248:251], v[32:47]
	ds_read_b128 v[228:231], v164 offset:28672
	s_waitcnt lgkmcnt(4)
	v_mfma_f32_32x32x16_bf16 v[16:31], v[232:235], v[244:247], v[16:31]
	v_mfma_f32_32x32x16_bf16 v[0:15], v[232:235], v[248:251], v[0:15]
	ds_read_b128 v[232:235], v164 offset:32768
	s_waitcnt lgkmcnt(2)
	v_mfma_f32_32x32x16_bf16 v[80:95], v[224:227], v[236:239], v[80:95]
	v_mfma_f32_32x32x16_bf16 v[64:79], v[224:227], v[240:243], v[64:79]
	ds_read_b128 v[244:247], v173
	ds_read_b128 v[248:251], v173 offset:4096
	ds_read_b128 v[224:227], v165 offset:24576
	s_waitcnt lgkmcnt(4)
	v_mfma_f32_32x32x16_bf16 v[48:63], v[228:231], v[236:239], v[48:63]
	v_mfma_f32_32x32x16_bf16 v[32:47], v[228:231], v[240:243], v[32:47]
	ds_read_b128 v[228:231], v165 offset:28672
	s_waitcnt lgkmcnt(4)
	v_mfma_f32_32x32x16_bf16 v[16:31], v[232:235], v[236:239], v[16:31]
	v_mfma_f32_32x32x16_bf16 v[0:15], v[232:235], v[240:243], v[0:15]
	ds_read_b128 v[232:235], v165 offset:32768
	s_waitcnt lgkmcnt(2)
	v_mfma_f32_32x32x16_bf16 v[80:95], v[224:227], v[244:247], v[80:95]
	v_mfma_f32_32x32x16_bf16 v[64:79], v[224:227], v[248:251], v[64:79]
	s_waitcnt lgkmcnt(0)
	s_waitcnt vmcnt(0)
	s_barrier
	s_mov_b64 s[16:17], 0x5872080
	s_add_u32 m0, s100, 0x6000
	v_lshl_add_u64 v[106:107], v[252:253], 0, s[16:17]
	global_load_lds_dwordx4 v[106:107], off
	s_mov_b64 s[16:17], 0x589e080
	s_add_u32 m0, s100, 0x7000
	v_lshl_add_u64 v[106:107], v[252:253], 0, s[16:17]
	global_load_lds_dwordx4 v[106:107], off
	s_mov_b64 s[16:17], 0x58ca080
	s_add_u32 m0, s100, 0x8000
	v_lshl_add_u64 v[106:107], v[252:253], 0, s[16:17]
	global_load_lds_dwordx4 v[106:107], off
	s_mov_b64 s[16:17], 0x58f6080
	s_add_u32 m0, s100, 0x9000
	v_lshl_add_u64 v[106:107], v[252:253], 0, s[16:17]
	global_load_lds_dwordx4 v[106:107], off
	ds_read_b128 v[236:239], v166 offset:49152
	ds_read_b128 v[240:243], v166 offset:53248
	ds_read_b128 v[224:227], v162
	v_mfma_f32_32x32x16_bf16 v[48:63], v[228:231], v[244:247], v[48:63]
	v_mfma_f32_32x32x16_bf16 v[32:47], v[228:231], v[248:251], v[32:47]
	ds_read_b128 v[228:231], v162 offset:4096
	v_mfma_f32_32x32x16_bf16 v[16:31], v[232:235], v[244:247], v[16:31]
	v_mfma_f32_32x32x16_bf16 v[0:15], v[232:235], v[248:251], v[0:15]
	s_add_u32 s15, s15, 2
	s_branch .Lgd_loop

; template <int EPI, int MI>
; DI void gemm_tile(const GemmDesc& g, int tm, int tn, char* smem) {
;     ...
;   const int tid = get_tid(), lane = tid & 63, wave = tid >> 6, r = lane & 31, hh = lane >> 5;
;   const int wm = wave >> 1, wn = wave & 1;
;   const int m0 = tm * BM, n0 = tn * 128;
;   const int nk = g.K >> 6;
;   f32x16 acc[MI][2];
; #pragma unroll
;   for (int a = 0; a < MI; ++a)
; #pragma unroll
;     for (int b = 0; b < 2; ++b)
; #pragma unroll
;       for (int i = 0; i < 16; ++i) acc[a][b][i] = 0.f;
;   const int srow = tid >> 3;
;   const int schunk = (tid & 7) ^ ((srow & 7) ^ ((srow >> 3) & 3));
;     ...
;   const int rowA = wm * (32 * MI) + r, rowB = wn * 64 + r;
;   const int hk = hh ^ ((r & 7) ^ ((r >> 3) & 3));
;     ...
;   G_GLDS(0, 0);
;   asm volatile("s_waitcnt vmcnt(0)" ::: "memory");
;   __syncthreads();
; template <int EPI, int MI>
; DI void gemm_phase(const GemmDesc& g, char* smem, int vb, int nvb) {
;     ...
;   for (int q = start; q < local; q += step) {
;     const int mg = q / per;
;     const int rem = q - mg * per;
;     const int tn = rem / PM;
;     const int tm = mbase + mg * PM + (rem - tn * PM);
;     gemm_tile<EPI, MI>(g, tm, tn, smem);
.LBB0_371:
	s_abs_i32 s1, s47
	s_mul_hi_u32 s4, s1, s45
	s_mul_i32 s5, s4, s43
	s_sub_i32 s1, s1, s5
	s_ashr_i32 s0, s47, 31
	s_add_i32 s5, s4, 1
	s_sub_i32 s15, s1, s43
	s_cmp_ge_u32 s1, s43
	s_cselect_b32 s4, s5, s4
	s_cselect_b32 s1, s15, s1
	s_add_i32 s5, s4, 1
	s_cmp_ge_u32 s1, s43
	s_cselect_b32 s1, s5, s4
	s_xor_b32 s1, s1, s0
	s_sub_i32 s4, s1, s0
	s_mul_i32 s5, s4, s43
	s_sub_i32 s5, s47, s5
	s_abs_i32 s16, s5
	v_readlane_b32 s17, v219, 46
	s_mul_hi_u32 s17, s16, s17
	v_readlane_b32 s38, v218, 32
	s_mul_i32 s18, s17, s38
	s_sub_i32 s16, s16, s18
	s_ashr_i32 s15, s5, 31
	s_add_i32 s18, s17, 1
	s_sub_i32 s19, s16, s38
	s_cmp_ge_u32 s16, s38
	s_cselect_b32 s17, s18, s17
	s_cselect_b32 s16, s19, s16
	s_add_i32 s18, s17, 1
	s_cmp_ge_u32 s16, s38
	s_cselect_b32 s16, s18, s17
	s_xor_b32 s16, s16, s15
	s_sub_i32 s17, s16, s15
	s_sub_i32 s18, s4, s17
	v_mov_b32_e32 v97, v132
	s_mul_i32 s18, s18, s38
	s_add_i32 s5, s5, s54
	s_add_i32 s48, s5, s18
	v_ashrrev_i32_e32 v0, 7, v97
	v_and_b32_e32 v1, 7, v97
	v_mul_lo_u32 v115, v0, s6
	v_lshrrev_b32_e32 v0, 3, v97
	s_mulk_i32 s48, 0xc0
	s_waitcnt vmcnt(8)
	v_bfe_u32 v109, v97, 5, 1
	v_ashrrev_i32_e32 v8, 3, v97
	v_bitop3_b32 v0, v0, v1, 3 bitop3:0x6c
	v_bfe_u32 v2, v97, 6, 2
	v_xor_b32_e32 v3, v8, v97
	v_xor_b32_e32 v10, v0, v109
	v_add_u32_e32 v0, s48, v8
	s_lshl_b32 s49, s17, 7
	v_bitop3_b32 v2, v3, v2, 7 bitop3:0x6c
	v_ashrrev_i32_e32 v1, 31, v0
	v_readlane_b32 s18, v223, 59
	v_lshlrev_b64 v[0:1], 11, v[0:1]
	v_readlane_b32 s19, v223, 60
	v_lshlrev_b32_e32 v98, 4, v2
	v_add_u32_e32 v2, s49, v8
	v_lshlrev_b32_e32 v120, 4, v97
	v_lshl_add_u64 v[0:1], s[18:19], 0, v[0:1]
	v_ashrrev_i32_e32 v3, 31, v2
	v_readlane_b32 s18, v221, 16
	v_add_u32_e32 v121, 0, v120
	v_mov_b32_e32 v99, v96
	v_lshlrev_b64 v[2:3], 11, v[2:3]
	v_readlane_b32 s19, v221, 17
	v_readfirstlane_b32 s5, v121
	v_add_u32_e32 v122, 0x1000, v121
	v_lshl_add_u64 v[0:1], v[0:1], 0, v[98:99]
	v_lshl_add_u64 v[4:5], s[18:19], 0, v[2:3]
	s_mov_b32 m0, s5
	s_mov_b64 s[18:19], 0x10000
	v_readfirstlane_b32 s5, v122
	v_add_u32_e32 v123, 0x2000, v121
	global_load_lds_dwordx4 v[0:1], off
	v_lshl_add_u64 v[6:7], v[0:1], 0, s[18:19]
	s_mov_b32 m0, s5
	s_mov_b64 s[38:39], 0x20000
	v_readfirstlane_b32 s5, v123
	v_add_u32_e32 v124, 0x3000, v121
	global_load_lds_dwordx4 v[6:7], off
	v_lshl_add_u64 v[6:7], v[0:1], 0, s[38:39]
	s_mov_b32 m0, s5
	s_mov_b64 s[52:53], 0x30000
	v_readfirstlane_b32 s5, v124
	v_add_u32_e32 v125, 0x4000, v121
	global_load_lds_dwordx4 v[6:7], off
	v_lshl_add_u64 v[6:7], v[0:1], 0, s[52:53]
	s_mov_b32 m0, s5
	s_mov_b64 s[72:73], 0x40000
	v_readfirstlane_b32 s5, v125
	v_add_u32_e32 v126, 0x5000, v121
	global_load_lds_dwordx4 v[6:7], off
	v_lshl_add_u64 v[6:7], v[0:1], 0, s[72:73]
	s_mov_b32 m0, s5
	s_mov_b64 s[72:73], 0x50000
	v_readfirstlane_b32 s5, v126
	v_add_u32_e32 v127, 0xc000, v121
	global_load_lds_dwordx4 v[6:7], off
	v_lshl_add_u64 v[0:1], v[0:1], 0, s[72:73]
	s_mov_b32 m0, s5
	v_readfirstlane_b32 s5, v127
	v_add_u32_e32 v128, 0xd000, v121
	global_load_lds_dwordx4 v[0:1], off
	v_lshl_add_u64 v[0:1], v[4:5], 0, v[98:99]
	s_mov_b32 m0, s5
	v_readfirstlane_b32 s5, v128
	v_add_u32_e32 v129, 0xe000, v121
	global_load_lds_dwordx4 v[0:1], off
	v_lshl_add_u64 v[4:5], v[0:1], 0, s[18:19]
	s_mov_b32 m0, s5
	v_readfirstlane_b32 s5, v129
	v_add_u32_e32 v130, 0xf000, v121
	global_load_lds_dwordx4 v[4:5], off
	v_lshl_add_u64 v[4:5], v[0:1], 0, s[38:39]
	s_mov_b32 m0, s5
	v_readfirstlane_b32 s5, v130
	global_load_lds_dwordx4 v[4:5], off
	v_lshl_add_u64 v[0:1], v[0:1], 0, s[52:53]
	s_mov_b32 m0, s5
	s_add_i32 s1, s1, s15
	global_load_lds_dwordx4 v[0:1], off
	s_mul_i32 s4, s20, s4
	s_sub_i32 s1, s1, s4
	s_sub_i32 s1, s1, s16
	s_sub_i32 s0, s1, s0
	v_readlane_b32 s1, v218, 33
	v_lshlrev_b32_e32 v0, 7, v97
	s_mul_i32 s0, s1, s0
	v_and_b32_e32 v0, 0x2f80, v0
	s_add_i32 s0, s0, s46
	v_add_u32_e32 v153, 0, v0
	v_add_u32_e32 v155, s10, v0
	v_add_u32_e32 v0, s0, v8
	v_ashrrev_i32_e32 v1, 31, v0
	v_and_b32_e32 v108, 31, v97
	s_waitcnt vmcnt(0)
	v_lshlrev_b64 v[0:1], 11, v[0:1]
	v_or_b32_e32 v9, v115, v108
	v_lshlrev_b32_e32 v154, 4, v10
	v_lshl_add_u64 v[102:103], s[70:71], 0, v[0:1]
	v_mov_b32_e32 v0, 0
	v_lshl_add_u32 v131, v9, 7, 0
	v_xor_b32_e32 v156, 32, v154
	v_xor_b32_e32 v157, 64, v154
	v_xor_b32_e32 v158, 0x60, v154
	v_lshl_add_u64 v[100:101], s[70:71], 0, v[2:3]
	s_mov_b32 s4, 0
	v_mov_b32_e32 v1, v0
	v_mov_b32_e32 v2, v0
	v_mov_b32_e32 v3, v0
	v_mov_b32_e32 v4, v0
	v_mov_b32_e32 v5, v0
	v_mov_b32_e32 v6, v0
	v_mov_b32_e32 v7, v0
	v_mov_b32_e32 v8, v0
	v_mov_b32_e32 v9, v0
	v_mov_b32_e32 v10, v0
	v_mov_b32_e32 v11, v0
	v_mov_b32_e32 v12, v0
	v_mov_b32_e32 v13, v0
	v_mov_b32_e32 v14, v0
	v_mov_b32_e32 v15, v0
	v_mov_b32_e32 v16, v0
	v_mov_b32_e32 v17, v0
	v_mov_b32_e32 v18, v0
	v_mov_b32_e32 v19, v0
	v_mov_b32_e32 v20, v0
	v_mov_b32_e32 v21, v0
	v_mov_b32_e32 v22, v0
	v_mov_b32_e32 v23, v0
	v_mov_b32_e32 v24, v0
	v_mov_b32_e32 v25, v0
	v_mov_b32_e32 v26, v0
	v_mov_b32_e32 v27, v0
	v_mov_b32_e32 v28, v0
	v_mov_b32_e32 v29, v0
	v_mov_b32_e32 v30, v0
	v_mov_b32_e32 v31, v0
	v_mov_b32_e32 v32, v0
	v_mov_b32_e32 v33, v0
	v_mov_b32_e32 v34, v0
	v_mov_b32_e32 v35, v0
	v_mov_b32_e32 v36, v0
	v_mov_b32_e32 v37, v0
	v_mov_b32_e32 v38, v0
	v_mov_b32_e32 v39, v0
	v_mov_b32_e32 v40, v0
	v_mov_b32_e32 v41, v0
	v_mov_b32_e32 v42, v0
	v_mov_b32_e32 v43, v0
	v_mov_b32_e32 v44, v0
	v_mov_b32_e32 v45, v0
	v_mov_b32_e32 v46, v0
	v_mov_b32_e32 v47, v0
	v_mov_b32_e32 v48, v0
	s_waitcnt vmcnt(0)
; template <int EPI, int MI>
; DI void gemm_tile(const GemmDesc& g, int tm, int tn, char* smem) {
;     ...
;   f32x16 acc[MI][2];
; #pragma unroll
;   for (int a = 0; a < MI; ++a)
; #pragma unroll
;     for (int b = 0; b < 2; ++b)
; #pragma unroll
;       for (int i = 0; i < 16; ++i) acc[a][b][i] = 0.f;
;   const int srow = tid >> 3;
;   const int schunk = (tid & 7) ^ ((srow & 7) ^ ((srow >> 3) & 3));
;     ...
;   const int rowA = wm * (32 * MI) + r, rowB = wn * 64 + r;
;   const int hk = hh ^ ((r & 7) ^ ((r >> 3) & 3));
;     ...
;   G_GLDS(0, 0);
;   asm volatile("s_waitcnt vmcnt(0)" ::: "memory");
;   __syncthreads();
;   for (int kt = 0; kt < nk; kt += 2) {
;     if (kt + 1 < nk) G_GLDS(kt + 1, 1);
;     G_COMPUTE(0);
;     asm volatile("s_waitcnt vmcnt(0)" ::: "memory");
;     __syncthreads();
;     if (kt + 1 < nk) {
;       if (kt + 2 < nk) G_GLDS(kt + 2, 0);
;       G_COMPUTE(1);
;       asm volatile("s_waitcnt vmcnt(0)" ::: "memory");
;       __syncthreads();
;     }
;   }
	v_mov_b32_e32 v49, v0
	v_mov_b32_e32 v50, v0
	v_mov_b32_e32 v51, v0
	v_mov_b32_e32 v52, v0
	v_mov_b32_e32 v53, v0
	v_mov_b32_e32 v54, v0
	v_mov_b32_e32 v55, v0
	v_mov_b32_e32 v56, v0
	v_mov_b32_e32 v57, v0
	v_mov_b32_e32 v58, v0
	v_mov_b32_e32 v59, v0
	v_mov_b32_e32 v60, v0
	v_mov_b32_e32 v61, v0
	v_mov_b32_e32 v62, v0
	v_mov_b32_e32 v63, v0
	v_mov_b32_e32 v64, v0
	v_mov_b32_e32 v65, v0
	v_mov_b32_e32 v66, v0
	v_mov_b32_e32 v67, v0
	v_mov_b32_e32 v68, v0
	v_mov_b32_e32 v69, v0
	v_mov_b32_e32 v70, v0
	v_mov_b32_e32 v71, v0
	v_mov_b32_e32 v72, v0
	v_mov_b32_e32 v73, v0
	v_mov_b32_e32 v74, v0
	v_mov_b32_e32 v75, v0
	v_mov_b32_e32 v76, v0
	v_mov_b32_e32 v77, v0
	v_mov_b32_e32 v78, v0
	v_mov_b32_e32 v79, v0
	v_mov_b32_e32 v80, v0
	v_mov_b32_e32 v81, v0
	v_mov_b32_e32 v82, v0
	v_mov_b32_e32 v83, v0
	v_mov_b32_e32 v84, v0
	v_mov_b32_e32 v85, v0
	v_mov_b32_e32 v86, v0
	v_mov_b32_e32 v87, v0
	v_mov_b32_e32 v88, v0
	v_mov_b32_e32 v89, v0
	v_mov_b32_e32 v90, v0
	v_mov_b32_e32 v91, v0
	v_mov_b32_e32 v92, v0
	v_mov_b32_e32 v93, v0
	v_mov_b32_e32 v94, v0
	v_mov_b32_e32 v95, v0
	v_add_u32_e32 v162, v131, v154
	v_add_u32_e32 v163, v131, v156
	v_add_u32_e32 v164, v131, v157
	v_add_u32_e32 v165, v131, v158
	v_add_u32_e32 v166, v153, v154
	v_add_u32_e32 v167, v153, v156
	v_add_u32_e32 v168, v153, v157
	v_add_u32_e32 v169, v153, v158
	v_add_u32_e32 v170, v155, v154
	v_add_u32_e32 v171, v155, v156
	v_add_u32_e32 v172, v155, v157
	v_add_u32_e32 v173, v155, v158
	v_lshl_add_u64 v[252:253], v[102:103], 0, v[98:99]
	v_lshl_add_u64 v[254:255], v[100:101], 0, v[98:99]
	v_readfirstlane_b32 s100, v121
	s_mov_b64 s[0:1], 0x80
	s_waitcnt vmcnt(0) lgkmcnt(0)
	s_barrier
	s_add_u32 m0, s100, 0x6000
	v_lshl_add_u64 v[106:107], v[252:253], 0, s[96:97]
	global_load_lds_dwordx4 v[106:107], off
	s_add_u32 m0, s100, 0x7000
	v_lshl_add_u64 v[106:107], v[252:253], 0, s[50:51]
	global_load_lds_dwordx4 v[106:107], off
	s_add_u32 m0, s100, 0x8000
	v_lshl_add_u64 v[106:107], v[252:253], 0, s[24:25]
	global_load_lds_dwordx4 v[106:107], off
	s_add_u32 m0, s100, 0x9000
	v_lshl_add_u64 v[106:107], v[252:253], 0, s[26:27]
	global_load_lds_dwordx4 v[106:107], off
	ds_read_b128 v[236:239], v166 offset:49152
	ds_read_b128 v[240:243], v166 offset:53248
	ds_read_b128 v[224:227], v162
	ds_read_b128 v[228:231], v162 offset:4096
	s_mov_b32 s101, 0
.Lgw_loop:
	ds_read_b128 v[232:235], v162 offset:8192
	s_waitcnt lgkmcnt(2)
	v_mfma_f32_32x32x16_bf16 v[80:95], v[224:227], v[236:239], v[80:95]
	v_mfma_f32_32x32x16_bf16 v[64:79], v[224:227], v[240:243], v[64:79]
	s_add_u32 m0, s100, 0xa000
	v_lshl_add_u64 v[106:107], v[252:253], 0, s[28:29]
	global_load_lds_dwordx4 v[106:107], off
	s_add_u32 m0, s100, 0xb000
	v_lshl_add_u64 v[106:107], v[252:253], 0, s[30:31]
	global_load_lds_dwordx4 v[106:107], off
	v_lshl_add_u64 v[252:253], v[252:253], 0, s[0:1]
	ds_read_b128 v[244:247], v167 offset:49152
	ds_read_b128 v[248:251], v167 offset:53248
	ds_read_b128 v[224:227], v163
	s_waitcnt lgkmcnt(4)
	v_mfma_f32_32x32x16_bf16 v[48:63], v[228:231], v[236:239], v[48:63]
	v_mfma_f32_32x32x16_bf16 v[32:47], v[228:231], v[240:243], v[32:47]
	s_mov_b64 s[16:17], 0x2100080
	s_add_u32 m0, s100, 0x10000
	v_lshl_add_u64 v[106:107], v[254:255], 0, s[16:17]
	global_load_lds_dwordx4 v[106:107], off
	s_mov_b64 s[16:17], 0x2110080
	s_add_u32 m0, s100, 0x11000
	v_lshl_add_u64 v[106:107], v[254:255], 0, s[16:17]
	global_load_lds_dwordx4 v[106:107], off
	ds_read_b128 v[228:231], v163 offset:4096
	s_waitcnt lgkmcnt(4)
	v_mfma_f32_32x32x16_bf16 v[16:31], v[232:235], v[236:239], v[16:31]
	v_mfma_f32_32x32x16_bf16 v[0:15], v[232:235], v[240:243], v[0:15]
	s_mov_b64 s[16:17], 0x2120080
	s_add_u32 m0, s100, 0x12000
	v_lshl_add_u64 v[106:107], v[254:255], 0, s[16:17]
	global_load_lds_dwordx4 v[106:107], off
	s_mov_b64 s[16:17], 0x2130080
	s_add_u32 m0, s100, 0x13000
	v_lshl_add_u64 v[106:107], v[254:255], 0, s[16:17]
	global_load_lds_dwordx4 v[106:107], off
	v_lshl_add_u64 v[254:255], v[254:255], 0, s[0:1]
	ds_read_b128 v[232:235], v163 offset:8192
	s_waitcnt lgkmcnt(2)
	v_mfma_f32_32x32x16_bf16 v[80:95], v[224:227], v[244:247], v[80:95]
	v_mfma_f32_32x32x16_bf16 v[64:79], v[224:227], v[248:251], v[64:79]
	ds_read_b128 v[236:239], v168 offset:49152
	ds_read_b128 v[240:243], v168 offset:53248
	ds_read_b128 v[224:227], v164
	s_waitcnt lgkmcnt(4)
	v_mfma_f32_32x32x16_bf16 v[48:63], v[228:231], v[244:247], v[48:63]
	v_mfma_f32_32x32x16_bf16 v[32:47], v[228:231], v[248:251], v[32:47]
	ds_read_b128 v[228:231], v164 offset:4096
	s_waitcnt lgkmcnt(4)
	v_mfma_f32_32x32x16_bf16 v[16:31], v[232:235], v[244:247], v[16:31]
	v_mfma_f32_32x32x16_bf16 v[0:15], v[232:235], v[248:251], v[0:15]
	ds_read_b128 v[232:235], v164 offset:8192
	s_waitcnt lgkmcnt(2)
	v_mfma_f32_32x32x16_bf16 v[80:95], v[224:227], v[236:239], v[80:95]
	v_mfma_f32_32x32x16_bf16 v[64:79], v[224:227], v[240:243], v[64:79]
	ds_read_b128 v[244:247], v169 offset:49152
	ds_read_b128 v[248:251], v169 offset:53248
	ds_read_b128 v[224:227], v165
	s_waitcnt lgkmcnt(4)
	v_mfma_f32_32x32x16_bf16 v[48:63], v[228:231], v[236:239], v[48:63]
	v_mfma_f32_32x32x16_bf16 v[32:47], v[228:231], v[240:243], v[32:47]
	ds_read_b128 v[228:231], v165 offset:4096
	s_waitcnt lgkmcnt(4)
	v_mfma_f32_32x32x16_bf16 v[16:31], v[232:235], v[236:239], v[16:31]
	v_mfma_f32_32x32x16_bf16 v[0:15], v[232:235], v[240:243], v[0:15]
	ds_read_b128 v[232:235], v165 offset:8192
	s_waitcnt lgkmcnt(2)
	v_mfma_f32_32x32x16_bf16 v[80:95], v[224:227], v[244:247], v[80:95]
	v_mfma_f32_32x32x16_bf16 v[64:79], v[224:227], v[248:251], v[64:79]
	s_waitcnt lgkmcnt(0)
	s_waitcnt vmcnt(0)
	s_barrier
	s_cmp_eq_u32 s101, 14
	s_cbranch_scc1 .Lgw_noearly
	s_mov_b32 m0, s100
	v_lshl_add_u64 v[106:107], v[252:253], 0, s[96:97]
	global_load_lds_dwordx4 v[106:107], off
	s_add_u32 m0, s100, 0x1000
	v_lshl_add_u64 v[106:107], v[252:253], 0, s[50:51]
	global_load_lds_dwordx4 v[106:107], off
	s_add_u32 m0, s100, 0x2000
	v_lshl_add_u64 v[106:107], v[252:253], 0, s[24:25]
	global_load_lds_dwordx4 v[106:107], off
	s_add_u32 m0, s100, 0x3000
	v_lshl_add_u64 v[106:107], v[252:253], 0, s[26:27]
	global_load_lds_dwordx4 v[106:107], off
; template <int EPI, int MI>
; DI void gemm_tile(const GemmDesc& g, int tm, int tn, char* smem) {
;     ...
;   const int rowA = wm * (32 * MI) + r, rowB = wn * 64 + r;
;   const int hk = hh ^ ((r & 7) ^ ((r >> 3) & 3));
;     ...
;   G_GLDS(0, 0);
;   asm volatile("s_waitcnt vmcnt(0)" ::: "memory");
;   __syncthreads();
;   for (int kt = 0; kt < nk; kt += 2) {
;     if (kt + 1 < nk) G_GLDS(kt + 1, 1);
;     G_COMPUTE(0);
;     asm volatile("s_waitcnt vmcnt(0)" ::: "memory");
;     __syncthreads();
;     if (kt + 1 < nk) {
;       if (kt + 2 < nk) G_GLDS(kt + 2, 0);
;       G_COMPUTE(1);
;       asm volatile("s_waitcnt vmcnt(0)" ::: "memory");
;       __syncthreads();
;     }
;   }
.Lgw_noearly:
	ds_read_b128 v[236:239], v170
	ds_read_b128 v[240:243], v170 offset:4096
	ds_read_b128 v[224:227], v162 offset:24576
	v_mfma_f32_32x32x16_bf16 v[48:63], v[228:231], v[244:247], v[48:63]
	v_mfma_f32_32x32x16_bf16 v[32:47], v[228:231], v[248:251], v[32:47]
	ds_read_b128 v[228:231], v162 offset:28672
	v_mfma_f32_32x32x16_bf16 v[16:31], v[232:235], v[244:247], v[16:31]
	v_mfma_f32_32x32x16_bf16 v[0:15], v[232:235], v[248:251], v[0:15]
	s_cmp_eq_u32 s101, 14
	s_cbranch_scc1 .Lgw_last
	ds_read_b128 v[232:235], v162 offset:32768
	s_waitcnt lgkmcnt(2)
	v_mfma_f32_32x32x16_bf16 v[80:95], v[224:227], v[236:239], v[80:95]
	v_mfma_f32_32x32x16_bf16 v[64:79], v[224:227], v[240:243], v[64:79]
	s_add_u32 m0, s100, 0x4000
	v_lshl_add_u64 v[106:107], v[252:253], 0, s[28:29]
	global_load_lds_dwordx4 v[106:107], off
	s_add_u32 m0, s100, 0x5000
	v_lshl_add_u64 v[106:107], v[252:253], 0, s[30:31]
	global_load_lds_dwordx4 v[106:107], off
	v_lshl_add_u64 v[252:253], v[252:253], 0, s[0:1]
	ds_read_b128 v[244:247], v171
	ds_read_b128 v[248:251], v171 offset:4096
	ds_read_b128 v[224:227], v163 offset:24576
	s_waitcnt lgkmcnt(4)
	v_mfma_f32_32x32x16_bf16 v[48:63], v[228:231], v[236:239], v[48:63]
	v_mfma_f32_32x32x16_bf16 v[32:47], v[228:231], v[240:243], v[32:47]
	s_mov_b64 s[16:17], 0x2100080
	s_add_u32 m0, s100, 0xc000
	v_lshl_add_u64 v[106:107], v[254:255], 0, s[16:17]
	global_load_lds_dwordx4 v[106:107], off
	s_mov_b64 s[16:17], 0x2110080
	s_add_u32 m0, s100, 0xd000
	v_lshl_add_u64 v[106:107], v[254:255], 0, s[16:17]
	global_load_lds_dwordx4 v[106:107], off
	ds_read_b128 v[228:231], v163 offset:28672
	s_waitcnt lgkmcnt(4)
	v_mfma_f32_32x32x16_bf16 v[16:31], v[232:235], v[236:239], v[16:31]
	v_mfma_f32_32x32x16_bf16 v[0:15], v[232:235], v[240:243], v[0:15]
	s_mov_b64 s[16:17], 0x2120080
	s_add_u32 m0, s100, 0xe000
	v_lshl_add_u64 v[106:107], v[254:255], 0, s[16:17]
	global_load_lds_dwordx4 v[106:107], off
	s_mov_b64 s[16:17], 0x2130080
	s_add_u32 m0, s100, 0xf000
	v_lshl_add_u64 v[106:107], v[254:255], 0, s[16:17]
	global_load_lds_dwordx4 v[106:107], off
	v_lshl_add_u64 v[254:255], v[254:255], 0, s[0:1]
	ds_read_b128 v[232:235], v163 offset:32768
	s_waitcnt lgkmcnt(2)
	v_mfma_f32_32x32x16_bf16 v[80:95], v[224:227], v[244:247], v[80:95]
	v_mfma_f32_32x32x16_bf16 v[64:79], v[224:227], v[248:251], v[64:79]
	ds_read_b128 v[236:239], v172
	ds_read_b128 v[240:243], v172 offset:4096
	ds_read_b128 v[224:227], v164 offset:24576
	s_waitcnt lgkmcnt(4)
	v_mfma_f32_32x32x16_bf16 v[48:63], v[228:231], v[244:247], v[48:63]
	v_mfma_f32_32x32x16_bf16 v[32:47], v[228:231], v[248:251], v[32:47]
	ds_read_b128 v[228:231], v164 offset:28672
	s_waitcnt lgkmcnt(4)
	v_mfma_f32_32x32x16_bf16 v[16:31], v[232:235], v[244:247], v[16:31]
	v_mfma_f32_32x32x16_bf16 v[0:15], v[232:235], v[248:251], v[0:15]
	ds_read_b128 v[232:235], v164 offset:32768
	s_waitcnt lgkmcnt(2)
	v_mfma_f32_32x32x16_bf16 v[80:95], v[224:227], v[236:239], v[80:95]
	v_mfma_f32_32x32x16_bf16 v[64:79], v[224:227], v[240:243], v[64:79]
	ds_read_b128 v[244:247], v173
	ds_read_b128 v[248:251], v173 offset:4096
	ds_read_b128 v[224:227], v165 offset:24576
	s_waitcnt lgkmcnt(4)
	v_mfma_f32_32x32x16_bf16 v[48:63], v[228:231], v[236:239], v[48:63]
	v_mfma_f32_32x32x16_bf16 v[32:47], v[228:231], v[240:243], v[32:47]
	ds_read_b128 v[228:231], v165 offset:28672
	s_waitcnt lgkmcnt(4)
	v_mfma_f32_32x32x16_bf16 v[16:31], v[232:235], v[236:239], v[16:31]
	v_mfma_f32_32x32x16_bf16 v[0:15], v[232:235], v[240:243], v[0:15]
	ds_read_b128 v[232:235], v165 offset:32768
	s_waitcnt lgkmcnt(2)
	v_mfma_f32_32x32x16_bf16 v[80:95], v[224:227], v[244:247], v[80:95]
	v_mfma_f32_32x32x16_bf16 v[64:79], v[224:227], v[248:251], v[64:79]
	s_waitcnt lgkmcnt(0)
	s_waitcnt vmcnt(0)
	s_barrier
	s_add_u32 m0, s100, 0x6000
	v_lshl_add_u64 v[106:107], v[252:253], 0, s[96:97]
	global_load_lds_dwordx4 v[106:107], off
	s_add_u32 m0, s100, 0x7000
	v_lshl_add_u64 v[106:107], v[252:253], 0, s[50:51]
	global_load_lds_dwordx4 v[106:107], off
	s_add_u32 m0, s100, 0x8000
	v_lshl_add_u64 v[106:107], v[252:253], 0, s[24:25]
	global_load_lds_dwordx4 v[106:107], off
	s_add_u32 m0, s100, 0x9000
	v_lshl_add_u64 v[106:107], v[252:253], 0, s[26:27]
	global_load_lds_dwordx4 v[106:107], off
	ds_read_b128 v[236:239], v166 offset:49152
	ds_read_b128 v[240:243], v166 offset:53248
	ds_read_b128 v[224:227], v162
	v_mfma_f32_32x32x16_bf16 v[48:63], v[228:231], v[244:247], v[48:63]
	v_mfma_f32_32x32x16_bf16 v[32:47], v[228:231], v[248:251], v[32:47]
	ds_read_b128 v[228:231], v162 offset:4096
	v_mfma_f32_32x32x16_bf16 v[16:31], v[232:235], v[244:247], v[16:31]
	v_mfma_f32_32x32x16_bf16 v[0:15], v[232:235], v[248:251], v[0:15]
	s_add_u32 s101, s101, 2
	s_branch .Lgw_loop

; template <int EPI, int MI>
; DI void gemm_tile(const GemmDesc& g, int tm, int tn, char* smem) {
;     ...
;   const int tid = get_tid(), lane = tid & 63, wave = tid >> 6, r = lane & 31, hh = lane >> 5;
;   const int wm = wave >> 1, wn = wave & 1;
;   const int m0 = tm * BM, n0 = tn * 128;
;   const int nk = g.K >> 6;
;   f32x16 acc[MI][2];
; #pragma unroll
;   for (int a = 0; a < MI; ++a)
; #pragma unroll
;     for (int b = 0; b < 2; ++b)
; #pragma unroll
;       for (int i = 0; i < 16; ++i) acc[a][b][i] = 0.f;
;   const int srow = tid >> 3;
;   const int schunk = (tid & 7) ^ ((srow & 7) ^ ((srow >> 3) & 3));
;     ...
;   const int rowA = wm * (32 * MI) + r, rowB = wn * 64 + r;
;   const int hk = hh ^ ((r & 7) ^ ((r >> 3) & 3));
;     ...
;   G_GLDS(0, 0);
;   asm volatile("s_waitcnt vmcnt(0)" ::: "memory");
;   __syncthreads();
;   for (int kt = 0; kt < nk; kt += 2) {
;     if (kt + 1 < nk) G_GLDS(kt + 1, 1);
;     G_COMPUTE(0);
;     asm volatile("s_waitcnt vmcnt(0)" ::: "memory");
;     __syncthreads();
;     if (kt + 1 < nk) {
;       if (kt + 2 < nk) G_GLDS(kt + 2, 0);
;       G_COMPUTE(1);
;       asm volatile("s_waitcnt vmcnt(0)" ::: "memory");
;       __syncthreads();
;     }
;   }
.LBB0_1410:
	s_abs_i32 s1, s39
	s_mul_hi_u32 s40, s1, s17
	s_mul_i32 s41, s40, s15
	s_sub_i32 s1, s1, s41
	s_ashr_i32 s0, s39, 31
	s_add_i32 s41, s40, 1
	s_sub_i32 s42, s1, s15
	s_cmp_ge_u32 s1, s15
	s_cselect_b32 s40, s41, s40
	s_cselect_b32 s1, s42, s1
	s_add_i32 s41, s40, 1
	s_cmp_ge_u32 s1, s15
	s_cselect_b32 s1, s41, s40
	s_xor_b32 s1, s1, s0
	s_sub_i32 s40, s1, s0
	s_mul_i32 s41, s40, s15
	s_sub_i32 s42, s39, s41
	s_abs_i32 s41, s42
	s_mul_hi_u32 s44, s41, s18
	s_mul_i32 s45, s44, s4
	s_sub_i32 s41, s41, s45
	s_ashr_i32 s43, s42, 31
	s_add_i32 s45, s44, 1
	s_sub_i32 s46, s41, s4
	s_cmp_ge_u32 s41, s4
	s_cselect_b32 s44, s45, s44
	s_cselect_b32 s41, s46, s41
	s_add_i32 s45, s44, 1
	s_cmp_ge_u32 s41, s4
	s_cselect_b32 s41, s45, s44
	s_xor_b32 s44, s41, s43
	s_sub_i32 s41, s44, s43
	s_sub_i32 s40, s40, s41
	v_mov_b32_e32 v6, v132
	s_mul_i32 s40, s40, s4
	s_add_i32 s42, s42, s16
	s_add_i32 s42, s42, s40
	v_ashrrev_i32_e32 v76, 3, v6
	v_bfe_u32 v0, v6, 6, 2
	v_xor_b32_e32 v1, v76, v6
	s_lshl_b32 s40, s42, 7
	v_bitop3_b32 v2, v1, v0, 7 bitop3:0x6c
	v_ashrrev_i32_e32 v0, 1, v6
	v_and_b32_e32 v77, 7, v6
	v_and_b32_e32 v79, 0xffffffc0, v0
	v_lshrrev_b32_e32 v0, 3, v6
	v_add_u32_e32 v64, s40, v76
	v_bfe_u32 v78, v6, 5, 1
	v_bitop3_b32 v0, v0, v77, 3 bitop3:0x6c
	v_ashrrev_i32_e32 v65, 31, v64
	v_readlane_b32 s46, v223, 59
	v_and_b32_e32 v80, 31, v6
	v_bfe_u32 v81, v6, 6, 1
	v_xor_b32_e32 v9, v0, v78
	v_lshlrev_b64 v[0:1], 11, v[64:65]
	v_readlane_b32 s47, v223, 60
	v_lshlrev_b32_e32 v66, 4, v2
	v_lshl_add_u32 v2, s41, 7, v76
	v_lshlrev_b32_e32 v6, 4, v6
	v_lshl_add_u64 v[0:1], s[46:47], 0, v[0:1]
	v_ashrrev_i32_e32 v3, 31, v2
	v_readlane_b32 s46, v220, 54
	v_add_u32_e32 v65, 0, v6
	v_mov_b32_e32 v67, v96
	v_lshlrev_b64 v[2:3], 11, v[2:3]
	v_readlane_b32 s47, v220, 55
	v_readfirstlane_b32 s42, v65
	v_add_u32_e32 v82, 0x1000, v65
	v_lshl_add_u64 v[0:1], v[0:1], 0, v[66:67]
	v_lshl_add_u64 v[4:5], s[46:47], 0, v[2:3]
	s_mov_b32 m0, s42
	s_mov_b64 s[46:47], 0x10000
	v_readfirstlane_b32 s42, v82
	v_add_u32_e32 v83, 0x2000, v65
	global_load_lds_dwordx4 v[0:1], off
	v_lshl_add_u64 v[6:7], v[0:1], 0, s[46:47]
	s_mov_b32 m0, s42
	s_mov_b64 s[52:53], 0x20000
	v_readfirstlane_b32 s42, v83
	v_add_u32_e32 v84, 0x3000, v65
	global_load_lds_dwordx4 v[6:7], off
	v_lshl_add_u64 v[6:7], v[0:1], 0, s[52:53]
	s_mov_b32 m0, s42
	s_mov_b64 s[72:73], 0x30000
	v_readfirstlane_b32 s42, v84
	v_add_u32_e32 v85, 0x8000, v65
	global_load_lds_dwordx4 v[6:7], off
	v_lshl_add_u64 v[0:1], v[0:1], 0, s[72:73]
	s_mov_b32 m0, s42
	v_readfirstlane_b32 s42, v85
	v_add_u32_e32 v86, 0x9000, v65
	global_load_lds_dwordx4 v[0:1], off
	v_lshl_add_u64 v[0:1], v[4:5], 0, v[66:67]
	s_mov_b32 m0, s42
	v_readfirstlane_b32 s42, v86
	v_add_u32_e32 v87, 0xa000, v65
	global_load_lds_dwordx4 v[0:1], off
	v_lshl_add_u64 v[4:5], v[0:1], 0, s[46:47]
	s_mov_b32 m0, s42
	v_readfirstlane_b32 s42, v87
	v_add_u32_e32 v88, 0xb000, v65
	global_load_lds_dwordx4 v[4:5], off
	v_lshl_add_u64 v[4:5], v[0:1], 0, s[52:53]
	s_mov_b32 m0, s42
	v_readfirstlane_b32 s42, v88
	global_load_lds_dwordx4 v[4:5], off
	v_lshl_add_u64 v[0:1], v[0:1], 0, s[72:73]
	s_mov_b32 m0, s42
	s_mul_i32 s0, s0, 43
	global_load_lds_dwordx4 v[0:1], off
	s_add_i32 s43, s43, s0
	s_sub_i32 s0, s43, s44
	s_mul_i32 s1, s1, 43
	s_sub_i32 s0, s0, s1
	v_lshlrev_b32_e32 v0, 7, v80
	s_mul_i32 s0, s38, s0
	v_lshl_or_b32 v0, v81, 13, v0
	s_add_i32 s0, s0, s19
	v_add_u32_e32 v90, 0, v0
	v_add_u32_e32 v0, s0, v76
	v_ashrrev_i32_e32 v1, 31, v0
	s_waitcnt vmcnt(0)
	v_lshlrev_b64 v[0:1], 11, v[0:1]
	v_or_b32_e32 v8, v79, v80
	v_lshlrev_b32_e32 v91, 4, v9
	v_lshl_add_u64 v[68:69], s[70:71], 0, v[0:1]
	v_mov_b32_e32 v0, 0
	v_lshl_add_u32 v89, v8, 7, 0
	v_xor_b32_e32 v92, 32, v91
	v_xor_b32_e32 v93, 64, v91
	v_xor_b32_e32 v94, 0x60, v91
	v_lshl_add_u64 v[70:71], s[70:71], 0, v[2:3]
	s_mov_b32 s42, 0
	v_mov_b32_e32 v1, v0
	v_mov_b32_e32 v2, v0
	v_mov_b32_e32 v3, v0
	v_mov_b32_e32 v4, v0
	v_mov_b32_e32 v5, v0
	v_mov_b32_e32 v6, v0
	v_mov_b32_e32 v7, v0
	v_mov_b32_e32 v8, v0
	v_mov_b32_e32 v9, v0
	v_mov_b32_e32 v10, v0
	v_mov_b32_e32 v11, v0
	v_mov_b32_e32 v12, v0
	v_mov_b32_e32 v13, v0
	v_mov_b32_e32 v14, v0
	v_mov_b32_e32 v15, v0
	v_mov_b32_e32 v16, v0
	v_mov_b32_e32 v17, v0
	v_mov_b32_e32 v18, v0
	v_mov_b32_e32 v19, v0
	v_mov_b32_e32 v20, v0
	v_mov_b32_e32 v21, v0
	v_mov_b32_e32 v22, v0
	v_mov_b32_e32 v23, v0
	v_mov_b32_e32 v24, v0
	v_mov_b32_e32 v25, v0
	v_mov_b32_e32 v26, v0
	v_mov_b32_e32 v27, v0
	v_mov_b32_e32 v28, v0
	v_mov_b32_e32 v29, v0
	v_mov_b32_e32 v30, v0
	v_mov_b32_e32 v31, v0
	v_mov_b32_e32 v32, v0
	v_mov_b32_e32 v33, v0
	v_mov_b32_e32 v34, v0
	v_mov_b32_e32 v35, v0
	v_mov_b32_e32 v36, v0
	v_mov_b32_e32 v37, v0
	v_mov_b32_e32 v38, v0
	v_mov_b32_e32 v39, v0
	v_mov_b32_e32 v40, v0
	v_mov_b32_e32 v41, v0
	v_mov_b32_e32 v42, v0
	v_mov_b32_e32 v43, v0
	v_mov_b32_e32 v44, v0
	v_mov_b32_e32 v45, v0
	v_mov_b32_e32 v46, v0
	v_mov_b32_e32 v47, v0
	v_mov_b32_e32 v48, v0
	v_mov_b32_e32 v49, v0
	v_mov_b32_e32 v50, v0
	v_mov_b32_e32 v51, v0
	v_mov_b32_e32 v52, v0
	v_mov_b32_e32 v53, v0
	v_mov_b32_e32 v54, v0
	v_mov_b32_e32 v55, v0
	v_mov_b32_e32 v56, v0
	v_mov_b32_e32 v57, v0
	v_mov_b32_e32 v58, v0
	v_mov_b32_e32 v59, v0
	v_mov_b32_e32 v60, v0
	v_mov_b32_e32 v61, v0
	v_mov_b32_e32 v62, v0
	v_mov_b32_e32 v63, v0
	v_add_u32_e32 v98, v89, v91
	v_add_u32_e32 v99, v89, v92
	v_add_u32_e32 v100, v89, v93
	v_add_u32_e32 v101, v89, v94
	v_add_u32_e32 v102, v90, v91
	v_add_u32_e32 v103, v90, v92
	v_add_u32_e32 v104, v90, v93
	v_add_u32_e32 v105, v90, v94
	v_lshl_add_u64 v[72:73], v[68:69], 0, v[66:67]
	v_lshl_add_u64 v[74:75], v[70:71], 0, v[66:67]
	v_readfirstlane_b32 s100, v65
	s_mov_b64 s[44:45], 0x80
	s_waitcnt vmcnt(0) lgkmcnt(0)
	s_barrier
	s_add_u32 m0, s100, 0x4000
	v_lshl_add_u64 v[106:107], v[72:73], 0, s[96:97]
	global_load_lds_dwordx4 v[106:107], off
	s_add_u32 m0, s100, 0x5000
	v_lshl_add_u64 v[106:107], v[72:73], 0, s[50:51]
	global_load_lds_dwordx4 v[106:107], off
	s_add_u32 m0, s100, 0x6000
	v_lshl_add_u64 v[106:107], v[72:73], 0, s[24:25]
	global_load_lds_dwordx4 v[106:107], off
	s_add_u32 m0, s100, 0x7000
	v_lshl_add_u64 v[106:107], v[72:73], 0, s[26:27]
	global_load_lds_dwordx4 v[106:107], off
	v_lshl_add_u64 v[72:73], v[72:73], 0, s[44:45]
	ds_read_b128 v[240:243], v102 offset:32768
	ds_read_b128 v[244:247], v102 offset:36864
	ds_read_b128 v[224:227], v98
	ds_read_b128 v[228:231], v98 offset:4096
	s_mov_b32 s101, 0
; template <int EPI, int MI>
; DI void gemm_tile(const GemmDesc& g, int tm, int tn, char* smem) {
;     ...
;   const int rowA = wm * (32 * MI) + r, rowB = wn * 64 + r;
;   const int hk = hh ^ ((r & 7) ^ ((r >> 3) & 3));
;     ...
;   G_GLDS(0, 0);
;   asm volatile("s_waitcnt vmcnt(0)" ::: "memory");
;   __syncthreads();
;   for (int kt = 0; kt < nk; kt += 2) {
;     if (kt + 1 < nk) G_GLDS(kt + 1, 1);
;     G_COMPUTE(0);
;     asm volatile("s_waitcnt vmcnt(0)" ::: "memory");
;     __syncthreads();
;     if (kt + 1 < nk) {
;       if (kt + 2 < nk) G_GLDS(kt + 2, 0);
;       G_COMPUTE(1);
;       asm volatile("s_waitcnt vmcnt(0)" ::: "memory");
;       __syncthreads();
;     }
;   }
.Lgc_loop:
	ds_read_b128 v[248:251], v103 offset:32768
	ds_read_b128 v[252:255], v103 offset:36864
	ds_read_b128 v[232:235], v99
	s_waitcnt lgkmcnt(4)
	v_mfma_f32_32x32x16_bf16 v[48:63], v[224:227], v[240:243], v[48:63]
	v_mfma_f32_32x32x16_bf16 v[32:47], v[224:227], v[244:247], v[32:47]
	s_mov_b64 s[0:1], 0xb00080
	s_add_u32 m0, s100, 0xc000
	v_lshl_add_u64 v[106:107], v[74:75], 0, s[0:1]
	global_load_lds_dwordx4 v[106:107], off
	s_mov_b64 s[0:1], 0xb10080
	s_add_u32 m0, s100, 0xd000
	v_lshl_add_u64 v[106:107], v[74:75], 0, s[0:1]
	global_load_lds_dwordx4 v[106:107], off
	ds_read_b128 v[236:239], v99 offset:4096
	s_waitcnt lgkmcnt(4)
	v_mfma_f32_32x32x16_bf16 v[16:31], v[228:231], v[240:243], v[16:31]
	v_mfma_f32_32x32x16_bf16 v[0:15], v[228:231], v[244:247], v[0:15]
	s_mov_b64 s[0:1], 0xb20080
	s_add_u32 m0, s100, 0xe000
	v_lshl_add_u64 v[106:107], v[74:75], 0, s[0:1]
	global_load_lds_dwordx4 v[106:107], off
	s_mov_b64 s[0:1], 0xb30080
	s_add_u32 m0, s100, 0xf000
	v_lshl_add_u64 v[106:107], v[74:75], 0, s[0:1]
	global_load_lds_dwordx4 v[106:107], off
	v_lshl_add_u64 v[74:75], v[74:75], 0, s[44:45]
	ds_read_b128 v[240:243], v104 offset:32768
	ds_read_b128 v[244:247], v104 offset:36864
	ds_read_b128 v[224:227], v100
	s_waitcnt lgkmcnt(4)
	v_mfma_f32_32x32x16_bf16 v[48:63], v[232:235], v[248:251], v[48:63]
	v_mfma_f32_32x32x16_bf16 v[32:47], v[232:235], v[252:255], v[32:47]
	ds_read_b128 v[228:231], v100 offset:4096
	s_waitcnt lgkmcnt(4)
	v_mfma_f32_32x32x16_bf16 v[16:31], v[236:239], v[248:251], v[16:31]
	v_mfma_f32_32x32x16_bf16 v[0:15], v[236:239], v[252:255], v[0:15]
	ds_read_b128 v[248:251], v105 offset:32768
	ds_read_b128 v[252:255], v105 offset:36864
	ds_read_b128 v[232:235], v101
	s_waitcnt lgkmcnt(4)
	v_mfma_f32_32x32x16_bf16 v[48:63], v[224:227], v[240:243], v[48:63]
	v_mfma_f32_32x32x16_bf16 v[32:47], v[224:227], v[244:247], v[32:47]
	ds_read_b128 v[236:239], v101 offset:4096
	s_waitcnt lgkmcnt(4)
	v_mfma_f32_32x32x16_bf16 v[16:31], v[228:231], v[240:243], v[16:31]
	v_mfma_f32_32x32x16_bf16 v[0:15], v[228:231], v[244:247], v[0:15]
	s_waitcnt lgkmcnt(0)
	s_waitcnt vmcnt(0)
	s_barrier
	s_cmp_eq_u32 s101, 14
	s_cbranch_scc1 .Lgc_noearly
	s_mov_b32 m0, s100
	v_lshl_add_u64 v[106:107], v[72:73], 0, s[96:97]
	global_load_lds_dwordx4 v[106:107], off
	s_add_u32 m0, s100, 0x1000
	v_lshl_add_u64 v[106:107], v[72:73], 0, s[50:51]
	global_load_lds_dwordx4 v[106:107], off
	s_add_u32 m0, s100, 0x2000
	v_lshl_add_u64 v[106:107], v[72:73], 0, s[24:25]
	global_load_lds_dwordx4 v[106:107], off
	s_add_u32 m0, s100, 0x3000
	v_lshl_add_u64 v[106:107], v[72:73], 0, s[26:27]
	global_load_lds_dwordx4 v[106:107], off
	v_lshl_add_u64 v[72:73], v[72:73], 0, s[44:45]
.Lgc_noearly:
	ds_read_b128 v[240:243], v102 offset:49152
	ds_read_b128 v[244:247], v102 offset:53248
	ds_read_b128 v[224:227], v98 offset:16384
	v_mfma_f32_32x32x16_bf16 v[48:63], v[232:235], v[248:251], v[48:63]
	v_mfma_f32_32x32x16_bf16 v[32:47], v[232:235], v[252:255], v[32:47]
	ds_read_b128 v[228:231], v98 offset:20480
	v_mfma_f32_32x32x16_bf16 v[16:31], v[236:239], v[248:251], v[16:31]
	v_mfma_f32_32x32x16_bf16 v[0:15], v[236:239], v[252:255], v[0:15]
	s_cmp_eq_u32 s101, 14
	s_cbranch_scc1 .Lgc_last
	ds_read_b128 v[248:251], v103 offset:49152
	ds_read_b128 v[252:255], v103 offset:53248
	ds_read_b128 v[232:235], v99 offset:16384
	s_waitcnt lgkmcnt(4)
	v_mfma_f32_32x32x16_bf16 v[48:63], v[224:227], v[240:243], v[48:63]
	v_mfma_f32_32x32x16_bf16 v[32:47], v[224:227], v[244:247], v[32:47]
	s_mov_b64 s[0:1], 0xb00080
	s_add_u32 m0, s100, 0x8000
	v_lshl_add_u64 v[106:107], v[74:75], 0, s[0:1]
	global_load_lds_dwordx4 v[106:107], off
	s_mov_b64 s[0:1], 0xb10080
	s_add_u32 m0, s100, 0x9000
	v_lshl_add_u64 v[106:107], v[74:75], 0, s[0:1]
	global_load_lds_dwordx4 v[106:107], off
	ds_read_b128 v[236:239], v99 offset:20480
	s_waitcnt lgkmcnt(4)
	v_mfma_f32_32x32x16_bf16 v[16:31], v[228:231], v[240:243], v[16:31]
	v_mfma_f32_32x32x16_bf16 v[0:15], v[228:231], v[244:247], v[0:15]
	s_mov_b64 s[0:1], 0xb20080
	s_add_u32 m0, s100, 0xa000
	v_lshl_add_u64 v[106:107], v[74:75], 0, s[0:1]
	global_load_lds_dwordx4 v[106:107], off
	s_mov_b64 s[0:1], 0xb30080
	s_add_u32 m0, s100, 0xb000
	v_lshl_add_u64 v[106:107], v[74:75], 0, s[0:1]
	global_load_lds_dwordx4 v[106:107], off
	v_lshl_add_u64 v[74:75], v[74:75], 0, s[44:45]
	ds_read_b128 v[240:243], v104 offset:49152
	ds_read_b128 v[244:247], v104 offset:53248
	ds_read_b128 v[224:227], v100 offset:16384
	s_waitcnt lgkmcnt(4)
	v_mfma_f32_32x32x16_bf16 v[48:63], v[232:235], v[248:251], v[48:63]
	v_mfma_f32_32x32x16_bf16 v[32:47], v[232:235], v[252:255], v[32:47]
	ds_read_b128 v[228:231], v100 offset:20480
	s_waitcnt lgkmcnt(4)
	v_mfma_f32_32x32x16_bf16 v[16:31], v[236:239], v[248:251], v[16:31]
	v_mfma_f32_32x32x16_bf16 v[0:15], v[236:239], v[252:255], v[0:15]
	ds_read_b128 v[248:251], v105 offset:49152
	ds_read_b128 v[252:255], v105 offset:53248
	ds_read_b128 v[232:235], v101 offset:16384
	s_waitcnt lgkmcnt(4)
	v_mfma_f32_32x32x16_bf16 v[48:63], v[224:227], v[240:243], v[48:63]
	v_mfma_f32_32x32x16_bf16 v[32:47], v[224:227], v[244:247], v[32:47]
	ds_read_b128 v[236:239], v101 offset:20480
	s_waitcnt lgkmcnt(4)
	v_mfma_f32_32x32x16_bf16 v[16:31], v[228:231], v[240:243], v[16:31]
	v_mfma_f32_32x32x16_bf16 v[0:15], v[228:231], v[244:247], v[0:15]
	s_waitcnt lgkmcnt(0)
	s_waitcnt vmcnt(0)
	s_barrier
	s_add_u32 m0, s100, 0x4000
	v_lshl_add_u64 v[106:107], v[72:73], 0, s[96:97]
	global_load_lds_dwordx4 v[106:107], off
	s_add_u32 m0, s100, 0x5000
	v_lshl_add_u64 v[106:107], v[72:73], 0, s[50:51]
	global_load_lds_dwordx4 v[106:107], off
	s_add_u32 m0, s100, 0x6000
	v_lshl_add_u64 v[106:107], v[72:73], 0, s[24:25]
	global_load_lds_dwordx4 v[106:107], off
	s_add_u32 m0, s100, 0x7000
	v_lshl_add_u64 v[106:107], v[72:73], 0, s[26:27]
	global_load_lds_dwordx4 v[106:107], off
	v_lshl_add_u64 v[72:73], v[72:73], 0, s[44:45]
	ds_read_b128 v[240:243], v102 offset:32768
	ds_read_b128 v[244:247], v102 offset:36864
	ds_read_b128 v[224:227], v98
	v_mfma_f32_32x32x16_bf16 v[48:63], v[232:235], v[248:251], v[48:63]
	v_mfma_f32_32x32x16_bf16 v[32:47], v[232:235], v[252:255], v[32:47]
	ds_read_b128 v[228:231], v98 offset:4096
	v_mfma_f32_32x32x16_bf16 v[16:31], v[236:239], v[248:251], v[16:31]
	v_mfma_f32_32x32x16_bf16 v[0:15], v[236:239], v[252:255], v[0:15]
	s_add_u32 s101, s101, 2
	s_branch .Lgc_loop

; template <int EPI, int MI>
; DI void gemm_tile(const GemmDesc& g, int tm, int tn, char* smem) {
;     ...
;   const int tid = get_tid(), lane = tid & 63, wave = tid >> 6, r = lane & 31, hh = lane >> 5;
;   const int wm = wave >> 1, wn = wave & 1;
;   const int m0 = tm * BM, n0 = tn * 128;
;   const int nk = g.K >> 6;
;   f32x16 acc[MI][2];
; #pragma unroll
;   for (int a = 0; a < MI; ++a)
; #pragma unroll
;     for (int b = 0; b < 2; ++b)
; #pragma unroll
;       for (int i = 0; i < 16; ++i) acc[a][b][i] = 0.f;
;   const int srow = tid >> 3;
;   const int schunk = (tid & 7) ^ ((srow & 7) ^ ((srow >> 3) & 3));
;     ...
;   const int rowA = wm * (32 * MI) + r, rowB = wn * 64 + r;
;   const int hk = hh ^ ((r & 7) ^ ((r >> 3) & 3));
;     ...
;   G_GLDS(0, 0);
;   asm volatile("s_waitcnt vmcnt(0)" ::: "memory");
;   __syncthreads();
; template <int EPI, int MI>
; DI void gemm_phase(const GemmDesc& g, char* smem, int vb, int nvb) {
;     ...
;   for (int q = start; q < local; q += step) {
;     const int mg = q / per;
;     const int rem = q - mg * per;
;     const int tn = rem / PM;
;     const int tm = mbase + mg * PM + (rem - tn * PM);
;     gemm_tile<EPI, MI>(g, tm, tn, smem);
.LBB0_1421:
	s_abs_i32 s1, s5
	v_readlane_b32 s15, v219, 45
	s_mul_hi_u32 s15, s1, s15
	v_readlane_b32 s18, v219, 44
	s_mul_i32 s16, s15, s18
	s_sub_i32 s1, s1, s16
	s_ashr_i32 s0, s5, 31
	s_add_i32 s16, s15, 1
	s_sub_i32 s17, s1, s18
	s_cmp_ge_u32 s1, s18
	s_cselect_b32 s15, s16, s15
	s_cselect_b32 s1, s17, s1
	s_add_i32 s16, s15, 1
	s_cmp_ge_u32 s1, s18
	s_cselect_b32 s1, s16, s15
	s_xor_b32 s1, s1, s0
	s_sub_i32 s15, s1, s0
	s_mul_i32 s16, s15, s18
	s_sub_i32 s16, s5, s16
	s_abs_i32 s18, s16
	v_readlane_b32 s19, v219, 46
	s_mul_hi_u32 s19, s18, s19
	v_readlane_b32 s40, v218, 32
	s_mul_i32 s38, s19, s40
	s_sub_i32 s18, s18, s38
	s_ashr_i32 s17, s16, 31
	s_add_i32 s38, s19, 1
	s_sub_i32 s39, s18, s40
	s_cmp_ge_u32 s18, s40
	s_cselect_b32 s19, s38, s19
	s_cselect_b32 s18, s39, s18
	s_add_i32 s38, s19, 1
	s_cmp_ge_u32 s18, s40
	s_cselect_b32 s18, s38, s19
	s_xor_b32 s18, s18, s17
	s_sub_i32 s39, s18, s17
	s_sub_i32 s15, s15, s39
	v_mov_b32_e32 v6, v132
	s_mul_i32 s15, s15, s40
	s_add_i32 s16, s16, s54
	s_add_i32 s38, s16, s15
	v_ashrrev_i32_e32 v97, 3, v6
	v_ashrrev_i32_e32 v120, 7, v6
	v_bfe_u32 v0, v6, 6, 2
	v_xor_b32_e32 v1, v97, v6
	s_mulk_i32 s38, 0xc0
	v_and_b32_e32 v121, 31, v6
	v_bitop3_b32 v2, v1, v0, 7 bitop3:0x6c
	v_mul_lo_u32 v0, v120, s6
	v_and_b32_e32 v115, 7, v6
	v_or_b32_e32 v8, v0, v121
	v_lshrrev_b32_e32 v0, 3, v6
	s_waitcnt vmcnt(10)
	v_add_u32_e32 v98, s38, v97
	v_bfe_u32 v122, v6, 5, 1
	v_bitop3_b32 v0, v0, v115, 3 bitop3:0x6c
	v_ashrrev_i32_e32 v99, 31, v98
	v_readlane_b32 s40, v223, 59
	v_xor_b32_e32 v9, v0, v122
	v_lshlrev_b64 v[0:1], 11, v[98:99]
	v_readlane_b32 s41, v223, 60
	v_lshlrev_b32_e32 v100, 4, v2
	v_lshl_add_u32 v2, s39, 7, v97
	v_lshlrev_b32_e32 v99, 4, v6
	v_lshl_add_u64 v[0:1], s[40:41], 0, v[0:1]
	v_ashrrev_i32_e32 v3, 31, v2
	v_readlane_b32 s40, v220, 54
	v_add_u32_e32 v124, 0, v99
	v_mov_b32_e32 v101, v96
	v_lshlrev_b64 v[2:3], 11, v[2:3]
	v_readlane_b32 s41, v220, 55
	v_readfirstlane_b32 s15, v124
	v_add_u32_e32 v125, 0x1000, v124
	v_lshl_add_u64 v[0:1], v[0:1], 0, v[100:101]
	v_lshl_add_u64 v[4:5], s[40:41], 0, v[2:3]
	s_mov_b32 m0, s15
	s_mov_b64 s[40:41], 0x10000
	v_readfirstlane_b32 s15, v125
	v_add_u32_e32 v126, 0x2000, v124
	v_bfe_u32 v123, v6, 6, 1
	global_load_lds_dwordx4 v[0:1], off
	v_lshl_add_u64 v[6:7], v[0:1], 0, s[40:41]
	s_mov_b32 m0, s15
	s_mov_b64 s[42:43], 0x20000
	v_readfirstlane_b32 s15, v126
	v_add_u32_e32 v127, 0x3000, v124
	global_load_lds_dwordx4 v[6:7], off
	v_lshl_add_u64 v[6:7], v[0:1], 0, s[42:43]
	s_mov_b32 m0, s15
	s_mov_b64 s[44:45], 0x30000
	v_readfirstlane_b32 s15, v127
	v_add_u32_e32 v128, 0x4000, v124
	global_load_lds_dwordx4 v[6:7], off
	v_lshl_add_u64 v[6:7], v[0:1], 0, s[44:45]
	s_mov_b32 m0, s15
	s_mov_b64 s[46:47], 0x40000
	v_readfirstlane_b32 s15, v128
	v_add_u32_e32 v129, 0x5000, v124
	global_load_lds_dwordx4 v[6:7], off
	v_lshl_add_u64 v[6:7], v[0:1], 0, s[46:47]
	s_mov_b32 m0, s15
	s_mov_b64 s[46:47], 0x50000
	v_readfirstlane_b32 s15, v129
	v_add_u32_e32 v130, 0xc000, v124
	global_load_lds_dwordx4 v[6:7], off
	v_lshl_add_u64 v[0:1], v[0:1], 0, s[46:47]
	s_mov_b32 m0, s15
	v_readfirstlane_b32 s15, v130
	v_add_u32_e32 v131, 0xd000, v124
	global_load_lds_dwordx4 v[0:1], off
	v_lshl_add_u64 v[0:1], v[4:5], 0, v[100:101]
	s_mov_b32 m0, s15
	v_readfirstlane_b32 s15, v131
	v_add_u32_e32 v153, 0xe000, v124
	global_load_lds_dwordx4 v[0:1], off
	v_lshl_add_u64 v[4:5], v[0:1], 0, s[40:41]
	s_mov_b32 m0, s15
	v_readfirstlane_b32 s15, v153
	v_add_u32_e32 v154, 0xf000, v124
	global_load_lds_dwordx4 v[4:5], off
	v_lshl_add_u64 v[4:5], v[0:1], 0, s[42:43]
	s_mov_b32 m0, s15
	v_readfirstlane_b32 s15, v154
	global_load_lds_dwordx4 v[4:5], off
	v_lshl_add_u64 v[0:1], v[0:1], 0, s[44:45]
	s_mov_b32 m0, s15
	s_mul_i32 s0, s0, 43
	global_load_lds_dwordx4 v[0:1], off
	s_add_i32 s17, s17, s0
	s_sub_i32 s0, s17, s18
	s_mul_i32 s1, s1, 43
	s_sub_i32 s0, s0, s1
	v_readlane_b32 s1, v218, 33
	v_lshlrev_b32_e32 v0, 7, v121
	s_mul_i32 s0, s1, s0
	v_lshl_or_b32 v0, v123, 13, v0
	s_add_i32 s0, s0, s4
	v_add_u32_e32 v156, 0, v0
	v_add_u32_e32 v158, s10, v0
	v_add_u32_e32 v0, s0, v97
	v_ashrrev_i32_e32 v1, 31, v0
	s_waitcnt vmcnt(0)
	v_lshlrev_b64 v[0:1], 11, v[0:1]
	v_lshlrev_b32_e32 v157, 4, v9
	s_waitcnt vmcnt(0)
; template <int EPI, int MI>
; DI void gemm_tile(const GemmDesc& g, int tm, int tn, char* smem) {
;     ...
;   f32x16 acc[MI][2];
; #pragma unroll
;   for (int a = 0; a < MI; ++a)
; #pragma unroll
;     for (int b = 0; b < 2; ++b)
; #pragma unroll
;       for (int i = 0; i < 16; ++i) acc[a][b][i] = 0.f;
;   const int srow = tid >> 3;
;   const int schunk = (tid & 7) ^ ((srow & 7) ^ ((srow >> 3) & 3));
;     ...
;   const int rowA = wm * (32 * MI) + r, rowB = wn * 64 + r;
;   const int hk = hh ^ ((r & 7) ^ ((r >> 3) & 3));
;     ...
;   G_GLDS(0, 0);
;   asm volatile("s_waitcnt vmcnt(0)" ::: "memory");
;   __syncthreads();
;   for (int kt = 0; kt < nk; kt += 2) {
;     if (kt + 1 < nk) G_GLDS(kt + 1, 1);
;     G_COMPUTE(0);
;     asm volatile("s_waitcnt vmcnt(0)" ::: "memory");
;     __syncthreads();
;     if (kt + 1 < nk) {
;       if (kt + 2 < nk) G_GLDS(kt + 2, 0);
;       G_COMPUTE(1);
;       asm volatile("s_waitcnt vmcnt(0)" ::: "memory");
;       __syncthreads();
;     }
;   }
	v_lshl_add_u64 v[102:103], s[70:71], 0, v[0:1]
	v_mov_b32_e32 v0, 0
	v_lshl_add_u32 v155, v8, 7, 0
	v_xor_b32_e32 v159, 32, v157
	v_xor_b32_e32 v160, 64, v157
	v_xor_b32_e32 v161, 0x60, v157
	v_lshl_add_u64 v[104:105], s[70:71], 0, v[2:3]
	s_mov_b32 s15, 0
	v_mov_b32_e32 v1, v0
	v_mov_b32_e32 v2, v0
	v_mov_b32_e32 v3, v0
	v_mov_b32_e32 v4, v0
	v_mov_b32_e32 v5, v0
	v_mov_b32_e32 v6, v0
	v_mov_b32_e32 v7, v0
	v_mov_b32_e32 v8, v0
	v_mov_b32_e32 v9, v0
	v_mov_b32_e32 v10, v0
	v_mov_b32_e32 v11, v0
	v_mov_b32_e32 v12, v0
	v_mov_b32_e32 v13, v0
	v_mov_b32_e32 v14, v0
	v_mov_b32_e32 v15, v0
	v_mov_b32_e32 v16, v0
	v_mov_b32_e32 v17, v0
	v_mov_b32_e32 v18, v0
	v_mov_b32_e32 v19, v0
	v_mov_b32_e32 v20, v0
	v_mov_b32_e32 v21, v0
	v_mov_b32_e32 v22, v0
	v_mov_b32_e32 v23, v0
	v_mov_b32_e32 v24, v0
	v_mov_b32_e32 v25, v0
	v_mov_b32_e32 v26, v0
	v_mov_b32_e32 v27, v0
	v_mov_b32_e32 v28, v0
	v_mov_b32_e32 v29, v0
	v_mov_b32_e32 v30, v0
	v_mov_b32_e32 v31, v0
	v_mov_b32_e32 v32, v0
	v_mov_b32_e32 v33, v0
	v_mov_b32_e32 v34, v0
	v_mov_b32_e32 v35, v0
	v_mov_b32_e32 v36, v0
	v_mov_b32_e32 v37, v0
	v_mov_b32_e32 v38, v0
	v_mov_b32_e32 v39, v0
	v_mov_b32_e32 v40, v0
	v_mov_b32_e32 v41, v0
	v_mov_b32_e32 v42, v0
	v_mov_b32_e32 v43, v0
	v_mov_b32_e32 v44, v0
	v_mov_b32_e32 v45, v0
	v_mov_b32_e32 v46, v0
	v_mov_b32_e32 v47, v0
	v_mov_b32_e32 v48, v0
	v_mov_b32_e32 v49, v0
	v_mov_b32_e32 v50, v0
	v_mov_b32_e32 v51, v0
	v_mov_b32_e32 v52, v0
	v_mov_b32_e32 v53, v0
	v_mov_b32_e32 v54, v0
	v_mov_b32_e32 v55, v0
	v_mov_b32_e32 v56, v0
	v_mov_b32_e32 v57, v0
	v_mov_b32_e32 v58, v0
	v_mov_b32_e32 v59, v0
	v_mov_b32_e32 v60, v0
	v_mov_b32_e32 v61, v0
	v_mov_b32_e32 v62, v0
	v_mov_b32_e32 v63, v0
	v_mov_b32_e32 v64, v0
	v_mov_b32_e32 v65, v0
	v_mov_b32_e32 v66, v0
	v_mov_b32_e32 v67, v0
	v_mov_b32_e32 v68, v0
	v_mov_b32_e32 v69, v0
	v_mov_b32_e32 v70, v0
	v_mov_b32_e32 v71, v0
	v_mov_b32_e32 v72, v0
	v_mov_b32_e32 v73, v0
	v_mov_b32_e32 v74, v0
	v_mov_b32_e32 v75, v0
	v_mov_b32_e32 v76, v0
	v_mov_b32_e32 v77, v0
	v_mov_b32_e32 v78, v0
	v_mov_b32_e32 v79, v0
	v_mov_b32_e32 v80, v0
	v_mov_b32_e32 v81, v0
	v_mov_b32_e32 v82, v0
	v_mov_b32_e32 v83, v0
	v_mov_b32_e32 v84, v0
	v_mov_b32_e32 v85, v0
	v_mov_b32_e32 v86, v0
	v_mov_b32_e32 v87, v0
	v_mov_b32_e32 v88, v0
	v_mov_b32_e32 v89, v0
	v_mov_b32_e32 v90, v0
	v_mov_b32_e32 v91, v0
	v_mov_b32_e32 v92, v0
	v_mov_b32_e32 v93, v0
	v_mov_b32_e32 v94, v0
	v_mov_b32_e32 v95, v0
	v_add_u32_e32 v162, v155, v157
	v_add_u32_e32 v163, v155, v159
	v_add_u32_e32 v164, v155, v160
	v_add_u32_e32 v165, v155, v161
	v_add_u32_e32 v166, v156, v157
	v_add_u32_e32 v167, v156, v159
	v_add_u32_e32 v168, v156, v160
	v_add_u32_e32 v169, v156, v161
	v_add_u32_e32 v170, v158, v157
	v_add_u32_e32 v171, v158, v159
	v_add_u32_e32 v172, v158, v160
	v_add_u32_e32 v173, v158, v161
	v_lshl_add_u64 v[252:253], v[102:103], 0, v[100:101]
	v_lshl_add_u64 v[254:255], v[104:105], 0, v[100:101]
	v_readfirstlane_b32 s100, v124
	s_mov_b64 s[0:1], 0x80
	s_waitcnt vmcnt(0) lgkmcnt(0)
	s_barrier
	s_add_u32 m0, s100, 0x6000
	v_lshl_add_u64 v[106:107], v[252:253], 0, s[96:97]
	global_load_lds_dwordx4 v[106:107], off
	s_add_u32 m0, s100, 0x7000
	v_lshl_add_u64 v[106:107], v[252:253], 0, s[50:51]
	global_load_lds_dwordx4 v[106:107], off
	s_add_u32 m0, s100, 0x8000
	v_lshl_add_u64 v[106:107], v[252:253], 0, s[24:25]
	global_load_lds_dwordx4 v[106:107], off
	s_add_u32 m0, s100, 0x9000
	v_lshl_add_u64 v[106:107], v[252:253], 0, s[26:27]
	global_load_lds_dwordx4 v[106:107], off
	ds_read_b128 v[236:239], v166 offset:49152
	ds_read_b128 v[240:243], v166 offset:53248
	ds_read_b128 v[224:227], v162
	ds_read_b128 v[228:231], v162 offset:4096
	s_mov_b32 s101, 0
.Lgb_loop:
	ds_read_b128 v[232:235], v162 offset:8192
	s_waitcnt lgkmcnt(2)
	v_mfma_f32_32x32x16_bf16 v[80:95], v[224:227], v[236:239], v[80:95]
	v_mfma_f32_32x32x16_bf16 v[64:79], v[224:227], v[240:243], v[64:79]
	s_add_u32 m0, s100, 0xa000
	v_lshl_add_u64 v[106:107], v[252:253], 0, s[28:29]
	global_load_lds_dwordx4 v[106:107], off
	s_add_u32 m0, s100, 0xb000
	v_lshl_add_u64 v[106:107], v[252:253], 0, s[30:31]
	global_load_lds_dwordx4 v[106:107], off
	v_lshl_add_u64 v[252:253], v[252:253], 0, s[0:1]
	ds_read_b128 v[244:247], v167 offset:49152
	ds_read_b128 v[248:251], v167 offset:53248
	ds_read_b128 v[224:227], v163
	s_waitcnt lgkmcnt(4)
	v_mfma_f32_32x32x16_bf16 v[48:63], v[228:231], v[236:239], v[48:63]
	v_mfma_f32_32x32x16_bf16 v[32:47], v[228:231], v[240:243], v[32:47]
	s_mov_b64 s[16:17], 0xb00080
	s_add_u32 m0, s100, 0x10000
	v_lshl_add_u64 v[106:107], v[254:255], 0, s[16:17]
	global_load_lds_dwordx4 v[106:107], off
	s_mov_b64 s[16:17], 0xb10080
	s_add_u32 m0, s100, 0x11000
	v_lshl_add_u64 v[106:107], v[254:255], 0, s[16:17]
	global_load_lds_dwordx4 v[106:107], off
	ds_read_b128 v[228:231], v163 offset:4096
	s_waitcnt lgkmcnt(4)
	v_mfma_f32_32x32x16_bf16 v[16:31], v[232:235], v[236:239], v[16:31]
	v_mfma_f32_32x32x16_bf16 v[0:15], v[232:235], v[240:243], v[0:15]
	s_mov_b64 s[16:17], 0xb20080
	s_add_u32 m0, s100, 0x12000
	v_lshl_add_u64 v[106:107], v[254:255], 0, s[16:17]
	global_load_lds_dwordx4 v[106:107], off
	s_mov_b64 s[16:17], 0xb30080
	s_add_u32 m0, s100, 0x13000
	v_lshl_add_u64 v[106:107], v[254:255], 0, s[16:17]
	global_load_lds_dwordx4 v[106:107], off
	v_lshl_add_u64 v[254:255], v[254:255], 0, s[0:1]
	ds_read_b128 v[232:235], v163 offset:8192
	s_waitcnt lgkmcnt(2)
	v_mfma_f32_32x32x16_bf16 v[80:95], v[224:227], v[244:247], v[80:95]
	v_mfma_f32_32x32x16_bf16 v[64:79], v[224:227], v[248:251], v[64:79]
	ds_read_b128 v[236:239], v168 offset:49152
	ds_read_b128 v[240:243], v168 offset:53248
	ds_read_b128 v[224:227], v164
	s_waitcnt lgkmcnt(4)
	v_mfma_f32_32x32x16_bf16 v[48:63], v[228:231], v[244:247], v[48:63]
	v_mfma_f32_32x32x16_bf16 v[32:47], v[228:231], v[248:251], v[32:47]
	ds_read_b128 v[228:231], v164 offset:4096
	s_waitcnt lgkmcnt(4)
	v_mfma_f32_32x32x16_bf16 v[16:31], v[232:235], v[244:247], v[16:31]
	v_mfma_f32_32x32x16_bf16 v[0:15], v[232:235], v[248:251], v[0:15]
	ds_read_b128 v[232:235], v164 offset:8192
	s_waitcnt lgkmcnt(2)
	v_mfma_f32_32x32x16_bf16 v[80:95], v[224:227], v[236:239], v[80:95]
	v_mfma_f32_32x32x16_bf16 v[64:79], v[224:227], v[240:243], v[64:79]
	ds_read_b128 v[244:247], v169 offset:49152
	ds_read_b128 v[248:251], v169 offset:53248
	ds_read_b128 v[224:227], v165
	s_waitcnt lgkmcnt(4)
	v_mfma_f32_32x32x16_bf16 v[48:63], v[228:231], v[236:239], v[48:63]
	v_mfma_f32_32x32x16_bf16 v[32:47], v[228:231], v[240:243], v[32:47]
	ds_read_b128 v[228:231], v165 offset:4096
	s_waitcnt lgkmcnt(4)
	v_mfma_f32_32x32x16_bf16 v[16:31], v[232:235], v[236:239], v[16:31]
	v_mfma_f32_32x32x16_bf16 v[0:15], v[232:235], v[240:243], v[0:15]
	ds_read_b128 v[232:235], v165 offset:8192
	s_waitcnt lgkmcnt(2)
	v_mfma_f32_32x32x16_bf16 v[80:95], v[224:227], v[244:247], v[80:95]
	v_mfma_f32_32x32x16_bf16 v[64:79], v[224:227], v[248:251], v[64:79]
	s_waitcnt lgkmcnt(0)
	s_waitcnt vmcnt(0)
	s_barrier
; template <int EPI, int MI>
; DI void gemm_tile(const GemmDesc& g, int tm, int tn, char* smem) {
;     ...
;   const int rowA = wm * (32 * MI) + r, rowB = wn * 64 + r;
;   const int hk = hh ^ ((r & 7) ^ ((r >> 3) & 3));
;     ...
;   G_GLDS(0, 0);
;   asm volatile("s_waitcnt vmcnt(0)" ::: "memory");
;   __syncthreads();
;   for (int kt = 0; kt < nk; kt += 2) {
;     if (kt + 1 < nk) G_GLDS(kt + 1, 1);
;     G_COMPUTE(0);
;     asm volatile("s_waitcnt vmcnt(0)" ::: "memory");
;     __syncthreads();
;     if (kt + 1 < nk) {
;       if (kt + 2 < nk) G_GLDS(kt + 2, 0);
;       G_COMPUTE(1);
;       asm volatile("s_waitcnt vmcnt(0)" ::: "memory");
;       __syncthreads();
;     }
;   }
	s_cmp_eq_u32 s101, 14
	s_cbranch_scc1 .Lgb_noearly
	s_mov_b32 m0, s100
	v_lshl_add_u64 v[106:107], v[252:253], 0, s[96:97]
	global_load_lds_dwordx4 v[106:107], off
	s_add_u32 m0, s100, 0x1000
	v_lshl_add_u64 v[106:107], v[252:253], 0, s[50:51]
	global_load_lds_dwordx4 v[106:107], off
	s_add_u32 m0, s100, 0x2000
	v_lshl_add_u64 v[106:107], v[252:253], 0, s[24:25]
	global_load_lds_dwordx4 v[106:107], off
	s_add_u32 m0, s100, 0x3000
	v_lshl_add_u64 v[106:107], v[252:253], 0, s[26:27]
	global_load_lds_dwordx4 v[106:107], off
.Lgb_noearly:
	ds_read_b128 v[236:239], v170
	ds_read_b128 v[240:243], v170 offset:4096
	ds_read_b128 v[224:227], v162 offset:24576
	v_mfma_f32_32x32x16_bf16 v[48:63], v[228:231], v[244:247], v[48:63]
	v_mfma_f32_32x32x16_bf16 v[32:47], v[228:231], v[248:251], v[32:47]
	ds_read_b128 v[228:231], v162 offset:28672
	v_mfma_f32_32x32x16_bf16 v[16:31], v[232:235], v[244:247], v[16:31]
	v_mfma_f32_32x32x16_bf16 v[0:15], v[232:235], v[248:251], v[0:15]
	s_cmp_eq_u32 s101, 14
	s_cbranch_scc1 .Lgb_last
	ds_read_b128 v[232:235], v162 offset:32768
	s_waitcnt lgkmcnt(2)
	v_mfma_f32_32x32x16_bf16 v[80:95], v[224:227], v[236:239], v[80:95]
	v_mfma_f32_32x32x16_bf16 v[64:79], v[224:227], v[240:243], v[64:79]
	s_add_u32 m0, s100, 0x4000
	v_lshl_add_u64 v[106:107], v[252:253], 0, s[28:29]
	global_load_lds_dwordx4 v[106:107], off
	s_add_u32 m0, s100, 0x5000
	v_lshl_add_u64 v[106:107], v[252:253], 0, s[30:31]
	global_load_lds_dwordx4 v[106:107], off
	v_lshl_add_u64 v[252:253], v[252:253], 0, s[0:1]
	ds_read_b128 v[244:247], v171
	ds_read_b128 v[248:251], v171 offset:4096
	ds_read_b128 v[224:227], v163 offset:24576
	s_waitcnt lgkmcnt(4)
	v_mfma_f32_32x32x16_bf16 v[48:63], v[228:231], v[236:239], v[48:63]
	v_mfma_f32_32x32x16_bf16 v[32:47], v[228:231], v[240:243], v[32:47]
	s_mov_b64 s[16:17], 0xb00080
	s_add_u32 m0, s100, 0xc000
	v_lshl_add_u64 v[106:107], v[254:255], 0, s[16:17]
	global_load_lds_dwordx4 v[106:107], off
	s_mov_b64 s[16:17], 0xb10080
	s_add_u32 m0, s100, 0xd000
	v_lshl_add_u64 v[106:107], v[254:255], 0, s[16:17]
	global_load_lds_dwordx4 v[106:107], off
	ds_read_b128 v[228:231], v163 offset:28672
	s_waitcnt lgkmcnt(4)
	v_mfma_f32_32x32x16_bf16 v[16:31], v[232:235], v[236:239], v[16:31]
	v_mfma_f32_32x32x16_bf16 v[0:15], v[232:235], v[240:243], v[0:15]
	s_mov_b64 s[16:17], 0xb20080
	s_add_u32 m0, s100, 0xe000
	v_lshl_add_u64 v[106:107], v[254:255], 0, s[16:17]
	global_load_lds_dwordx4 v[106:107], off
	s_mov_b64 s[16:17], 0xb30080
	s_add_u32 m0, s100, 0xf000
	v_lshl_add_u64 v[106:107], v[254:255], 0, s[16:17]
	global_load_lds_dwordx4 v[106:107], off
	v_lshl_add_u64 v[254:255], v[254:255], 0, s[0:1]
	ds_read_b128 v[232:235], v163 offset:32768
	s_waitcnt lgkmcnt(2)
	v_mfma_f32_32x32x16_bf16 v[80:95], v[224:227], v[244:247], v[80:95]
	v_mfma_f32_32x32x16_bf16 v[64:79], v[224:227], v[248:251], v[64:79]
	ds_read_b128 v[236:239], v172
	ds_read_b128 v[240:243], v172 offset:4096
	ds_read_b128 v[224:227], v164 offset:24576
	s_waitcnt lgkmcnt(4)
	v_mfma_f32_32x32x16_bf16 v[48:63], v[228:231], v[244:247], v[48:63]
	v_mfma_f32_32x32x16_bf16 v[32:47], v[228:231], v[248:251], v[32:47]
	ds_read_b128 v[228:231], v164 offset:28672
	s_waitcnt lgkmcnt(4)
	v_mfma_f32_32x32x16_bf16 v[16:31], v[232:235], v[244:247], v[16:31]
	v_mfma_f32_32x32x16_bf16 v[0:15], v[232:235], v[248:251], v[0:15]
	ds_read_b128 v[232:235], v164 offset:32768
	s_waitcnt lgkmcnt(2)
	v_mfma_f32_32x32x16_bf16 v[80:95], v[224:227], v[236:239], v[80:95]
	v_mfma_f32_32x32x16_bf16 v[64:79], v[224:227], v[240:243], v[64:79]
	ds_read_b128 v[244:247], v173
	ds_read_b128 v[248:251], v173 offset:4096
	ds_read_b128 v[224:227], v165 offset:24576
	s_waitcnt lgkmcnt(4)
	v_mfma_f32_32x32x16_bf16 v[48:63], v[228:231], v[236:239], v[48:63]
	v_mfma_f32_32x32x16_bf16 v[32:47], v[228:231], v[240:243], v[32:47]
	ds_read_b128 v[228:231], v165 offset:28672
	s_waitcnt lgkmcnt(4)
	v_mfma_f32_32x32x16_bf16 v[16:31], v[232:235], v[236:239], v[16:31]
	v_mfma_f32_32x32x16_bf16 v[0:15], v[232:235], v[240:243], v[0:15]
	ds_read_b128 v[232:235], v165 offset:32768
	s_waitcnt lgkmcnt(2)
	v_mfma_f32_32x32x16_bf16 v[80:95], v[224:227], v[244:247], v[80:95]
	v_mfma_f32_32x32x16_bf16 v[64:79], v[224:227], v[248:251], v[64:79]
	s_waitcnt lgkmcnt(0)
	s_waitcnt vmcnt(0)
	s_barrier
	s_add_u32 m0, s100, 0x6000
	v_lshl_add_u64 v[106:107], v[252:253], 0, s[96:97]
	global_load_lds_dwordx4 v[106:107], off
	s_add_u32 m0, s100, 0x7000
	v_lshl_add_u64 v[106:107], v[252:253], 0, s[50:51]
	global_load_lds_dwordx4 v[106:107], off
	s_add_u32 m0, s100, 0x8000
	v_lshl_add_u64 v[106:107], v[252:253], 0, s[24:25]
	global_load_lds_dwordx4 v[106:107], off
	s_add_u32 m0, s100, 0x9000
	v_lshl_add_u64 v[106:107], v[252:253], 0, s[26:27]
	global_load_lds_dwordx4 v[106:107], off
	ds_read_b128 v[236:239], v166 offset:49152
	ds_read_b128 v[240:243], v166 offset:53248
	ds_read_b128 v[224:227], v162
	v_mfma_f32_32x32x16_bf16 v[48:63], v[228:231], v[244:247], v[48:63]
	v_mfma_f32_32x32x16_bf16 v[32:47], v[228:231], v[248:251], v[32:47]
	ds_read_b128 v[228:231], v162 offset:4096
	v_mfma_f32_32x32x16_bf16 v[16:31], v[232:235], v[244:247], v[16:31]
	v_mfma_f32_32x32x16_bf16 v[0:15], v[232:235], v[248:251], v[0:15]
	s_add_u32 s101, s101, 2
	s_branch .Lgb_loop

; template <int EPI, int MI>
; DI void gemm_tile(const GemmDesc& g, int tm, int tn, char* smem) {
;     ...
;   const int tid = get_tid(), lane = tid & 63, wave = tid >> 6, r = lane & 31, hh = lane >> 5;
;   const int wm = wave >> 1, wn = wave & 1;
;   const int m0 = tm * BM, n0 = tn * 128;
;   const int nk = g.K >> 6;
;   f32x16 acc[MI][2];
; #pragma unroll
;   for (int a = 0; a < MI; ++a)
; #pragma unroll
;     for (int b = 0; b < 2; ++b)
; #pragma unroll
;       for (int i = 0; i < 16; ++i) acc[a][b][i] = 0.f;
;   const int srow = tid >> 3;
;   const int schunk = (tid & 7) ^ ((srow & 7) ^ ((srow >> 3) & 3));
;     ...
;   const int rowA = wm * (32 * MI) + r, rowB = wn * 64 + r;
;   const int hk = hh ^ ((r & 7) ^ ((r >> 3) & 3));
;     ...
;   G_GLDS(0, 0);
;   asm volatile("s_waitcnt vmcnt(0)" ::: "memory");
;   __syncthreads();
;   for (int kt = 0; kt < nk; kt += 2) {
;     if (kt + 1 < nk) G_GLDS(kt + 1, 1);
;     G_COMPUTE(0);
;     asm volatile("s_waitcnt vmcnt(0)" ::: "memory");
;     __syncthreads();
;     if (kt + 1 < nk) {
;       if (kt + 2 < nk) G_GLDS(kt + 2, 0);
;       G_COMPUTE(1);
;       asm volatile("s_waitcnt vmcnt(0)" ::: "memory");
;       __syncthreads();
;     }
;   }
.LBB0_1478:
	s_abs_i32 s0, s44
	s_mul_hi_u32 s1, s0, s42
	s_mul_i32 s4, s1, s38
	s_sub_i32 s0, s0, s4
	s_ashr_i32 s18, s44, 31
	s_add_i32 s4, s1, 1
	s_sub_i32 s5, s0, s38
	s_cmp_ge_u32 s0, s38
	s_cselect_b32 s1, s4, s1
	s_cselect_b32 s0, s5, s0
	s_add_i32 s4, s1, 1
	s_cmp_ge_u32 s0, s38
	s_cselect_b32 s0, s4, s1
	s_xor_b32 s19, s0, s18
	s_sub_i32 s0, s19, s18
	s_mul_i32 s1, s0, s38
	s_sub_i32 s1, s44, s1
	s_abs_i32 s4, s1
	s_mul_hi_u32 s5, s4, s16
	s_mul_i32 s45, s5, s15
	s_sub_i32 s4, s4, s45
	s_ashr_i32 s46, s1, 31
	s_add_i32 s45, s5, 1
	s_sub_i32 s47, s4, s15
	s_cmp_ge_u32 s4, s15
	s_cselect_b32 s5, s45, s5
	s_cselect_b32 s4, s47, s4
	s_add_i32 s45, s5, 1
	s_cmp_ge_u32 s4, s15
	s_cselect_b32 s4, s45, s5
	s_xor_b32 s47, s4, s46
	s_sub_i32 s4, s47, s46
	v_mov_b32_e32 v75, v132
	s_mul_i32 s0, s0, s15
	s_mul_i32 s5, s4, s15
	s_add_i32 s0, s0, s39
	v_ashrrev_i32_e32 v6, 3, v75
	s_sub_i32 s1, s1, s5
	v_bfe_u32 v1, v75, 6, 2
	v_xor_b32_e32 v2, v6, v75
	s_add_i32 s1, s0, s1
	s_lshl_b32 s0, s4, 7
	v_and_b32_e32 v0, 7, v75
	v_bitop3_b32 v2, v2, v1, 7 bitop3:0x6c
	v_lshrrev_b32_e32 v1, 3, v75
	v_readlane_b32 s4, v221, 5
	s_lshl_b32 s45, s1, 7
	v_bfe_u32 v77, v75, 5, 1
	v_bitop3_b32 v0, v1, v0, 3 bitop3:0x6c
	v_readlane_b32 s5, v221, 6
	v_xor_b32_e32 v7, v0, v77
	v_add_u32_e32 v3, s45, v6
	v_mov_b64_e32 v[0:1], s[4:5]
	s_movk_i32 s52, 0x1600
	v_mad_i64_i32 v[0:1], s[4:5], v3, s52, v[0:1]
	v_readlane_b32 s4, v220, 56
	v_readlane_b32 s5, v220, 57
	v_lshlrev_b32_e32 v64, 4, v2
	v_add_u32_e32 v8, s0, v6
	v_mov_b64_e32 v[2:3], s[4:5]
	v_lshlrev_b32_e32 v4, 4, v75
	v_mad_i64_i32 v[2:3], s[4:5], v8, s52, v[2:3]
	v_add_u32_e32 v78, 0, v4
	v_mov_b32_e32 v65, v96
	v_readfirstlane_b32 s4, v78
	v_add_u32_e32 v79, 0x1000, v78
	v_lshl_add_u64 v[0:1], v[0:1], 0, v[64:65]
	s_mov_b32 m0, s4
	s_mov_b64 s[72:73], 0x2c000
	v_readfirstlane_b32 s4, v79
	v_add_u32_e32 v80, 0x2000, v78
	global_load_lds_dwordx4 v[0:1], off
	v_lshl_add_u64 v[4:5], v[0:1], 0, s[72:73]
	s_mov_b32 m0, s4
	s_mov_b64 s[74:75], 0x58000
	v_readfirstlane_b32 s4, v80
	v_add_u32_e32 v81, 0x3000, v78
	global_load_lds_dwordx4 v[4:5], off
	v_lshl_add_u64 v[4:5], v[0:1], 0, s[74:75]
	s_mov_b32 m0, s4
	s_mov_b64 s[76:77], 0x84000
	v_readfirstlane_b32 s4, v81
	v_add_u32_e32 v82, 0x8000, v78
	global_load_lds_dwordx4 v[4:5], off
	v_lshl_add_u64 v[0:1], v[0:1], 0, s[76:77]
	s_mov_b32 m0, s4
	v_readfirstlane_b32 s4, v82
	v_add_u32_e32 v83, 0x9000, v78
	global_load_lds_dwordx4 v[0:1], off
	v_lshl_add_u64 v[0:1], v[2:3], 0, v[64:65]
	s_mov_b32 m0, s4
	v_readfirstlane_b32 s4, v83
	v_add_u32_e32 v84, 0xa000, v78
	global_load_lds_dwordx4 v[0:1], off
	v_lshl_add_u64 v[2:3], v[0:1], 0, s[72:73]
	s_mov_b32 m0, s4
	v_readfirstlane_b32 s4, v84
	v_add_u32_e32 v85, 0xb000, v78
	global_load_lds_dwordx4 v[2:3], off
	v_lshl_add_u64 v[2:3], v[0:1], 0, s[74:75]
	s_mov_b32 m0, s4
	v_readfirstlane_b32 s4, v85
	global_load_lds_dwordx4 v[2:3], off
	v_lshl_add_u64 v[0:1], v[0:1], 0, s[76:77]
	s_mov_b32 m0, s4
	s_mul_i32 s18, s18, 7
	global_load_lds_dwordx4 v[0:1], off
	v_and_b32_e32 v74, 31, v75
	s_add_i32 s46, s46, s18
	v_ashrrev_i32_e32 v76, 7, v75
	v_lshlrev_b32_e32 v0, 7, v74
	s_sub_i32 s4, s46, s47
	s_mul_i32 s19, s19, 7
	v_lshl_or_b32 v0, v76, 13, v0
	s_sub_i32 s4, s4, s19
	v_add_u32_e32 v86, 0, v0
	v_lshlrev_b32_e32 v0, 7, v75
	s_mul_i32 s4, s43, s4
	v_and_b32_e32 v0, 0x2f80, v0
	s_add_i32 s4, s4, s17
	s_waitcnt vmcnt(0)
	v_add_u32_e32 v87, 0, v0
	v_add_u32_e32 v2, s4, v6
	v_mov_b64_e32 v[0:1], s[70:71]
	s_waitcnt vmcnt(0)
	v_lshlrev_b32_e32 v88, 4, v7
	v_mad_i64_i32 v[66:67], s[4:5], v2, s52, v[0:1]
	v_mad_i64_i32 v[68:69], s[4:5], v8, s52, v[0:1]
	v_mov_b32_e32 v0, 0
	v_xor_b32_e32 v89, 32, v88
	v_xor_b32_e32 v90, 64, v88
	v_xor_b32_e32 v91, 0x60, v88
	s_mov_b32 s18, 0
	v_mov_b32_e32 v1, v0
	v_mov_b32_e32 v2, v0
	v_mov_b32_e32 v3, v0
	v_mov_b32_e32 v4, v0
	v_mov_b32_e32 v5, v0
	v_mov_b32_e32 v6, v0
	v_mov_b32_e32 v7, v0
	v_mov_b32_e32 v8, v0
	v_mov_b32_e32 v9, v0
	v_mov_b32_e32 v10, v0
	v_mov_b32_e32 v11, v0
	v_mov_b32_e32 v12, v0
	v_mov_b32_e32 v13, v0
	v_mov_b32_e32 v14, v0
	v_mov_b32_e32 v15, v0
	v_mov_b32_e32 v16, v0
	v_mov_b32_e32 v17, v0
	v_mov_b32_e32 v18, v0
	v_mov_b32_e32 v19, v0
	v_mov_b32_e32 v20, v0
	v_mov_b32_e32 v21, v0
	v_mov_b32_e32 v22, v0
	v_mov_b32_e32 v23, v0
	v_mov_b32_e32 v24, v0
	v_mov_b32_e32 v25, v0
	v_mov_b32_e32 v26, v0
	v_mov_b32_e32 v27, v0
	v_mov_b32_e32 v28, v0
	v_mov_b32_e32 v29, v0
	v_mov_b32_e32 v30, v0
	v_mov_b32_e32 v31, v0
	v_mov_b32_e32 v32, v0
	v_mov_b32_e32 v33, v0
	v_mov_b32_e32 v34, v0
	v_mov_b32_e32 v35, v0
	v_mov_b32_e32 v36, v0
	v_mov_b32_e32 v37, v0
	v_mov_b32_e32 v38, v0
	v_mov_b32_e32 v39, v0
	v_mov_b32_e32 v40, v0
	v_mov_b32_e32 v41, v0
	v_mov_b32_e32 v42, v0
	v_mov_b32_e32 v43, v0
	v_mov_b32_e32 v44, v0
	v_mov_b32_e32 v45, v0
	v_mov_b32_e32 v46, v0
	v_mov_b32_e32 v47, v0
	v_mov_b32_e32 v48, v0
	v_mov_b32_e32 v49, v0
	v_mov_b32_e32 v50, v0
	v_mov_b32_e32 v51, v0
	v_mov_b32_e32 v52, v0
	v_mov_b32_e32 v53, v0
	v_mov_b32_e32 v54, v0
	v_mov_b32_e32 v55, v0
	v_mov_b32_e32 v56, v0
	v_mov_b32_e32 v57, v0
	v_mov_b32_e32 v58, v0
	v_mov_b32_e32 v59, v0
	v_mov_b32_e32 v60, v0
	v_mov_b32_e32 v61, v0
	v_mov_b32_e32 v62, v0
	v_mov_b32_e32 v63, v0
	v_add_u32_e32 v92, v86, v88
	v_add_u32_e32 v93, v86, v89
	v_add_u32_e32 v94, v86, v90
	v_add_u32_e32 v95, v86, v91
	v_add_u32_e32 v97, v87, v88
	v_add_u32_e32 v98, v87, v89
	v_add_u32_e32 v99, v87, v90
	v_add_u32_e32 v100, v87, v91
	v_lshl_add_u64 v[104:105], v[66:67], 0, v[64:65]
	v_lshl_add_u64 v[106:107], v[68:69], 0, v[64:65]
	v_readfirstlane_b32 s100, v78
	s_mov_b64 s[46:47], 0x80
	s_waitcnt vmcnt(0) lgkmcnt(0)
	s_barrier
	s_mov_b64 s[4:5], 0x5872080
	s_add_u32 m0, s100, 0x4000
	v_lshl_add_u64 v[102:103], v[104:105], 0, s[4:5]
	global_load_lds_dwordx4 v[102:103], off
	s_mov_b64 s[4:5], 0x589e080
	s_add_u32 m0, s100, 0x5000
	v_lshl_add_u64 v[102:103], v[104:105], 0, s[4:5]
	global_load_lds_dwordx4 v[102:103], off
	s_mov_b64 s[4:5], 0x58ca080
	s_add_u32 m0, s100, 0x6000
	v_lshl_add_u64 v[102:103], v[104:105], 0, s[4:5]
	global_load_lds_dwordx4 v[102:103], off
	s_mov_b64 s[4:5], 0x58f6080
	s_add_u32 m0, s100, 0x7000
	v_lshl_add_u64 v[102:103], v[104:105], 0, s[4:5]
	global_load_lds_dwordx4 v[102:103], off
	v_lshl_add_u64 v[104:105], v[104:105], 0, s[46:47]
	ds_read_b128 v[240:243], v97 offset:32768
	ds_read_b128 v[244:247], v97 offset:36864
	ds_read_b128 v[224:227], v92
	ds_read_b128 v[228:231], v92 offset:4096
	s_mov_b32 s101, 0
; template <int EPI, int MI>
; DI void gemm_tile(const GemmDesc& g, int tm, int tn, char* smem) {
;     ...
;   const int rowA = wm * (32 * MI) + r, rowB = wn * 64 + r;
;   const int hk = hh ^ ((r & 7) ^ ((r >> 3) & 3));
;     ...
;   G_GLDS(0, 0);
;   asm volatile("s_waitcnt vmcnt(0)" ::: "memory");
;   __syncthreads();
;   for (int kt = 0; kt < nk; kt += 2) {
;     if (kt + 1 < nk) G_GLDS(kt + 1, 1);
;     G_COMPUTE(0);
;     asm volatile("s_waitcnt vmcnt(0)" ::: "memory");
;     __syncthreads();
;     if (kt + 1 < nk) {
;       if (kt + 2 < nk) G_GLDS(kt + 2, 0);
;       G_COMPUTE(1);
;       asm volatile("s_waitcnt vmcnt(0)" ::: "memory");
;       __syncthreads();
;     }
;   }
.Lgf_loop:
	ds_read_b128 v[248:251], v98 offset:32768
	ds_read_b128 v[252:255], v98 offset:36864
	ds_read_b128 v[232:235], v93
	s_waitcnt lgkmcnt(4)
	v_mfma_f32_32x32x16_bf16 v[48:63], v[224:227], v[240:243], v[48:63]
	v_mfma_f32_32x32x16_bf16 v[32:47], v[224:227], v[244:247], v[32:47]
	s_mov_b64 s[4:5], 0x1b80080
	s_add_u32 m0, s100, 0xc000
	v_lshl_add_u64 v[102:103], v[106:107], 0, s[4:5]
	global_load_lds_dwordx4 v[102:103], off
	s_mov_b64 s[4:5], 0x1bac080
	s_add_u32 m0, s100, 0xd000
	v_lshl_add_u64 v[102:103], v[106:107], 0, s[4:5]
	global_load_lds_dwordx4 v[102:103], off
	ds_read_b128 v[236:239], v93 offset:4096
	s_waitcnt lgkmcnt(4)
	v_mfma_f32_32x32x16_bf16 v[16:31], v[228:231], v[240:243], v[16:31]
	v_mfma_f32_32x32x16_bf16 v[0:15], v[228:231], v[244:247], v[0:15]
	s_mov_b64 s[4:5], 0x1bd8080
	s_add_u32 m0, s100, 0xe000
	v_lshl_add_u64 v[102:103], v[106:107], 0, s[4:5]
	global_load_lds_dwordx4 v[102:103], off
	s_mov_b64 s[4:5], 0x1c04080
	s_add_u32 m0, s100, 0xf000
	v_lshl_add_u64 v[102:103], v[106:107], 0, s[4:5]
	global_load_lds_dwordx4 v[102:103], off
	v_lshl_add_u64 v[106:107], v[106:107], 0, s[46:47]
	ds_read_b128 v[240:243], v99 offset:32768
	ds_read_b128 v[244:247], v99 offset:36864
	ds_read_b128 v[224:227], v94
	s_waitcnt lgkmcnt(4)
	v_mfma_f32_32x32x16_bf16 v[48:63], v[232:235], v[248:251], v[48:63]
	v_mfma_f32_32x32x16_bf16 v[32:47], v[232:235], v[252:255], v[32:47]
	ds_read_b128 v[228:231], v94 offset:4096
	s_waitcnt lgkmcnt(4)
	v_mfma_f32_32x32x16_bf16 v[16:31], v[236:239], v[248:251], v[16:31]
	v_mfma_f32_32x32x16_bf16 v[0:15], v[236:239], v[252:255], v[0:15]
	ds_read_b128 v[248:251], v100 offset:32768
	ds_read_b128 v[252:255], v100 offset:36864
	ds_read_b128 v[232:235], v95
	s_waitcnt lgkmcnt(4)
	v_mfma_f32_32x32x16_bf16 v[48:63], v[224:227], v[240:243], v[48:63]
	v_mfma_f32_32x32x16_bf16 v[32:47], v[224:227], v[244:247], v[32:47]
	ds_read_b128 v[236:239], v95 offset:4096
	s_waitcnt lgkmcnt(4)
	v_mfma_f32_32x32x16_bf16 v[16:31], v[228:231], v[240:243], v[16:31]
	v_mfma_f32_32x32x16_bf16 v[0:15], v[228:231], v[244:247], v[0:15]
	s_waitcnt lgkmcnt(0)
	s_waitcnt vmcnt(0)
	s_barrier
	s_cmp_eq_u32 s101, 42
	s_cbranch_scc1 .Lgf_noearly
	s_mov_b64 s[4:5], 0x5872080
	s_mov_b32 m0, s100
	v_lshl_add_u64 v[102:103], v[104:105], 0, s[4:5]
	global_load_lds_dwordx4 v[102:103], off
	s_mov_b64 s[4:5], 0x589e080
	s_add_u32 m0, s100, 0x1000
	v_lshl_add_u64 v[102:103], v[104:105], 0, s[4:5]
	global_load_lds_dwordx4 v[102:103], off
	s_mov_b64 s[4:5], 0x58ca080
	s_add_u32 m0, s100, 0x2000
	v_lshl_add_u64 v[102:103], v[104:105], 0, s[4:5]
	global_load_lds_dwordx4 v[102:103], off
	s_mov_b64 s[4:5], 0x58f6080
	s_add_u32 m0, s100, 0x3000
	v_lshl_add_u64 v[102:103], v[104:105], 0, s[4:5]
	global_load_lds_dwordx4 v[102:103], off
	v_lshl_add_u64 v[104:105], v[104:105], 0, s[46:47]
.Lgf_noearly:
	ds_read_b128 v[240:243], v97 offset:49152
	ds_read_b128 v[244:247], v97 offset:53248
	ds_read_b128 v[224:227], v92 offset:16384
	v_mfma_f32_32x32x16_bf16 v[48:63], v[232:235], v[248:251], v[48:63]
	v_mfma_f32_32x32x16_bf16 v[32:47], v[232:235], v[252:255], v[32:47]
	ds_read_b128 v[228:231], v92 offset:20480
	v_mfma_f32_32x32x16_bf16 v[16:31], v[236:239], v[248:251], v[16:31]
	v_mfma_f32_32x32x16_bf16 v[0:15], v[236:239], v[252:255], v[0:15]
	s_cmp_eq_u32 s101, 42
	s_cbranch_scc1 .Lgf_last
	ds_read_b128 v[248:251], v98 offset:49152
	ds_read_b128 v[252:255], v98 offset:53248
	ds_read_b128 v[232:235], v93 offset:16384
	s_waitcnt lgkmcnt(4)
	v_mfma_f32_32x32x16_bf16 v[48:63], v[224:227], v[240:243], v[48:63]
	v_mfma_f32_32x32x16_bf16 v[32:47], v[224:227], v[244:247], v[32:47]
	s_mov_b64 s[4:5], 0x1b80080
	s_add_u32 m0, s100, 0x8000
	v_lshl_add_u64 v[102:103], v[106:107], 0, s[4:5]
	global_load_lds_dwordx4 v[102:103], off
	s_mov_b64 s[4:5], 0x1bac080
	s_add_u32 m0, s100, 0x9000
	v_lshl_add_u64 v[102:103], v[106:107], 0, s[4:5]
	global_load_lds_dwordx4 v[102:103], off
	ds_read_b128 v[236:239], v93 offset:20480
	s_waitcnt lgkmcnt(4)
	v_mfma_f32_32x32x16_bf16 v[16:31], v[228:231], v[240:243], v[16:31]
	v_mfma_f32_32x32x16_bf16 v[0:15], v[228:231], v[244:247], v[0:15]
	s_mov_b64 s[4:5], 0x1bd8080
	s_add_u32 m0, s100, 0xa000
	v_lshl_add_u64 v[102:103], v[106:107], 0, s[4:5]
	global_load_lds_dwordx4 v[102:103], off
	s_mov_b64 s[4:5], 0x1c04080
	s_add_u32 m0, s100, 0xb000
	v_lshl_add_u64 v[102:103], v[106:107], 0, s[4:5]
	global_load_lds_dwordx4 v[102:103], off
	v_lshl_add_u64 v[106:107], v[106:107], 0, s[46:47]
	ds_read_b128 v[240:243], v99 offset:49152
	ds_read_b128 v[244:247], v99 offset:53248
	ds_read_b128 v[224:227], v94 offset:16384
	s_waitcnt lgkmcnt(4)
	v_mfma_f32_32x32x16_bf16 v[48:63], v[232:235], v[248:251], v[48:63]
	v_mfma_f32_32x32x16_bf16 v[32:47], v[232:235], v[252:255], v[32:47]
	ds_read_b128 v[228:231], v94 offset:20480
	s_waitcnt lgkmcnt(4)
	v_mfma_f32_32x32x16_bf16 v[16:31], v[236:239], v[248:251], v[16:31]
	v_mfma_f32_32x32x16_bf16 v[0:15], v[236:239], v[252:255], v[0:15]
	ds_read_b128 v[248:251], v100 offset:49152
	ds_read_b128 v[252:255], v100 offset:53248
	ds_read_b128 v[232:235], v95 offset:16384
	s_waitcnt lgkmcnt(4)
	v_mfma_f32_32x32x16_bf16 v[48:63], v[224:227], v[240:243], v[48:63]
	v_mfma_f32_32x32x16_bf16 v[32:47], v[224:227], v[244:247], v[32:47]
	ds_read_b128 v[236:239], v95 offset:20480
	s_waitcnt lgkmcnt(4)
	v_mfma_f32_32x32x16_bf16 v[16:31], v[228:231], v[240:243], v[16:31]
	v_mfma_f32_32x32x16_bf16 v[0:15], v[228:231], v[244:247], v[0:15]
	s_waitcnt lgkmcnt(0)
	s_waitcnt vmcnt(0)
	s_barrier
	s_mov_b64 s[4:5], 0x5872080
	s_add_u32 m0, s100, 0x4000
	v_lshl_add_u64 v[102:103], v[104:105], 0, s[4:5]
	global_load_lds_dwordx4 v[102:103], off
	s_mov_b64 s[4:5], 0x589e080
	s_add_u32 m0, s100, 0x5000
	v_lshl_add_u64 v[102:103], v[104:105], 0, s[4:5]
	global_load_lds_dwordx4 v[102:103], off
	s_mov_b64 s[4:5], 0x58ca080
	s_add_u32 m0, s100, 0x6000
	v_lshl_add_u64 v[102:103], v[104:105], 0, s[4:5]
	global_load_lds_dwordx4 v[102:103], off
	s_mov_b64 s[4:5], 0x58f6080
	s_add_u32 m0, s100, 0x7000
	v_lshl_add_u64 v[102:103], v[104:105], 0, s[4:5]
	global_load_lds_dwordx4 v[102:103], off
	v_lshl_add_u64 v[104:105], v[104:105], 0, s[46:47]
	ds_read_b128 v[240:243], v97 offset:32768
	ds_read_b128 v[244:247], v97 offset:36864
	ds_read_b128 v[224:227], v92
	v_mfma_f32_32x32x16_bf16 v[48:63], v[232:235], v[248:251], v[48:63]
	v_mfma_f32_32x32x16_bf16 v[32:47], v[232:235], v[252:255], v[32:47]
	ds_read_b128 v[228:231], v92 offset:4096
	v_mfma_f32_32x32x16_bf16 v[16:31], v[236:239], v[248:251], v[16:31]
	v_mfma_f32_32x32x16_bf16 v[0:15], v[236:239], v[252:255], v[0:15]
	s_add_u32 s101, s101, 2
	s_branch .Lgf_loop

; template <int EPI, int MI>
; DI void gemm_tile(const GemmDesc& g, int tm, int tn, char* smem) {
;     ...
;   const int tid = get_tid(), lane = tid & 63, wave = tid >> 6, r = lane & 31, hh = lane >> 5;
;   const int wm = wave >> 1, wn = wave & 1;
;   const int m0 = tm * BM, n0 = tn * 128;
;   const int nk = g.K >> 6;
;   f32x16 acc[MI][2];
; #pragma unroll
;   for (int a = 0; a < MI; ++a)
; #pragma unroll
;     for (int b = 0; b < 2; ++b)
; #pragma unroll
;       for (int i = 0; i < 16; ++i) acc[a][b][i] = 0.f;
;   const int srow = tid >> 3;
;   const int schunk = (tid & 7) ^ ((srow & 7) ^ ((srow >> 3) & 3));
;     ...
;   const int rowA = wm * (32 * MI) + r, rowB = wn * 64 + r;
;   const int hk = hh ^ ((r & 7) ^ ((r >> 3) & 3));
;     ...
;   G_GLDS(0, 0);
;   asm volatile("s_waitcnt vmcnt(0)" ::: "memory");
;   __syncthreads();
; template <int EPI, int MI>
; DI void gemm_phase(const GemmDesc& g, char* smem, int vb, int nvb) {
;     ...
;   for (int q = start; q < local; q += step) {
;     const int mg = q / per;
;     const int rem = q - mg * per;
;     const int tn = rem / PM;
;     const int tm = mbase + mg * PM + (rem - tn * PM);
;     gemm_tile<EPI, MI>(g, tm, tn, smem);
.LBB0_1491:
	s_abs_i32 s0, s40
	v_readlane_b32 s1, v219, 48
	s_mul_hi_u32 s1, s0, s1
	v_readlane_b32 s17, v219, 47
	s_mul_i32 s4, s1, s17
	s_sub_i32 s0, s0, s4
	s_ashr_i32 s15, s40, 31
	s_add_i32 s4, s1, 1
	s_sub_i32 s5, s0, s17
	s_cmp_ge_u32 s0, s17
	s_cselect_b32 s1, s4, s1
	s_cselect_b32 s0, s5, s0
	s_add_i32 s4, s1, 1
	s_cmp_ge_u32 s0, s17
	s_cselect_b32 s0, s4, s1
	s_xor_b32 s16, s0, s15
	s_sub_i32 s0, s16, s15
	s_mul_i32 s1, s0, s17
	s_sub_i32 s1, s40, s1
	s_abs_i32 s4, s1
	v_readlane_b32 s5, v219, 46
	s_mul_hi_u32 s5, s4, s5
	v_readlane_b32 s41, v218, 32
	s_mul_i32 s18, s5, s41
	s_sub_i32 s4, s4, s18
	s_ashr_i32 s17, s1, 31
	s_add_i32 s18, s5, 1
	s_sub_i32 s19, s4, s41
	s_cmp_ge_u32 s4, s41
	s_cselect_b32 s5, s18, s5
	s_cselect_b32 s4, s19, s4
	s_add_i32 s18, s5, 1
	s_cmp_ge_u32 s4, s41
	s_cselect_b32 s4, s18, s5
	s_xor_b32 s18, s4, s17
	v_mov_b32_e32 v97, v132
	s_sub_i32 s4, s18, s17
	s_mul_i32 s0, s0, s41
	v_ashrrev_i32_e32 v6, 3, v97
	s_mul_i32 s5, s4, s41
	s_waitcnt vmcnt(8)
	v_ashrrev_i32_e32 v109, 7, v97
	v_bfe_u32 v1, v97, 6, 2
	v_xor_b32_e32 v2, v6, v97
	s_add_i32 s0, s0, s54
	s_sub_i32 s1, s1, s5
	v_and_b32_e32 v108, 31, v97
	v_bitop3_b32 v2, v2, v1, 7 bitop3:0x6c
	v_mul_lo_u32 v1, v109, s6
	s_add_i32 s1, s0, s1
	s_lshl_b32 s0, s4, 7
	v_and_b32_e32 v0, 7, v97
	v_or_b32_e32 v7, v1, v108
	v_lshrrev_b32_e32 v1, 3, v97
	v_readlane_b32 s4, v221, 5
	s_mul_i32 s41, s1, 0xc0
	v_bfe_u32 v115, v97, 5, 1
	v_bitop3_b32 v0, v1, v0, 3 bitop3:0x6c
	v_readlane_b32 s5, v221, 6
	v_xor_b32_e32 v8, v0, v115
	v_add_u32_e32 v3, s41, v6
	v_mov_b64_e32 v[0:1], s[4:5]
	s_movk_i32 s19, 0x1600
	v_mad_i64_i32 v[0:1], s[4:5], v3, s19, v[0:1]
	v_readlane_b32 s4, v220, 56
	v_readlane_b32 s5, v220, 57
	v_lshlrev_b32_e32 v98, 4, v2
	v_add_u32_e32 v9, s0, v6
	v_mov_b64_e32 v[2:3], s[4:5]
	v_lshlrev_b32_e32 v120, 4, v97
	v_mad_i64_i32 v[2:3], s[4:5], v9, s19, v[2:3]
	v_add_u32_e32 v121, 0, v120
	v_mov_b32_e32 v99, v96
	v_readfirstlane_b32 s4, v121
	v_add_u32_e32 v122, 0x1000, v121
	v_lshl_add_u64 v[0:1], v[0:1], 0, v[98:99]
	s_mov_b32 m0, s4
	s_mov_b64 s[42:43], 0x2c000
	v_readfirstlane_b32 s4, v122
	v_add_u32_e32 v123, 0x2000, v121
	global_load_lds_dwordx4 v[0:1], off
	v_lshl_add_u64 v[4:5], v[0:1], 0, s[42:43]
	s_mov_b32 m0, s4
	s_mov_b64 s[44:45], 0x58000
	v_readfirstlane_b32 s4, v123
	v_add_u32_e32 v124, 0x3000, v121
	global_load_lds_dwordx4 v[4:5], off
	v_lshl_add_u64 v[4:5], v[0:1], 0, s[44:45]
	s_mov_b32 m0, s4
	s_mov_b64 s[46:47], 0x84000
	v_readfirstlane_b32 s4, v124
	global_load_lds_dwordx4 v[4:5], off
	v_lshl_add_u64 v[4:5], v[0:1], 0, s[46:47]
	s_mov_b32 m0, s4
	s_mov_b64 s[4:5], 0xb0000
	v_add_u32_e32 v125, 0x4000, v121
	global_load_lds_dwordx4 v[4:5], off
	v_lshl_add_u64 v[4:5], v[0:1], 0, s[4:5]
	v_readfirstlane_b32 s4, v125
	s_mov_b32 m0, s4
	s_mov_b64 s[4:5], 0xdc000
	v_add_u32_e32 v126, 0x5000, v121
	v_lshl_add_u64 v[0:1], v[0:1], 0, s[4:5]
	v_readfirstlane_b32 s4, v126
	v_add_u32_e32 v127, 0xc000, v121
	global_load_lds_dwordx4 v[4:5], off
	s_mov_b32 m0, s4
	v_readfirstlane_b32 s4, v127
	v_add_u32_e32 v128, 0xd000, v121
	global_load_lds_dwordx4 v[0:1], off
	v_lshl_add_u64 v[0:1], v[2:3], 0, v[98:99]
	s_mov_b32 m0, s4
	v_readfirstlane_b32 s4, v128
	v_add_u32_e32 v129, 0xe000, v121
	global_load_lds_dwordx4 v[0:1], off
	v_lshl_add_u64 v[2:3], v[0:1], 0, s[42:43]
	s_mov_b32 m0, s4
	v_readfirstlane_b32 s4, v129
	v_add_u32_e32 v130, 0xf000, v121
	global_load_lds_dwordx4 v[2:3], off
	v_lshl_add_u64 v[2:3], v[0:1], 0, s[44:45]
	s_mov_b32 m0, s4
	v_readfirstlane_b32 s4, v130
	global_load_lds_dwordx4 v[2:3], off
	v_lshl_add_u64 v[0:1], v[0:1], 0, s[46:47]
	s_mov_b32 m0, s4
	s_mul_i32 s15, s15, 7
	global_load_lds_dwordx4 v[0:1], off
	s_add_i32 s17, s17, s15
	s_sub_i32 s4, s17, s18
	s_mul_i32 s16, s16, 7
	s_sub_i32 s4, s4, s16
	v_readlane_b32 s5, v218, 33
	v_lshlrev_b32_e32 v0, 7, v97
	s_mul_i32 s4, s5, s4
	v_and_b32_e32 v0, 0x2f80, v0
	s_add_i32 s4, s4, s39
	s_waitcnt vmcnt(0)
	v_add_u32_e32 v153, 0, v0
	v_add_u32_e32 v155, s10, v0
	v_add_u32_e32 v2, s4, v6
	v_mov_b64_e32 v[0:1], s[70:71]
	v_lshlrev_b32_e32 v154, 4, v8
	v_mad_i64_i32 v[100:101], s[4:5], v2, s19, v[0:1]
	v_mad_i64_i32 v[102:103], s[4:5], v9, s19, v[0:1]
	v_mov_b32_e32 v0, 0
	v_lshl_add_u32 v131, v7, 7, 0
	v_xor_b32_e32 v156, 32, v154
	v_xor_b32_e32 v157, 64, v154
	v_xor_b32_e32 v158, 0x60, v154
	s_mov_b32 s15, 0
	v_mov_b32_e32 v1, v0
	v_mov_b32_e32 v2, v0
	v_mov_b32_e32 v3, v0
	v_mov_b32_e32 v4, v0
	v_mov_b32_e32 v5, v0
	v_mov_b32_e32 v6, v0
	v_mov_b32_e32 v7, v0
	v_mov_b32_e32 v8, v0
	v_mov_b32_e32 v9, v0
	v_mov_b32_e32 v10, v0
	v_mov_b32_e32 v11, v0
	v_mov_b32_e32 v12, v0
	v_mov_b32_e32 v13, v0
	v_mov_b32_e32 v14, v0
	v_mov_b32_e32 v15, v0
	v_mov_b32_e32 v16, v0
	v_mov_b32_e32 v17, v0
	v_mov_b32_e32 v18, v0
	v_mov_b32_e32 v19, v0
	v_mov_b32_e32 v20, v0
	v_mov_b32_e32 v21, v0
	v_mov_b32_e32 v22, v0
	v_mov_b32_e32 v23, v0
	v_mov_b32_e32 v24, v0
	v_mov_b32_e32 v25, v0
	v_mov_b32_e32 v26, v0
	v_mov_b32_e32 v27, v0
	v_mov_b32_e32 v28, v0
	v_mov_b32_e32 v29, v0
	v_mov_b32_e32 v30, v0
	v_mov_b32_e32 v31, v0
	v_mov_b32_e32 v32, v0
	v_mov_b32_e32 v33, v0
	v_mov_b32_e32 v34, v0
	v_mov_b32_e32 v35, v0
	v_mov_b32_e32 v36, v0
	v_mov_b32_e32 v37, v0
	v_mov_b32_e32 v38, v0
	v_mov_b32_e32 v39, v0
	v_mov_b32_e32 v40, v0
	v_mov_b32_e32 v41, v0
	v_mov_b32_e32 v42, v0
	v_mov_b32_e32 v43, v0
	v_mov_b32_e32 v44, v0
	v_mov_b32_e32 v45, v0
	v_mov_b32_e32 v46, v0
	v_mov_b32_e32 v47, v0
	v_mov_b32_e32 v48, v0
	s_waitcnt vmcnt(0)
; template <int EPI, int MI>
; DI void gemm_tile(const GemmDesc& g, int tm, int tn, char* smem) {
;     ...
;   f32x16 acc[MI][2];
; #pragma unroll
;   for (int a = 0; a < MI; ++a)
; #pragma unroll
;     for (int b = 0; b < 2; ++b)
; #pragma unroll
;       for (int i = 0; i < 16; ++i) acc[a][b][i] = 0.f;
;   const int srow = tid >> 3;
;   const int schunk = (tid & 7) ^ ((srow & 7) ^ ((srow >> 3) & 3));
;     ...
;   const int rowA = wm * (32 * MI) + r, rowB = wn * 64 + r;
;   const int hk = hh ^ ((r & 7) ^ ((r >> 3) & 3));
;     ...
;   G_GLDS(0, 0);
;   asm volatile("s_waitcnt vmcnt(0)" ::: "memory");
;   __syncthreads();
;   for (int kt = 0; kt < nk; kt += 2) {
;     if (kt + 1 < nk) G_GLDS(kt + 1, 1);
;     G_COMPUTE(0);
;     asm volatile("s_waitcnt vmcnt(0)" ::: "memory");
;     __syncthreads();
;     if (kt + 1 < nk) {
;       if (kt + 2 < nk) G_GLDS(kt + 2, 0);
;       G_COMPUTE(1);
;       asm volatile("s_waitcnt vmcnt(0)" ::: "memory");
;       __syncthreads();
;     }
;   }
	v_mov_b32_e32 v49, v0
	v_mov_b32_e32 v50, v0
	v_mov_b32_e32 v51, v0
	v_mov_b32_e32 v52, v0
	v_mov_b32_e32 v53, v0
	v_mov_b32_e32 v54, v0
	v_mov_b32_e32 v55, v0
	v_mov_b32_e32 v56, v0
	v_mov_b32_e32 v57, v0
	v_mov_b32_e32 v58, v0
	v_mov_b32_e32 v59, v0
	v_mov_b32_e32 v60, v0
	v_mov_b32_e32 v61, v0
	v_mov_b32_e32 v62, v0
	v_mov_b32_e32 v63, v0
	v_mov_b32_e32 v64, v0
	v_mov_b32_e32 v65, v0
	v_mov_b32_e32 v66, v0
	v_mov_b32_e32 v67, v0
	v_mov_b32_e32 v68, v0
	v_mov_b32_e32 v69, v0
	v_mov_b32_e32 v70, v0
	v_mov_b32_e32 v71, v0
	v_mov_b32_e32 v72, v0
	v_mov_b32_e32 v73, v0
	v_mov_b32_e32 v74, v0
	v_mov_b32_e32 v75, v0
	v_mov_b32_e32 v76, v0
	v_mov_b32_e32 v77, v0
	v_mov_b32_e32 v78, v0
	v_mov_b32_e32 v79, v0
	v_mov_b32_e32 v80, v0
	v_mov_b32_e32 v81, v0
	v_mov_b32_e32 v82, v0
	v_mov_b32_e32 v83, v0
	v_mov_b32_e32 v84, v0
	v_mov_b32_e32 v85, v0
	v_mov_b32_e32 v86, v0
	v_mov_b32_e32 v87, v0
	v_mov_b32_e32 v88, v0
	v_mov_b32_e32 v89, v0
	v_mov_b32_e32 v90, v0
	v_mov_b32_e32 v91, v0
	v_mov_b32_e32 v92, v0
	v_mov_b32_e32 v93, v0
	v_mov_b32_e32 v94, v0
	v_mov_b32_e32 v95, v0
	v_add_u32_e32 v162, v131, v154
	v_add_u32_e32 v163, v131, v156
	v_add_u32_e32 v164, v131, v157
	v_add_u32_e32 v165, v131, v158
	v_add_u32_e32 v166, v153, v154
	v_add_u32_e32 v167, v153, v156
	v_add_u32_e32 v168, v153, v157
	v_add_u32_e32 v169, v153, v158
	v_add_u32_e32 v170, v155, v154
	v_add_u32_e32 v171, v155, v156
	v_add_u32_e32 v172, v155, v157
	v_add_u32_e32 v173, v155, v158
	v_lshl_add_u64 v[252:253], v[100:101], 0, v[98:99]
	v_lshl_add_u64 v[254:255], v[102:103], 0, v[98:99]
	v_readfirstlane_b32 s100, v121
	s_mov_b64 s[4:5], 0x80
	s_waitcnt vmcnt(0) lgkmcnt(0)
	s_barrier
	s_mov_b64 s[16:17], 0x5872080
	s_add_u32 m0, s100, 0x6000
	v_lshl_add_u64 v[106:107], v[252:253], 0, s[16:17]
	global_load_lds_dwordx4 v[106:107], off
	s_mov_b64 s[16:17], 0x589e080
	s_add_u32 m0, s100, 0x7000
	v_lshl_add_u64 v[106:107], v[252:253], 0, s[16:17]
	global_load_lds_dwordx4 v[106:107], off
	s_mov_b64 s[16:17], 0x58ca080
	s_add_u32 m0, s100, 0x8000
	v_lshl_add_u64 v[106:107], v[252:253], 0, s[16:17]
	global_load_lds_dwordx4 v[106:107], off
	s_mov_b64 s[16:17], 0x58f6080
	s_add_u32 m0, s100, 0x9000
	v_lshl_add_u64 v[106:107], v[252:253], 0, s[16:17]
	global_load_lds_dwordx4 v[106:107], off
	ds_read_b128 v[236:239], v166 offset:49152
	ds_read_b128 v[240:243], v166 offset:53248
	ds_read_b128 v[224:227], v162
	ds_read_b128 v[228:231], v162 offset:4096
	s_mov_b32 s15, 0
.Lge_loop:
	ds_read_b128 v[232:235], v162 offset:8192
	s_waitcnt lgkmcnt(2)
	v_mfma_f32_32x32x16_bf16 v[80:95], v[224:227], v[236:239], v[80:95]
	v_mfma_f32_32x32x16_bf16 v[64:79], v[224:227], v[240:243], v[64:79]
	s_mov_b64 s[16:17], 0x5922080
	s_add_u32 m0, s100, 0xa000
	v_lshl_add_u64 v[106:107], v[252:253], 0, s[16:17]
	global_load_lds_dwordx4 v[106:107], off
	s_mov_b64 s[16:17], 0x594e080
	s_add_u32 m0, s100, 0xb000
	v_lshl_add_u64 v[106:107], v[252:253], 0, s[16:17]
	global_load_lds_dwordx4 v[106:107], off
	v_lshl_add_u64 v[252:253], v[252:253], 0, s[4:5]
	ds_read_b128 v[244:247], v167 offset:49152
	ds_read_b128 v[248:251], v167 offset:53248
	ds_read_b128 v[224:227], v163
	s_waitcnt lgkmcnt(4)
	v_mfma_f32_32x32x16_bf16 v[48:63], v[228:231], v[236:239], v[48:63]
	v_mfma_f32_32x32x16_bf16 v[32:47], v[228:231], v[240:243], v[32:47]
	s_mov_b64 s[16:17], 0x1b80080
	s_add_u32 m0, s100, 0x10000
	v_lshl_add_u64 v[106:107], v[254:255], 0, s[16:17]
	global_load_lds_dwordx4 v[106:107], off
	s_mov_b64 s[16:17], 0x1bac080
	s_add_u32 m0, s100, 0x11000
	v_lshl_add_u64 v[106:107], v[254:255], 0, s[16:17]
	global_load_lds_dwordx4 v[106:107], off
	ds_read_b128 v[228:231], v163 offset:4096
	s_waitcnt lgkmcnt(4)
	v_mfma_f32_32x32x16_bf16 v[16:31], v[232:235], v[236:239], v[16:31]
	v_mfma_f32_32x32x16_bf16 v[0:15], v[232:235], v[240:243], v[0:15]
	s_mov_b64 s[16:17], 0x1bd8080
	s_add_u32 m0, s100, 0x12000
	v_lshl_add_u64 v[106:107], v[254:255], 0, s[16:17]
	global_load_lds_dwordx4 v[106:107], off
	s_mov_b64 s[16:17], 0x1c04080
	s_add_u32 m0, s100, 0x13000
	v_lshl_add_u64 v[106:107], v[254:255], 0, s[16:17]
	global_load_lds_dwordx4 v[106:107], off
	v_lshl_add_u64 v[254:255], v[254:255], 0, s[4:5]
	ds_read_b128 v[232:235], v163 offset:8192
	s_waitcnt lgkmcnt(2)
	v_mfma_f32_32x32x16_bf16 v[80:95], v[224:227], v[244:247], v[80:95]
	v_mfma_f32_32x32x16_bf16 v[64:79], v[224:227], v[248:251], v[64:79]
	ds_read_b128 v[236:239], v168 offset:49152
	ds_read_b128 v[240:243], v168 offset:53248
	ds_read_b128 v[224:227], v164
	s_waitcnt lgkmcnt(4)
	v_mfma_f32_32x32x16_bf16 v[48:63], v[228:231], v[244:247], v[48:63]
	v_mfma_f32_32x32x16_bf16 v[32:47], v[228:231], v[248:251], v[32:47]
	ds_read_b128 v[228:231], v164 offset:4096
	s_waitcnt lgkmcnt(4)
	v_mfma_f32_32x32x16_bf16 v[16:31], v[232:235], v[244:247], v[16:31]
	v_mfma_f32_32x32x16_bf16 v[0:15], v[232:235], v[248:251], v[0:15]
	ds_read_b128 v[232:235], v164 offset:8192
	s_waitcnt lgkmcnt(2)
	v_mfma_f32_32x32x16_bf16 v[80:95], v[224:227], v[236:239], v[80:95]
	v_mfma_f32_32x32x16_bf16 v[64:79], v[224:227], v[240:243], v[64:79]
	ds_read_b128 v[244:247], v169 offset:49152
	ds_read_b128 v[248:251], v169 offset:53248
	ds_read_b128 v[224:227], v165
	s_waitcnt lgkmcnt(4)
	v_mfma_f32_32x32x16_bf16 v[48:63], v[228:231], v[236:239], v[48:63]
	v_mfma_f32_32x32x16_bf16 v[32:47], v[228:231], v[240:243], v[32:47]
	ds_read_b128 v[228:231], v165 offset:4096
	s_waitcnt lgkmcnt(4)
	v_mfma_f32_32x32x16_bf16 v[16:31], v[232:235], v[236:239], v[16:31]
	v_mfma_f32_32x32x16_bf16 v[0:15], v[232:235], v[240:243], v[0:15]
	ds_read_b128 v[232:235], v165 offset:8192
	s_waitcnt lgkmcnt(2)
	v_mfma_f32_32x32x16_bf16 v[80:95], v[224:227], v[244:247], v[80:95]
	v_mfma_f32_32x32x16_bf16 v[64:79], v[224:227], v[248:251], v[64:79]
	s_waitcnt lgkmcnt(0)
	s_waitcnt vmcnt(0)
	s_barrier
	s_cmp_eq_u32 s15, 42
	s_cbranch_scc1 .Lge_noearly
	s_mov_b64 s[16:17], 0x5872080
	s_mov_b32 m0, s100
	v_lshl_add_u64 v[106:107], v[252:253], 0, s[16:17]
	global_load_lds_dwordx4 v[106:107], off
	s_mov_b64 s[16:17], 0x589e080
	s_add_u32 m0, s100, 0x1000
	v_lshl_add_u64 v[106:107], v[252:253], 0, s[16:17]
	global_load_lds_dwordx4 v[106:107], off
	s_mov_b64 s[16:17], 0x58ca080
	s_add_u32 m0, s100, 0x2000
	v_lshl_add_u64 v[106:107], v[252:253], 0, s[16:17]
	global_load_lds_dwordx4 v[106:107], off
	s_mov_b64 s[16:17], 0x58f6080
	s_add_u32 m0, s100, 0x3000
	v_lshl_add_u64 v[106:107], v[252:253], 0, s[16:17]
	global_load_lds_dwordx4 v[106:107], off
; template <int EPI, int MI>
; DI void gemm_tile(const GemmDesc& g, int tm, int tn, char* smem) {
;     ...
;   const int rowA = wm * (32 * MI) + r, rowB = wn * 64 + r;
;   const int hk = hh ^ ((r & 7) ^ ((r >> 3) & 3));
;     ...
;   G_GLDS(0, 0);
;   asm volatile("s_waitcnt vmcnt(0)" ::: "memory");
;   __syncthreads();
;   for (int kt = 0; kt < nk; kt += 2) {
;     if (kt + 1 < nk) G_GLDS(kt + 1, 1);
;     G_COMPUTE(0);
;     asm volatile("s_waitcnt vmcnt(0)" ::: "memory");
;     __syncthreads();
;     if (kt + 1 < nk) {
;       if (kt + 2 < nk) G_GLDS(kt + 2, 0);
;       G_COMPUTE(1);
;       asm volatile("s_waitcnt vmcnt(0)" ::: "memory");
;       __syncthreads();
;     }
;   }
.Lge_noearly:
	ds_read_b128 v[236:239], v170
	ds_read_b128 v[240:243], v170 offset:4096
	ds_read_b128 v[224:227], v162 offset:24576
	v_mfma_f32_32x32x16_bf16 v[48:63], v[228:231], v[244:247], v[48:63]
	v_mfma_f32_32x32x16_bf16 v[32:47], v[228:231], v[248:251], v[32:47]
	ds_read_b128 v[228:231], v162 offset:28672
	v_mfma_f32_32x32x16_bf16 v[16:31], v[232:235], v[244:247], v[16:31]
	v_mfma_f32_32x32x16_bf16 v[0:15], v[232:235], v[248:251], v[0:15]
	s_cmp_eq_u32 s15, 42
	s_cbranch_scc1 .Lge_last
	ds_read_b128 v[232:235], v162 offset:32768
	s_waitcnt lgkmcnt(2)
	v_mfma_f32_32x32x16_bf16 v[80:95], v[224:227], v[236:239], v[80:95]
	v_mfma_f32_32x32x16_bf16 v[64:79], v[224:227], v[240:243], v[64:79]
	s_mov_b64 s[16:17], 0x5922080
	s_add_u32 m0, s100, 0x4000
	v_lshl_add_u64 v[106:107], v[252:253], 0, s[16:17]
	global_load_lds_dwordx4 v[106:107], off
	s_mov_b64 s[16:17], 0x594e080
	s_add_u32 m0, s100, 0x5000
	v_lshl_add_u64 v[106:107], v[252:253], 0, s[16:17]
	global_load_lds_dwordx4 v[106:107], off
	v_lshl_add_u64 v[252:253], v[252:253], 0, s[4:5]
	ds_read_b128 v[244:247], v171
	ds_read_b128 v[248:251], v171 offset:4096
	ds_read_b128 v[224:227], v163 offset:24576
	s_waitcnt lgkmcnt(4)
	v_mfma_f32_32x32x16_bf16 v[48:63], v[228:231], v[236:239], v[48:63]
	v_mfma_f32_32x32x16_bf16 v[32:47], v[228:231], v[240:243], v[32:47]
	s_mov_b64 s[16:17], 0x1b80080
	s_add_u32 m0, s100, 0xc000
	v_lshl_add_u64 v[106:107], v[254:255], 0, s[16:17]
	global_load_lds_dwordx4 v[106:107], off
	s_mov_b64 s[16:17], 0x1bac080
	s_add_u32 m0, s100, 0xd000
	v_lshl_add_u64 v[106:107], v[254:255], 0, s[16:17]
	global_load_lds_dwordx4 v[106:107], off
	ds_read_b128 v[228:231], v163 offset:28672
	s_waitcnt lgkmcnt(4)
	v_mfma_f32_32x32x16_bf16 v[16:31], v[232:235], v[236:239], v[16:31]
	v_mfma_f32_32x32x16_bf16 v[0:15], v[232:235], v[240:243], v[0:15]
	s_mov_b64 s[16:17], 0x1bd8080
	s_add_u32 m0, s100, 0xe000
	v_lshl_add_u64 v[106:107], v[254:255], 0, s[16:17]
	global_load_lds_dwordx4 v[106:107], off
	s_mov_b64 s[16:17], 0x1c04080
	s_add_u32 m0, s100, 0xf000
	v_lshl_add_u64 v[106:107], v[254:255], 0, s[16:17]
	global_load_lds_dwordx4 v[106:107], off
	v_lshl_add_u64 v[254:255], v[254:255], 0, s[4:5]
	ds_read_b128 v[232:235], v163 offset:32768
	s_waitcnt lgkmcnt(2)
	v_mfma_f32_32x32x16_bf16 v[80:95], v[224:227], v[244:247], v[80:95]
	v_mfma_f32_32x32x16_bf16 v[64:79], v[224:227], v[248:251], v[64:79]
	ds_read_b128 v[236:239], v172
	ds_read_b128 v[240:243], v172 offset:4096
	ds_read_b128 v[224:227], v164 offset:24576
	s_waitcnt lgkmcnt(4)
	v_mfma_f32_32x32x16_bf16 v[48:63], v[228:231], v[244:247], v[48:63]
	v_mfma_f32_32x32x16_bf16 v[32:47], v[228:231], v[248:251], v[32:47]
	ds_read_b128 v[228:231], v164 offset:28672
	s_waitcnt lgkmcnt(4)
	v_mfma_f32_32x32x16_bf16 v[16:31], v[232:235], v[244:247], v[16:31]
	v_mfma_f32_32x32x16_bf16 v[0:15], v[232:235], v[248:251], v[0:15]
	ds_read_b128 v[232:235], v164 offset:32768
	s_waitcnt lgkmcnt(2)
	v_mfma_f32_32x32x16_bf16 v[80:95], v[224:227], v[236:239], v[80:95]
	v_mfma_f32_32x32x16_bf16 v[64:79], v[224:227], v[240:243], v[64:79]
	ds_read_b128 v[244:247], v173
	ds_read_b128 v[248:251], v173 offset:4096
	ds_read_b128 v[224:227], v165 offset:24576
	s_waitcnt lgkmcnt(4)
	v_mfma_f32_32x32x16_bf16 v[48:63], v[228:231], v[236:239], v[48:63]
	v_mfma_f32_32x32x16_bf16 v[32:47], v[228:231], v[240:243], v[32:47]
	ds_read_b128 v[228:231], v165 offset:28672
	s_waitcnt lgkmcnt(4)
	v_mfma_f32_32x32x16_bf16 v[16:31], v[232:235], v[236:239], v[16:31]
	v_mfma_f32_32x32x16_bf16 v[0:15], v[232:235], v[240:243], v[0:15]
	ds_read_b128 v[232:235], v165 offset:32768
	s_waitcnt lgkmcnt(2)
	v_mfma_f32_32x32x16_bf16 v[80:95], v[224:227], v[244:247], v[80:95]
	v_mfma_f32_32x32x16_bf16 v[64:79], v[224:227], v[248:251], v[64:79]
	s_waitcnt lgkmcnt(0)
	s_waitcnt vmcnt(0)
	s_barrier
	s_mov_b64 s[16:17], 0x5872080
	s_add_u32 m0, s100, 0x6000
	v_lshl_add_u64 v[106:107], v[252:253], 0, s[16:17]
	global_load_lds_dwordx4 v[106:107], off
	s_mov_b64 s[16:17], 0x589e080
	s_add_u32 m0, s100, 0x7000
	v_lshl_add_u64 v[106:107], v[252:253], 0, s[16:17]
	global_load_lds_dwordx4 v[106:107], off
	s_mov_b64 s[16:17], 0x58ca080
	s_add_u32 m0, s100, 0x8000
	v_lshl_add_u64 v[106:107], v[252:253], 0, s[16:17]
	global_load_lds_dwordx4 v[106:107], off
	s_mov_b64 s[16:17], 0x58f6080
	s_add_u32 m0, s100, 0x9000
	v_lshl_add_u64 v[106:107], v[252:253], 0, s[16:17]
	global_load_lds_dwordx4 v[106:107], off
	ds_read_b128 v[236:239], v166 offset:49152
	ds_read_b128 v[240:243], v166 offset:53248
	ds_read_b128 v[224:227], v162
	v_mfma_f32_32x32x16_bf16 v[48:63], v[228:231], v[244:247], v[48:63]
	v_mfma_f32_32x32x16_bf16 v[32:47], v[228:231], v[248:251], v[32:47]
	ds_read_b128 v[228:231], v162 offset:4096
	v_mfma_f32_32x32x16_bf16 v[16:31], v[232:235], v[244:247], v[16:31]
	v_mfma_f32_32x32x16_bf16 v[0:15], v[232:235], v[248:251], v[0:15]
	s_add_u32 s15, s15, 2
	s_branch .Lge_loop
